# peephole: v_mul+v_mov pairs left by the rcp-division rewrite fused (397 sites in GLU/SGU/attention epilogues)
# speedup vs baseline: 1.0224x; 1.0021x over previous
.Lsgu_join:
	global_load_dwordx4 v[18:21], v35, s[40:41] offset:16
	global_load_dwordx4 v[22:25], v35, s[40:41]
	global_load_dwordx4 v[26:29], v35, s[46:47] offset:16
	global_load_dwordx4 v[30:33], v35, s[46:47]
	v_mul_f32_e32 v36, v36, v16
	v_mul_f32_e32 v12, v12, v16
	v_fmac_f32_e32 v15, 0xbb000000, v17
	v_or_b32_e32 v131, s36, v132
	v_or_b32_e32 v142, 16, v131
	v_or_b32_e32 v141, 32, v131
	v_or_b32_e32 v140, 48, v131
	v_or_b32_e32 v139, 64, v131
	v_or_b32_e32 v138, 0x50, v131
	v_or_b32_e32 v137, 0x60, v131
	v_or_b32_e32 v133, 0x70, v131
	s_waitcnt vmcnt(0)
	v_fma_f32 v22, v22, v36, v30
	v_mul_u32_u24_e32 v30, 0x110, v45
	v_fma_f32 v12, v23, v12, v31
	v_add3_u32 v30, 0, v34, v30
	v_cvt_pk_bf16_f32 v12, v12, s0
	ds_write_b16 v30, v12 offset:272
	v_mul_f32_e32 v12, v37, v16
	v_fma_f32 v12, v24, v12, v32
	v_cvt_pk_bf16_f32 v12, v12, s0
	ds_write_b16 v30, v12 offset:544
	v_mul_f32_e32 v12, v13, v16
	v_fmac_f32_e32 v33, v25, v12
	v_cvt_pk_bf16_f32 v12, v33, s0
	ds_write_b16 v30, v12 offset:816
	v_mul_f32_e32 v12, v38, v16
	v_fma_f32 v12, v18, v12, v26
	v_cvt_pk_bf16_f32 v12, v12, s0
	ds_write_b16 v30, v12 offset:1088
	v_mul_f32_e32 v12, v14, v16
	v_fma_f32 v12, v19, v12, v27
	v_cvt_pk_bf16_f32 v12, v12, s0
	ds_write_b16 v30, v12 offset:1360
	v_mul_f32_e32 v12, v39, v16
	v_fma_f32 v12, v20, v12, v28
	v_cvt_pk_bf16_f32 v12, v12, s0
	ds_write_b16 v30, v12 offset:1632
	v_mul_f32_e32 v12, v15, v16
	v_fmac_f32_e32 v29, v21, v12
	v_cvt_pk_bf16_f32 v22, v22, s0
	v_cvt_pk_bf16_f32 v12, v29, s0
	ds_write_b16 v30, v22
	ds_write_b16 v30, v12 offset:1904
	global_load_dwordx4 v[12:15], v35, s[40:41] offset:144
	global_load_dwordx4 v[18:21], v35, s[40:41] offset:128
	global_load_dwordx4 v[22:25], v35, s[46:47] offset:144
	global_load_dwordx4 v[26:29], v35, s[46:47] offset:128
	v_lshlrev_b32_e32 v31, 16, v8
	v_and_b32_e32 v8, 0xffff0000, v8
	v_fmac_f32_e32 v8, 0xbb000000, v17
	v_mul_f32_e32 v8, v8, v16
	v_lshlrev_b32_e32 v32, 16, v9
	v_fmac_f32_e32 v32, 0xbb000000, v17
	v_and_b32_e32 v9, 0xffff0000, v9
	v_fmac_f32_e32 v9, 0xbb000000, v17
	v_lshlrev_b32_e32 v33, 16, v10
	v_fmac_f32_e32 v33, 0xbb000000, v17
	v_and_b32_e32 v10, 0xffff0000, v10
	v_fmac_f32_e32 v10, 0xbb000000, v17
	v_lshlrev_b32_e32 v34, 16, v11
	v_fmac_f32_e32 v34, 0xbb000000, v17
	v_and_b32_e32 v11, 0xffff0000, v11
	v_fmac_f32_e32 v31, 0xbb000000, v17
	v_fmac_f32_e32 v11, 0xbb000000, v17
	v_mul_f32_e32 v31, v31, v16
	s_waitcnt vmcnt(0)
	v_fma_f32 v8, v19, v8, v27
	v_cvt_pk_bf16_f32 v8, v8, s0
	ds_write_b16 v30, v8 offset:8976
	v_mul_f32_e32 v8, v32, v16
	v_fma_f32 v8, v20, v8, v28
	v_cvt_pk_bf16_f32 v8, v8, s0
	ds_write_b16 v30, v8 offset:9248
	v_mul_f32_e32 v8, v9, v16
	v_fmac_f32_e32 v29, v21, v8
	v_cvt_pk_bf16_f32 v8, v29, s0
	ds_write_b16 v30, v8 offset:9520
	v_mul_f32_e32 v8, v33, v16
	v_fma_f32 v8, v12, v8, v22
	v_cvt_pk_bf16_f32 v8, v8, s0
	ds_write_b16 v30, v8 offset:9792
	v_mul_f32_e32 v8, v10, v16
	v_fma_f32 v8, v13, v8, v23
	v_cvt_pk_bf16_f32 v8, v8, s0
	ds_write_b16 v30, v8 offset:10064
	v_mul_f32_e32 v8, v34, v16
	v_fma_f32 v8, v14, v8, v24
	v_cvt_pk_bf16_f32 v8, v8, s0
	ds_write_b16 v30, v8 offset:10336
	v_mul_f32_e32 v8, v11, v16
	v_fma_f32 v18, v18, v31, v26
	v_fmac_f32_e32 v25, v15, v8
	v_cvt_pk_bf16_f32 v18, v18, s0
	v_cvt_pk_bf16_f32 v8, v25, s0
	ds_write_b16 v30, v18 offset:8704
	ds_write_b16 v30, v8 offset:10608
	global_load_dwordx4 v[8:11], v35, s[40:41] offset:272
	global_load_dwordx4 v[12:15], v35, s[40:41] offset:256
	global_load_dwordx4 v[18:21], v35, s[46:47] offset:272
	global_load_dwordx4 v[22:25], v35, s[46:47] offset:256
	v_lshlrev_b32_e32 v26, 16, v4
	v_and_b32_e32 v4, 0xffff0000, v4
	v_fmac_f32_e32 v4, 0xbb000000, v17
	v_mul_f32_e32 v4, v4, v16
	v_lshlrev_b32_e32 v27, 16, v5
	v_fmac_f32_e32 v27, 0xbb000000, v17
	v_and_b32_e32 v5, 0xffff0000, v5
	v_fmac_f32_e32 v5, 0xbb000000, v17
	v_lshlrev_b32_e32 v28, 16, v6
	v_fmac_f32_e32 v28, 0xbb000000, v17
	v_and_b32_e32 v6, 0xffff0000, v6
	v_fmac_f32_e32 v6, 0xbb000000, v17
	v_lshlrev_b32_e32 v29, 16, v7
	v_fmac_f32_e32 v29, 0xbb000000, v17
	v_and_b32_e32 v7, 0xffff0000, v7
	v_fmac_f32_e32 v26, 0xbb000000, v17
	v_fmac_f32_e32 v7, 0xbb000000, v17
	v_mul_f32_e32 v26, v26, v16
	s_waitcnt vmcnt(0)
	v_fma_f32 v4, v13, v4, v23
	v_cvt_pk_bf16_f32 v4, v4, s0
	ds_write_b16 v30, v4 offset:17680
	v_mul_f32_e32 v4, v27, v16
	v_fma_f32 v4, v14, v4, v24
	v_cvt_pk_bf16_f32 v4, v4, s0
	ds_write_b16 v30, v4 offset:17952
	v_mul_f32_e32 v4, v5, v16
	v_fmac_f32_e32 v25, v15, v4
	v_cvt_pk_bf16_f32 v4, v25, s0
	ds_write_b16 v30, v4 offset:18224
	v_mul_f32_e32 v4, v28, v16
	v_fma_f32 v4, v8, v4, v18
	v_cvt_pk_bf16_f32 v4, v4, s0
	ds_write_b16 v30, v4 offset:18496
	v_mul_f32_e32 v4, v6, v16
	v_fma_f32 v4, v9, v4, v19
	v_cvt_pk_bf16_f32 v4, v4, s0
	ds_write_b16 v30, v4 offset:18768
	v_mul_f32_e32 v4, v29, v16
	v_fma_f32 v4, v10, v4, v20
	v_cvt_pk_bf16_f32 v4, v4, s0
	ds_write_b16 v30, v4 offset:19040
	v_mul_f32_e32 v4, v7, v16
	v_fma_f32 v12, v12, v26, v22
	v_fmac_f32_e32 v21, v11, v4
	v_cvt_pk_bf16_f32 v12, v12, s0
	v_cvt_pk_bf16_f32 v4, v21, s0
	ds_write_b16 v30, v12 offset:17408
	ds_write_b16 v30, v4 offset:19312
	global_load_dwordx4 v[4:7], v35, s[40:41] offset:400
	global_load_dwordx4 v[8:11], v35, s[40:41] offset:384
	global_load_dwordx4 v[12:15], v35, s[46:47] offset:400
	global_load_dwordx4 v[18:21], v35, s[46:47] offset:384
	v_lshlrev_b32_e32 v22, 16, v0
	v_and_b32_e32 v0, 0xffff0000, v0
	v_fmac_f32_e32 v0, 0xbb000000, v17
	v_mul_f32_e32 v0, v0, v16
	v_lshlrev_b32_e32 v23, 16, v1
	v_fmac_f32_e32 v23, 0xbb000000, v17
	v_and_b32_e32 v1, 0xffff0000, v1
	v_fmac_f32_e32 v1, 0xbb000000, v17
	v_lshlrev_b32_e32 v24, 16, v2
	v_fmac_f32_e32 v24, 0xbb000000, v17
	v_and_b32_e32 v2, 0xffff0000, v2
	v_fmac_f32_e32 v2, 0xbb000000, v17
	v_lshlrev_b32_e32 v25, 16, v3
	v_fmac_f32_e32 v25, 0xbb000000, v17
	v_and_b32_e32 v3, 0xffff0000, v3
	v_fmac_f32_e32 v3, 0xbb000000, v17
	v_fmac_f32_e32 v22, 0xbb000000, v17
	v_mul_f32_e32 v22, v22, v16
	v_and_b32_e32 v17, -16, v130
	s_waitcnt vmcnt(0)
	v_fma_f32 v0, v9, v0, v19
	v_cvt_pk_bf16_f32 v0, v0, s0
	ds_write_b16 v30, v0 offset:26384
	v_mul_f32_e32 v0, v23, v16
	v_fma_f32 v0, v10, v0, v20
	v_cvt_pk_bf16_f32 v0, v0, s0
	ds_write_b16 v30, v0 offset:26656
	v_mul_f32_e32 v0, v1, v16
	v_fmac_f32_e32 v21, v11, v0
	v_cvt_pk_bf16_f32 v0, v21, s0
	ds_write_b16 v30, v0 offset:26928
	v_mul_f32_e32 v0, v24, v16
	v_fma_f32 v0, v4, v0, v12
	v_cvt_pk_bf16_f32 v0, v0, s0
	ds_write_b16 v30, v0 offset:27200
	v_mul_f32_e32 v0, v2, v16
	v_fma_f32 v0, v5, v0, v13
	v_cvt_pk_bf16_f32 v0, v0, s0
	ds_write_b16 v30, v0 offset:27472
	v_mul_f32_e32 v0, v25, v16
	v_fma_f32 v0, v6, v0, v14
	v_cvt_pk_bf16_f32 v0, v0, s0
	ds_write_b16 v30, v0 offset:27744
	v_mul_f32_e32 v0, v3, v16
	v_ashrrev_i32_e32 v4, 4, v130
	v_fmac_f32_e32 v15, v7, v0
	v_lshlrev_b32_e32 v92, 2, v4
	v_cvt_pk_bf16_f32 v0, v15, s0
	v_ashrrev_i32_e32 v93, 31, v92
	ds_write_b16 v30, v0 offset:28016
	v_lshl_add_u64 v[0:1], v[92:93], 1, s[8:9]
	v_mad_u64_u32 v[2:3], s[8:9], v131, s14, v[0:1]
	v_mad_i32_i24 v3, s37, v225, v3
	global_load_dwordx2 v[126:127], v[2:3], off offset:1024
	v_add_co_u32_e32 v2, vcc, s15, v2
	v_fma_f32 v8, v8, v22, v18
	s_nop 0
	v_addc_co_u32_e32 v3, vcc, 0, v3, vcc
	global_load_dwordx2 v[128:129], v[2:3], off offset:2048
	v_mad_u64_u32 v[2:3], s[8:9], v142, s14, v[0:1]
	v_mad_i32_i24 v3, s37, v225, v3
	global_load_dwordx2 v[122:123], v[2:3], off offset:1024
	v_add_co_u32_e32 v2, vcc, s15, v2
	v_cvt_pk_bf16_f32 v8, v8, s0
	s_nop 0
	v_addc_co_u32_e32 v3, vcc, 0, v3, vcc
	global_load_dwordx2 v[124:125], v[2:3], off offset:2048
	v_mad_u64_u32 v[2:3], s[8:9], v141, s14, v[0:1]
	v_mad_i32_i24 v3, s37, v225, v3
	global_load_dwordx2 v[118:119], v[2:3], off offset:1024
	v_add_co_u32_e32 v2, vcc, s15, v2
	ds_write_b16 v30, v8 offset:26112
	s_nop 0
	v_addc_co_u32_e32 v3, vcc, 0, v3, vcc
	global_load_dwordx2 v[120:121], v[2:3], off offset:2048
	v_mad_u64_u32 v[2:3], s[8:9], v140, s14, v[0:1]
	v_mad_i32_i24 v3, s37, v225, v3
	global_load_dwordx2 v[114:115], v[2:3], off offset:1024
	v_add_co_u32_e32 v2, vcc, s15, v2
	v_or_b32_e32 v16, s10, v132
	s_nop 0
	v_addc_co_u32_e32 v3, vcc, 0, v3, vcc
	global_load_dwordx2 v[116:117], v[2:3], off offset:2048
	v_mad_u64_u32 v[2:3], s[8:9], v139, s14, v[0:1]
	v_mad_i32_i24 v3, s37, v225, v3
	global_load_dwordx2 v[110:111], v[2:3], off offset:1024
	v_add_co_u32_e32 v2, vcc, s15, v2
	v_or_b32_e32 v132, s60, v132
	s_nop 0
	v_addc_co_u32_e32 v3, vcc, 0, v3, vcc
	global_load_dwordx2 v[112:113], v[2:3], off offset:2048
	v_mad_u64_u32 v[2:3], s[8:9], v138, s14, v[0:1]
	v_mad_i32_i24 v3, s37, v225, v3
	global_load_dwordx2 v[106:107], v[2:3], off offset:1024
	v_add_co_u32_e32 v2, vcc, s15, v2
	v_lshlrev_b32_e32 v136, 2, v132
	s_nop 0
	v_addc_co_u32_e32 v3, vcc, 0, v3, vcc
	global_load_dwordx2 v[108:109], v[2:3], off offset:2048
	v_mad_u64_u32 v[2:3], s[8:9], v137, s14, v[0:1]
	v_mad_u64_u32 v[0:1], s[8:9], v133, s14, v[0:1]
	v_mad_i32_i24 v3, s37, v225, v3
	v_mad_i32_i24 v1, s37, v225, v1
	global_load_dwordx2 v[100:101], v[2:3], off offset:1024
	global_load_dwordx2 v[96:97], v[0:1], off offset:1024
	v_add_co_u32_e32 v2, vcc, s15, v2
	s_add_u32 s8, s3, s7
	s_nop 0
	v_addc_co_u32_e32 v3, vcc, 0, v3, vcc
	v_add_co_u32_e32 v0, vcc, s15, v0
	s_addc_u32 s9, s11, 0
	s_nop 0
	v_addc_co_u32_e32 v1, vcc, 0, v1, vcc
	global_load_dwordx2 v[98:99], v[0:1], off offset:2048
	v_lshlrev_b32_e32 v0, 3, v4
	v_ashrrev_i32_e32 v1, 31, v0
	v_lshl_add_u64 v[0:1], v[0:1], 1, s[8:9]
	v_lshl_add_u64 v[0:1], v[0:1], 0, v[194:195]
	global_load_dwordx2 v[104:105], v[2:3], off offset:2048
	global_load_dwordx4 v[144:147], v[0:1], off
	v_add_co_u32_e32 v2, vcc, s4, v0
	s_movk_i32 s7, 0x4000
	s_nop 0
	v_addc_co_u32_e32 v3, vcc, 0, v1, vcc
	global_load_dwordx4 v[88:91], v[2:3], off offset:-4096
	global_load_dwordx4 v[80:83], v[2:3], off
	global_load_dwordx4 v[84:87], v[2:3], off offset:64
	v_add_co_u32_e32 v2, vcc, s35, v0
	s_waitcnt vmcnt(18)
	v_lshlrev_b32_e32 v143, 16, v128
	v_addc_co_u32_e32 v3, vcc, 0, v1, vcc
	v_add_co_u32_e32 v4, vcc, s7, v0
	s_movk_i32 s7, 0x5000
	s_nop 0
	v_addc_co_u32_e32 v5, vcc, 0, v1, vcc
	global_load_dwordx4 v[72:75], v[4:5], off offset:-4096
	global_load_dwordx4 v[76:79], v[2:3], off offset:64
	global_load_dwordx4 v[60:63], v[4:5], off
	global_load_dwordx4 v[64:67], v[4:5], off offset:64
	global_load_dwordx4 v[68:71], v[4:5], off offset:128
	v_add_co_u32_e32 v2, vcc, s7, v0
	s_movk_i32 s7, 0x7000
	s_nop 0
	v_addc_co_u32_e32 v3, vcc, 0, v1, vcc
	v_add_co_u32_e32 v4, vcc, s95, v0
	v_and_b32_e32 v128, 0xffff0000, v128
	s_nop 0
	v_addc_co_u32_e32 v5, vcc, 0, v1, vcc
	v_add_co_u32_e32 v12, vcc, s7, v0
	s_movk_i32 s7, 0x110
	v_mul_lo_u32 v16, v16, s7
	v_addc_co_u32_e32 v13, vcc, 0, v1, vcc
	v_add3_u32 v28, 0, v16, v17
	global_load_dwordx4 v[48:51], v[4:5], off offset:-4096
	global_load_dwordx4 v[52:55], v[2:3], off offset:64
	global_load_dwordx4 v[56:59], v[2:3], off offset:128
	global_load_dwordx4 v[32:35], v[4:5], off
	global_load_dwordx4 v[36:39], v[4:5], off offset:64
	global_load_dwordx4 v[40:43], v[4:5], off offset:128
	global_load_dwordx4 v[44:47], v[4:5], off offset:192
	s_nop 0
	global_load_dwordx4 v[0:3], v[12:13], off
	global_load_dwordx4 v[4:7], v[12:13], off offset:64
	global_load_dwordx4 v[8:11], v[12:13], off offset:128
	s_nop 0
	global_load_dwordx4 v[12:15], v[12:13], off offset:192
	s_waitcnt lgkmcnt(0)
	s_barrier
	ds_read_b128 v[16:19], v28
	ds_read_b128 v[20:23], v28 offset:64
	ds_read_b128 v[24:27], v28 offset:128
	ds_read_b128 v[28:31], v28 offset:192
	global_load_dword v132, v136, s[0:1]
	global_load_dword v160, v136, s[0:1] offset:64
	global_load_dword v162, v136, s[0:1] offset:128
	global_load_dword v164, v136, s[0:1] offset:192
	global_load_dword v166, v136, s[0:1] offset:256
	global_load_dword v168, v136, s[0:1] offset:320
	global_load_dword v170, v136, s[0:1] offset:384
	global_load_dword v172, v136, s[0:1] offset:448
	s_add_i32 s7, s60, s10
	v_add_u32_e32 v92, s7, v92
	v_ashrrev_i32_e32 v93, 31, v92
	v_lshl_add_u64 v[102:103], v[92:93], 1, s[82:83]
	s_waitcnt vmcnt(27) lgkmcnt(3)
	v_mfma_f32_16x16x32_bf16 v[92:95], v[16:19], v[144:147], 0
	v_mul_f32_e32 v134, 0xbfb8aa3b, v143
	v_lshlrev_b32_e32 v144, 16, v126
	v_and_b32_e32 v145, 0xffff0000, v126
	v_mul_f32_e32 v126, 0xbfb8aa3b, v128
	v_exp_f32_e32 v134, v134
	v_exp_f32_e32 v135, v126
	v_mad_u64_u32 v[130:131], s[8:9], v131, s14, v[102:103]
	v_mad_i32_i24 v131, s37, v225, v131
	v_pk_add_f32 v[134:135], v[134:135], 1.0 op_sel_hi:[1,0]
	s_waitcnt vmcnt(26)
	v_mfma_f32_16x16x32_bf16 v[88:91], v[16:19], v[88:91], 0
	s_add_i32 s65, s65, s98
	s_waitcnt vmcnt(25)
	v_mfma_f32_16x16x32_bf16 v[80:83], v[16:19], v[80:83], 0
	s_add_i32 s64, s64, s99
	s_cmp_gt_i32 s65, s88
	s_waitcnt vmcnt(0)
	v_pk_add_f32 v[92:93], v[92:93], v[132:133] op_sel_hi:[1,0]
	s_nop 0
	v_pk_mul_f32 v[92:93], v[92:93], v[144:145]
	v_rcp_f32_e32 v144, v135
	v_pk_add_f32 v[94:95], v[94:95], v[132:133] op_sel_hi:[1,0]
	s_waitcnt lgkmcnt(2)
	v_mfma_f32_16x16x32_bf16 v[80:83], v[20:23], v[84:87], v[80:83]
	v_lshlrev_b32_e32 v87, 16, v120
	v_mul_f32_e32 v135, v128, v144
	v_rcp_f32_e32 v128, v134
	v_mfma_f32_16x16x32_bf16 v[72:75], v[16:19], v[72:75], 0
	v_mad_u64_u32 v[84:85], s[8:9], v141, s14, v[102:103]
	v_mul_f32_e32 v134, v143, v128
	v_pk_mul_f32 v[92:93], v[134:135], v[92:93]
	v_lshlrev_b32_e32 v134, 16, v129
	v_and_b32_e32 v135, 0xffff0000, v129
	v_mul_f32_e32 v126, 0xbfb8aa3b, v134
	v_lshlrev_b32_e32 v128, 16, v127
	v_and_b32_e32 v129, 0xffff0000, v127
	v_mul_f32_e32 v127, 0xbfb8aa3b, v135
	v_exp_f32_e32 v126, v126
	v_exp_f32_e32 v127, v127
	v_pk_mul_f32 v[94:95], v[94:95], v[128:129]
	v_cvt_pk_bf16_f32 v92, v92, v93
	v_mad_i32_i24 v85, s37, v225, v85
	v_pk_add_f32 v[126:127], v[126:127], 1.0 op_sel_hi:[1,0]
	v_mfma_f32_16x16x32_bf16 v[72:75], v[20:23], v[76:79], v[72:75]
	v_rcp_f32_e32 v129, v127
	v_lshlrev_b32_e32 v79, 16, v116
	v_mfma_f32_16x16x32_bf16 v[60:63], v[16:19], v[60:63], 0
	v_mad_u64_u32 v[76:77], s[8:9], v140, s14, v[102:103]
	v_mul_f32_e32 v127, v135, v129
	v_rcp_f32_e32 v129, v126
	v_mad_i32_i24 v77, s37, v225, v77
	v_mfma_f32_16x16x32_bf16 v[60:63], v[20:23], v[64:67], v[60:63]
	v_lshlrev_b32_e32 v67, 16, v112
	v_mul_f32_e32 v126, v134, v129
	v_pk_mul_f32 v[94:95], v[126:127], v[94:95]
	v_lshlrev_b32_e32 v128, 16, v122
	v_cvt_pk_bf16_f32 v93, v94, v95
	global_store_dwordx2 v[130:131], v[92:93], off offset:1024
	v_lshlrev_b32_e32 v95, 16, v124
	v_and_b32_e32 v124, 0xffff0000, v124
	v_mul_f32_e32 v126, 0xbfb8aa3b, v95
	v_and_b32_e32 v129, 0xffff0000, v122
	v_mul_f32_e32 v122, 0xbfb8aa3b, v124
	v_exp_f32_e32 v126, v126
	v_exp_f32_e32 v127, v122
	v_mad_u64_u32 v[92:93], s[8:9], v142, s14, v[102:103]
	v_mad_i32_i24 v93, s37, v225, v93
	v_pk_add_f32 v[126:127], v[126:127], 1.0 op_sel_hi:[1,0]
	s_waitcnt lgkmcnt(1)
	v_mfma_f32_16x16x32_bf16 v[60:63], v[24:27], v[68:71], v[60:63]
	v_mul_f32_e32 v68, 0xbfb8aa3b, v67
	v_exp_f32_e32 v68, v68
	v_lshlrev_b32_e32 v70, 16, v110
	v_and_b32_e32 v71, 0xffff0000, v110
	v_mfma_f32_16x16x32_bf16 v[48:51], v[16:19], v[48:51], 0
	v_mad_u64_u32 v[64:65], s[8:9], v139, s14, v[102:103]
	v_mad_i32_i24 v65, s37, v225, v65
	v_mfma_f32_16x16x32_bf16 v[48:51], v[20:23], v[52:55], v[48:51]
	v_lshlrev_b32_e32 v55, 16, v108
	v_mad_u64_u32 v[52:53], s[8:9], v138, s14, v[102:103]
	v_mfma_f32_16x16x32_bf16 v[48:51], v[24:27], v[56:59], v[48:51]
	v_mul_f32_e32 v56, 0xbfb8aa3b, v55
	v_exp_f32_e32 v56, v56
	v_lshlrev_b32_e32 v58, 16, v106
	v_and_b32_e32 v59, 0xffff0000, v106
	v_mfma_f32_16x16x32_bf16 v[32:35], v[16:19], v[32:35], 0
	v_mad_i32_i24 v53, s37, v225, v53
	v_pk_add_f32 v[88:89], v[88:89], v[160:161] op_sel_hi:[1,0]
	s_nop 0
	v_pk_mul_f32 v[88:89], v[88:89], v[128:129]
	v_rcp_f32_e32 v128, v127
	v_mfma_f32_16x16x32_bf16 v[32:35], v[20:23], v[36:39], v[32:35]
	v_lshlrev_b32_e32 v39, 16, v104
	v_mad_u64_u32 v[36:37], s[8:9], v137, s14, v[102:103]
	v_mul_f32_e32 v127, v124, v128
	v_rcp_f32_e32 v124, v126
	v_mfma_f32_16x16x32_bf16 v[32:35], v[24:27], v[40:43], v[32:35]
	v_mul_f32_e32 v40, 0xbfb8aa3b, v39
	v_exp_f32_e32 v40, v40
	v_mul_f32_e32 v126, v95, v124
	v_pk_mul_f32 v[88:89], v[126:127], v[88:89]
	v_lshlrev_b32_e32 v126, 16, v125
	v_and_b32_e32 v127, 0xffff0000, v125
	v_mul_f32_e32 v95, 0xbfb8aa3b, v126
	v_pk_add_f32 v[90:91], v[90:91], v[160:161] op_sel_hi:[1,0]
	v_mul_f32_e32 v94, 0xbfb8aa3b, v127
	v_exp_f32_e32 v122, v95
	v_lshlrev_b32_e32 v124, 16, v123
	v_and_b32_e32 v125, 0xffff0000, v123
	v_exp_f32_e32 v123, v94
	v_pk_mul_f32 v[90:91], v[90:91], v[124:125]
	v_cvt_pk_bf16_f32 v88, v88, v89
	s_waitcnt lgkmcnt(0)
	v_mfma_f32_16x16x32_bf16 v[32:35], v[28:31], v[44:47], v[32:35]
	v_add_f32_e64 v94, v122, 1.0
	v_add_f32_e64 v95, v123, 1.0
	v_and_b32_e32 v44, 0xffff0000, v104
	v_rcp_f32_e32 v123, v95
	v_mul_f32_e32 v41, 0xbfb8aa3b, v44
	v_exp_f32_e32 v41, v41
	v_lshlrev_b32_e32 v42, 16, v100
	v_mul_f32_e32 v95, v127, v123
	v_rcp_f32_e32 v123, v94
	v_and_b32_e32 v43, 0xffff0000, v100
	v_pk_add_f32 v[40:41], v[40:41], 1.0 op_sel_hi:[1,0]
	v_mfma_f32_16x16x32_bf16 v[0:3], v[16:19], v[0:3], 0
	v_mul_f32_e32 v122, v126, v123
	v_mov_b32_e32 v94, v122
	v_pk_mul_f32 v[90:91], v[94:95], v[90:91]
	v_mad_i32_i24 v37, s37, v225, v37
	v_cvt_pk_bf16_f32 v89, v90, v91
	global_store_dwordx2 v[92:93], v[88:89], off offset:1024
	v_and_b32_e32 v92, 0xffff0000, v120
	v_mul_f32_e32 v88, 0xbfb8aa3b, v87
	v_mul_f32_e32 v89, 0xbfb8aa3b, v92
	v_exp_f32_e32 v88, v88
	v_exp_f32_e32 v89, v89
	v_lshlrev_b32_e32 v90, 16, v118
	v_and_b32_e32 v91, 0xffff0000, v118
	v_mfma_f32_16x16x32_bf16 v[0:3], v[20:23], v[4:7], v[0:3]
	v_add_f32_e64 v88, v88, 1.0
	v_add_f32_e64 v89, v89, 1.0
	v_lshlrev_b32_e32 v7, 16, v98
	v_mad_u64_u32 v[4:5], s[8:9], v133, s14, v[102:103]
	v_mfma_f32_16x16x32_bf16 v[0:3], v[24:27], v[8:11], v[0:3]
	v_mul_f32_e32 v8, 0xbfb8aa3b, v7
	v_exp_f32_e32 v8, v8
	v_lshlrev_b32_e32 v10, 16, v96
	v_mfma_f32_16x16x32_bf16 v[0:3], v[28:31], v[12:15], v[0:3]
	v_and_b32_e32 v12, 0xffff0000, v98
	v_mul_f32_e32 v9, 0xbfb8aa3b, v12
	v_exp_f32_e32 v9, v9
	v_and_b32_e32 v11, 0xffff0000, v96
	v_mad_i32_i24 v5, s37, v225, v5
	v_pk_add_f32 v[8:9], v[8:9], 1.0 op_sel_hi:[1,0]
	v_pk_add_f32 v[80:81], v[80:81], v[162:163] op_sel_hi:[1,0]
	s_nop 0
	v_pk_mul_f32 v[80:81], v[80:81], v[90:91]
	v_rcp_f32_e32 v91, v89
	s_nop 0
	v_mul_f32_e32 v89, v92, v91
	v_rcp_f32_e32 v91, v88
	s_nop 0
	v_mul_f32_e32 v90, v87, v91
	v_lshlrev_b32_e32 v92, 16, v121
	v_mov_b32_e32 v88, v90
	v_and_b32_e32 v93, 0xffff0000, v121
	v_mul_f32_e32 v87, 0xbfb8aa3b, v92
	v_pk_add_f32 v[82:83], v[82:83], v[162:163] op_sel_hi:[1,0]
	v_mul_f32_e32 v86, 0xbfb8aa3b, v93
	v_pk_mul_f32 v[80:81], v[88:89], v[80:81]
	v_exp_f32_e32 v88, v87
	v_exp_f32_e32 v89, v86
	v_lshlrev_b32_e32 v90, 16, v119
	v_and_b32_e32 v91, 0xffff0000, v119
	v_pk_mul_f32 v[82:83], v[82:83], v[90:91]
	v_pk_add_f32 v[86:87], v[88:89], 1.0 op_sel_hi:[1,0]
	v_cvt_pk_bf16_f32 v80, v80, v81
	v_rcp_f32_e32 v89, v87
	s_nop 0
	v_mul_f32_e32 v87, v93, v89
	v_rcp_f32_e32 v89, v86
	s_nop 0
	v_mul_f32_e32 v88, v92, v89
	v_mov_b32_e32 v86, v88
	v_pk_mul_f32 v[82:83], v[86:87], v[82:83]
	s_nop 0
	v_cvt_pk_bf16_f32 v81, v82, v83
	global_store_dwordx2 v[84:85], v[80:81], off offset:1024
	v_and_b32_e32 v84, 0xffff0000, v116
	v_mul_f32_e32 v80, 0xbfb8aa3b, v79
	v_mul_f32_e32 v81, 0xbfb8aa3b, v84
	v_exp_f32_e32 v80, v80
	v_exp_f32_e32 v81, v81
	v_lshlrev_b32_e32 v82, 16, v114
	v_and_b32_e32 v83, 0xffff0000, v114
	v_pk_add_f32 v[80:81], v[80:81], 1.0 op_sel_hi:[1,0]
	v_pk_add_f32 v[72:73], v[72:73], v[164:165] op_sel_hi:[1,0]
	s_nop 0
	v_pk_mul_f32 v[72:73], v[72:73], v[82:83]
	v_rcp_f32_e32 v83, v81
	s_nop 0
	v_mul_f32_e32 v81, v84, v83
	v_rcp_f32_e32 v83, v80
	s_nop 0
	v_mul_f32_e32 v82, v79, v83
	v_lshlrev_b32_e32 v84, 16, v117
	v_mov_b32_e32 v80, v82
	v_and_b32_e32 v85, 0xffff0000, v117
	v_mul_f32_e32 v79, 0xbfb8aa3b, v84
	v_pk_add_f32 v[74:75], v[74:75], v[164:165] op_sel_hi:[1,0]
	v_mul_f32_e32 v78, 0xbfb8aa3b, v85
	v_pk_mul_f32 v[72:73], v[80:81], v[72:73]
	v_exp_f32_e32 v80, v79
	v_exp_f32_e32 v81, v78
	v_lshlrev_b32_e32 v82, 16, v115
	v_and_b32_e32 v83, 0xffff0000, v115
	v_pk_mul_f32 v[74:75], v[74:75], v[82:83]
	v_pk_add_f32 v[78:79], v[80:81], 1.0 op_sel_hi:[1,0]
	v_cvt_pk_bf16_f32 v72, v72, v73
	v_rcp_f32_e32 v81, v79
	s_nop 0
	v_mul_f32_e32 v79, v85, v81
	v_rcp_f32_e32 v81, v78
	s_nop 0
	v_mul_f32_e32 v80, v84, v81
	v_mov_b32_e32 v78, v80
	v_pk_mul_f32 v[74:75], v[78:79], v[74:75]
	s_nop 0
	v_cvt_pk_bf16_f32 v73, v74, v75
	global_store_dwordx2 v[76:77], v[72:73], off offset:1024
	v_and_b32_e32 v72, 0xffff0000, v112
	v_mul_f32_e32 v69, 0xbfb8aa3b, v72
	v_exp_f32_e32 v69, v69
	v_pk_add_f32 v[60:61], v[60:61], v[166:167] op_sel_hi:[1,0]
	v_pk_add_f32 v[68:69], v[68:69], 1.0 op_sel_hi:[1,0]
	v_pk_mul_f32 v[60:61], v[60:61], v[70:71]
	v_rcp_f32_e32 v71, v69
	s_nop 0
	v_mul_f32_e32 v69, v72, v71
	v_rcp_f32_e32 v71, v68
	s_nop 0
	v_mul_f32_e32 v70, v67, v71
	v_lshlrev_b32_e32 v72, 16, v113
	v_mov_b32_e32 v68, v70
	v_and_b32_e32 v73, 0xffff0000, v113
	v_mul_f32_e32 v67, 0xbfb8aa3b, v72
	v_pk_add_f32 v[62:63], v[62:63], v[166:167] op_sel_hi:[1,0]
	v_mul_f32_e32 v66, 0xbfb8aa3b, v73
	v_pk_mul_f32 v[60:61], v[68:69], v[60:61]
	v_exp_f32_e32 v68, v67
	v_exp_f32_e32 v69, v66
	v_lshlrev_b32_e32 v70, 16, v111
	v_and_b32_e32 v71, 0xffff0000, v111
	v_pk_mul_f32 v[62:63], v[62:63], v[70:71]
	v_pk_add_f32 v[66:67], v[68:69], 1.0 op_sel_hi:[1,0]
	v_cvt_pk_bf16_f32 v60, v60, v61
	v_rcp_f32_e32 v69, v67
	s_nop 0
	v_mul_f32_e32 v67, v73, v69
	v_rcp_f32_e32 v69, v66
	s_nop 0
	v_mul_f32_e32 v68, v72, v69
	v_mov_b32_e32 v66, v68
	v_pk_mul_f32 v[62:63], v[66:67], v[62:63]
	s_nop 0
	v_cvt_pk_bf16_f32 v61, v62, v63
	global_store_dwordx2 v[64:65], v[60:61], off offset:1024
	v_and_b32_e32 v60, 0xffff0000, v108
	v_mul_f32_e32 v57, 0xbfb8aa3b, v60
	v_exp_f32_e32 v57, v57
	v_pk_add_f32 v[48:49], v[48:49], v[168:169] op_sel_hi:[1,0]
	v_pk_add_f32 v[56:57], v[56:57], 1.0 op_sel_hi:[1,0]
	v_pk_mul_f32 v[48:49], v[48:49], v[58:59]
	v_rcp_f32_e32 v59, v57
	s_nop 0
	v_mul_f32_e32 v57, v60, v59
	v_rcp_f32_e32 v59, v56
	s_nop 0
	v_mul_f32_e32 v58, v55, v59
	v_lshlrev_b32_e32 v60, 16, v109
	v_mov_b32_e32 v56, v58
	v_and_b32_e32 v61, 0xffff0000, v109
	v_mul_f32_e32 v55, 0xbfb8aa3b, v60
	v_pk_add_f32 v[50:51], v[50:51], v[168:169] op_sel_hi:[1,0]
	v_mul_f32_e32 v54, 0xbfb8aa3b, v61
	v_pk_mul_f32 v[48:49], v[56:57], v[48:49]
	v_exp_f32_e32 v56, v55
	v_exp_f32_e32 v57, v54
	v_lshlrev_b32_e32 v58, 16, v107
	v_and_b32_e32 v59, 0xffff0000, v107
	v_pk_mul_f32 v[50:51], v[50:51], v[58:59]
	v_pk_add_f32 v[54:55], v[56:57], 1.0 op_sel_hi:[1,0]
	v_cvt_pk_bf16_f32 v48, v48, v49
	v_rcp_f32_e32 v57, v55
	s_nop 0
	v_mul_f32_e32 v55, v61, v57
	v_rcp_f32_e32 v57, v54
	s_nop 0
	v_mul_f32_e32 v56, v60, v57
	v_mov_b32_e32 v54, v56
	v_pk_mul_f32 v[50:51], v[54:55], v[50:51]
	s_nop 0
	v_cvt_pk_bf16_f32 v49, v50, v51
	global_store_dwordx2 v[52:53], v[48:49], off offset:1024
	v_pk_add_f32 v[32:33], v[32:33], v[170:171] op_sel_hi:[1,0]
	s_nop 0
	v_pk_mul_f32 v[32:33], v[32:33], v[42:43]
	v_rcp_f32_e32 v43, v41
	s_nop 0
	v_mul_f32_e32 v41, v44, v43
	v_rcp_f32_e32 v43, v40
	s_nop 0
	v_mul_f32_e32 v42, v39, v43
	v_lshlrev_b32_e32 v44, 16, v105
	v_mov_b32_e32 v40, v42
	v_and_b32_e32 v45, 0xffff0000, v105
	v_mul_f32_e32 v39, 0xbfb8aa3b, v44
	v_pk_add_f32 v[34:35], v[34:35], v[170:171] op_sel_hi:[1,0]
	v_mul_f32_e32 v38, 0xbfb8aa3b, v45
	v_pk_mul_f32 v[32:33], v[40:41], v[32:33]
	v_exp_f32_e32 v40, v39
	v_exp_f32_e32 v41, v38
	v_lshlrev_b32_e32 v42, 16, v101
	v_and_b32_e32 v43, 0xffff0000, v101
	v_pk_mul_f32 v[34:35], v[34:35], v[42:43]
	v_pk_add_f32 v[38:39], v[40:41], 1.0 op_sel_hi:[1,0]
	v_cvt_pk_bf16_f32 v32, v32, v33
	v_rcp_f32_e32 v41, v39
	s_nop 0
	v_mul_f32_e32 v39, v45, v41
	v_rcp_f32_e32 v41, v38
	s_nop 0
	v_mul_f32_e32 v40, v44, v41
	v_mov_b32_e32 v38, v40
	v_pk_mul_f32 v[34:35], v[38:39], v[34:35]
	s_nop 0
	v_cvt_pk_bf16_f32 v33, v34, v35
	global_store_dwordx2 v[36:37], v[32:33], off offset:1024
	v_pk_add_f32 v[0:1], v[0:1], v[172:173] op_sel_hi:[1,0]
	s_nop 0
	v_pk_mul_f32 v[0:1], v[0:1], v[10:11]
	v_rcp_f32_e32 v11, v9
	s_nop 0
	v_mul_f32_e32 v9, v12, v11
	v_rcp_f32_e32 v11, v8
	s_nop 0
	v_mul_f32_e32 v10, v7, v11
	v_lshlrev_b32_e32 v12, 16, v99
	v_mov_b32_e32 v8, v10
	v_and_b32_e32 v13, 0xffff0000, v99
	v_mul_f32_e32 v7, 0xbfb8aa3b, v12
	v_pk_add_f32 v[2:3], v[2:3], v[172:173] op_sel_hi:[1,0]
	v_mul_f32_e32 v6, 0xbfb8aa3b, v13
	v_pk_mul_f32 v[0:1], v[8:9], v[0:1]
	v_exp_f32_e32 v8, v7
	v_exp_f32_e32 v9, v6
	v_lshlrev_b32_e32 v10, 16, v97
	v_and_b32_e32 v11, 0xffff0000, v97
	v_pk_mul_f32 v[2:3], v[2:3], v[10:11]
	v_pk_add_f32 v[6:7], v[8:9], 1.0 op_sel_hi:[1,0]
	v_cvt_pk_bf16_f32 v0, v0, v1
	v_rcp_f32_e32 v9, v7
	s_nop 0
	v_mul_f32_e32 v7, v13, v9
	v_rcp_f32_e32 v9, v6
	s_nop 0
	v_mul_f32_e32 v8, v12, v9
	v_mov_b32_e32 v6, v8
	v_pk_mul_f32 v[2:3], v[6:7], v[2:3]
	s_nop 0
	v_cvt_pk_bf16_f32 v1, v2, v3
	global_store_dwordx2 v[4:5], v[0:1], off offset:1024
	s_barrier
	s_cbranch_scc0 .LBB0_825
	s_branch .LBB0_826

.LBB0_848:
	s_lshl_b32 s1, s8, 15
	s_and_b32 s1, s1, 0x18000
	s_add_i32 s1, s1, 0
	v_add_u32_e32 v118, s1, v227
	v_add_u32_e32 v119, v118, v228
	ds_read_b128 v[114:117], v119 offset:16384
	v_readlane_b32 s1, v254, 40
	s_waitcnt lgkmcnt(0)
	v_mfma_f32_32x32x16_bf16 v[0:15], v[114:117], v[108:111], v[0:15]
	ds_read_b128 v[114:117], v119 offset:20480
	s_waitcnt lgkmcnt(0)
	v_mfma_f32_32x32x16_bf16 v[48:63], v[114:117], v[108:111], v[48:63]
	ds_read_b128 v[114:117], v119 offset:24576
	s_waitcnt lgkmcnt(0)
	v_mfma_f32_32x32x16_bf16 v[32:47], v[114:117], v[108:111], v[32:47]
	ds_read_b128 v[114:117], v119 offset:28672
	v_add_u32_e32 v119, v118, v231
	s_waitcnt lgkmcnt(0)
	v_mfma_f32_32x32x16_bf16 v[16:31], v[114:117], v[108:111], v[16:31]
	ds_read_b128 v[108:111], v119 offset:16384
	v_and_b32_e32 v116, 64, v224
	v_add_u32_e32 v114, v118, v229
	v_xor_b32_e32 v115, 32, v224
	v_add_u32_e32 v116, 64, v116
	v_cmp_lt_i32_e32 vcc, v115, v116
	s_waitcnt lgkmcnt(0)
	v_mfma_f32_32x32x16_bf16 v[0:15], v[108:111], v[104:107], v[0:15]
	ds_read_b128 v[108:111], v119 offset:20480
	v_cndmask_b32_e32 v115, v224, v115, vcc
	v_lshlrev_b32_e32 v227, 2, v115
	s_waitcnt lgkmcnt(0)
	v_mfma_f32_32x32x16_bf16 v[48:63], v[108:111], v[104:107], v[48:63]
	ds_read_b128 v[108:111], v119 offset:24576
	s_waitcnt lgkmcnt(0)
	v_mfma_f32_32x32x16_bf16 v[32:47], v[108:111], v[104:107], v[32:47]
	ds_read_b128 v[108:111], v119 offset:28672
	s_waitcnt lgkmcnt(0)
	v_mfma_f32_32x32x16_bf16 v[16:31], v[108:111], v[104:107], v[16:31]
	v_add_u32_e32 v108, v118, v230
	ds_read_b128 v[104:107], v108 offset:16384
	ds_bpermute_b32 v118, v227, v112
	s_waitcnt lgkmcnt(0)
	v_add_f32_e32 v112, v112, v118
	v_mfma_f32_32x32x16_bf16 v[0:15], v[104:107], v[100:103], v[0:15]
	ds_read_b128 v[104:107], v108 offset:20480
	s_waitcnt lgkmcnt(0)
	v_mfma_f32_32x32x16_bf16 v[48:63], v[104:107], v[100:103], v[48:63]
	ds_read_b128 v[104:107], v108 offset:24576
	ds_read_b128 v[108:111], v108 offset:28672
	s_waitcnt lgkmcnt(1)
	v_mfma_f32_32x32x16_bf16 v[32:47], v[104:107], v[100:103], v[32:47]
	ds_read_b128 v[104:107], v114 offset:16384
	s_waitcnt lgkmcnt(1)
	v_mfma_f32_32x32x16_bf16 v[16:31], v[108:111], v[100:103], v[16:31]
	ds_read_b128 v[100:103], v114 offset:20480
	ds_read_b128 v[108:111], v114 offset:24576
	ds_read_b128 v[114:117], v114 offset:28672
	s_waitcnt lgkmcnt(0)
	s_barrier
	v_mfma_f32_32x32x16_bf16 v[0:15], v[104:107], v[96:99], v[0:15]
	v_rcp_f32_e32 v105, v112
	v_readlane_b32 s8, v254, 41
	v_readlane_b32 s9, v254, 42
	v_mfma_f32_32x32x16_bf16 v[48:63], v[100:103], v[96:99], v[48:63]
	v_mfma_f32_32x32x16_bf16 v[32:47], v[108:111], v[96:99], v[32:47]
	v_mov_b32_e32 v112, v105
	v_cndmask_b32_e64 v100, 0, 1, s[8:9]
	v_cmp_ne_u32_e64 s[40:41], 1, v100
	v_lshlrev_b32_e32 v100, 9, v215
	v_lshlrev_b32_e32 v101, 2, v214
	s_andn2_b64 vcc, exec, s[8:9]
	v_mfma_f32_32x32x16_bf16 v[16:31], v[114:117], v[96:99], v[16:31]
	v_add3_u32 v100, s1, v100, v101
	s_cbranch_vccnz .LBB0_850
	v_mul_f32_e32 v96, v0, v112
	v_mul_f32_e32 v97, v1, v112
	ds_write2_b32 v100, v96, v97 offset1:32
	v_mul_f32_e32 v96, v2, v112
	v_mul_f32_e32 v97, v3, v112
	ds_write2_b32 v100, v96, v97 offset0:64 offset1:96
	v_mul_f32_e32 v96, v4, v112
	v_mul_f32_e32 v97, v5, v112
	v_add_u32_e32 v98, 0x400, v100
	ds_write2_b32 v98, v96, v97 offset1:32
	v_mul_f32_e32 v96, v6, v112
	v_mul_f32_e32 v97, v7, v112
	ds_write2_b32 v98, v96, v97 offset0:64 offset1:96
	v_mul_f32_e32 v96, v8, v112
	v_mul_f32_e32 v97, v9, v112
	v_add_u32_e32 v98, 0x800, v100
	ds_write2_b32 v98, v96, v97 offset1:32
	v_mul_f32_e32 v96, v10, v112
	v_mul_f32_e32 v97, v11, v112
	ds_write2_b32 v98, v96, v97 offset0:64 offset1:96
	v_mul_f32_e32 v96, v12, v112
	v_mul_f32_e32 v97, v13, v112
	v_add_u32_e32 v98, 0xc00, v100
	ds_write2_b32 v98, v96, v97 offset1:32
	v_mul_f32_e32 v96, v14, v112
	v_mul_f32_e32 v97, v15, v112
	ds_write2_b32 v98, v96, v97 offset0:64 offset1:96
	v_mul_f32_e32 v96, v48, v112
	v_mul_f32_e32 v97, v49, v112
	v_add_u32_e32 v98, 0x1000, v100
	ds_write2_b32 v98, v96, v97 offset1:32
	v_mul_f32_e32 v96, v50, v112
	v_mul_f32_e32 v97, v51, v112
	ds_write2_b32 v98, v96, v97 offset0:64 offset1:96
	v_mul_f32_e32 v96, v52, v112
	v_mul_f32_e32 v97, v53, v112
	v_add_u32_e32 v98, 0x1400, v100
	ds_write2_b32 v98, v96, v97 offset1:32
	v_mul_f32_e32 v96, v54, v112
	v_mul_f32_e32 v97, v55, v112
	ds_write2_b32 v98, v96, v97 offset0:64 offset1:96
	v_mul_f32_e32 v96, v56, v112
	v_mul_f32_e32 v97, v57, v112
	v_add_u32_e32 v98, 0x1800, v100
	ds_write2_b32 v98, v96, v97 offset1:32
	v_mul_f32_e32 v96, v58, v112
	v_mul_f32_e32 v97, v59, v112
	ds_write2_b32 v98, v96, v97 offset0:64 offset1:96
	v_mul_f32_e32 v96, v60, v112
	v_mul_f32_e32 v97, v61, v112
	v_add_u32_e32 v98, 0x1c00, v100
	ds_write2_b32 v98, v96, v97 offset1:32
	v_mul_f32_e32 v96, v62, v112
	v_mul_f32_e32 v97, v63, v112
	ds_write2_b32 v98, v96, v97 offset0:64 offset1:96
	v_mul_f32_e32 v96, v32, v112
	v_mul_f32_e32 v97, v33, v112
	v_add_u32_e32 v98, 0x2000, v100
	ds_write2_b32 v98, v96, v97 offset1:32
	v_mul_f32_e32 v96, v34, v112
	v_mul_f32_e32 v97, v35, v112
	ds_write2_b32 v98, v96, v97 offset0:64 offset1:96
	v_mul_f32_e32 v96, v36, v112
	v_mul_f32_e32 v97, v37, v112
	v_add_u32_e32 v98, 0x2400, v100
	ds_write2_b32 v98, v96, v97 offset1:32
	v_mul_f32_e32 v96, v38, v112
	v_mul_f32_e32 v97, v39, v112
	ds_write2_b32 v98, v96, v97 offset0:64 offset1:96
	v_mul_f32_e32 v96, v40, v112
	v_mul_f32_e32 v97, v41, v112
	v_add_u32_e32 v98, 0x2800, v100
	ds_write2_b32 v98, v96, v97 offset1:32
	v_mul_f32_e32 v96, v42, v112
	v_mul_f32_e32 v97, v43, v112
	ds_write2_b32 v98, v96, v97 offset0:64 offset1:96
	v_mul_f32_e32 v96, v44, v112
	v_mul_f32_e32 v97, v45, v112
	v_add_u32_e32 v98, 0x2c00, v100
	ds_write2_b32 v98, v96, v97 offset1:32
	v_mul_f32_e32 v96, v46, v112
	v_mul_f32_e32 v97, v47, v112
	ds_write2_b32 v98, v96, v97 offset0:64 offset1:96
	v_mul_f32_e32 v96, v16, v112
	v_mul_f32_e32 v97, v17, v112
	v_add_u32_e32 v98, 0x3000, v100
	ds_write2_b32 v98, v96, v97 offset1:32
	v_mul_f32_e32 v96, v18, v112
	v_mul_f32_e32 v97, v19, v112
	ds_write2_b32 v98, v96, v97 offset0:64 offset1:96
	v_mul_f32_e32 v96, v20, v112
	v_mul_f32_e32 v97, v21, v112
	v_add_u32_e32 v98, 0x3400, v100
	ds_write2_b32 v98, v96, v97 offset1:32
	v_mul_f32_e32 v96, v22, v112
	v_mul_f32_e32 v97, v23, v112
	ds_write2_b32 v98, v96, v97 offset0:64 offset1:96
	v_mul_f32_e32 v96, v24, v112
	v_mul_f32_e32 v97, v25, v112
	v_add_u32_e32 v98, 0x3800, v100
	ds_write2_b32 v98, v96, v97 offset1:32
	v_mul_f32_e32 v96, v26, v112
	v_mul_f32_e32 v97, v27, v112
	ds_write2_b32 v98, v96, v97 offset0:64 offset1:96
	v_mul_f32_e32 v96, v28, v112
	v_mul_f32_e32 v97, v29, v112
	v_add_u32_e32 v98, 0x3c00, v100
	ds_write2_b32 v98, v96, v97 offset1:32
	v_mul_f32_e32 v96, v30, v112
	v_mul_f32_e32 v97, v31, v112
	ds_write2_b32 v98, v96, v97 offset0:64 offset1:96
.LBB0_850:
	s_and_b64 vcc, exec, s[38:39]
	s_waitcnt lgkmcnt(0)
	s_barrier
	s_cbranch_vccnz .LBB0_852
	v_add_u32_e32 v101, 0x400, v100
	ds_read2_b32 v[96:97], v100 offset1:32
	ds_read2_b32 v[98:99], v100 offset0:64 offset1:96
	ds_read2_b32 v[104:105], v101 offset1:32
	ds_read2_b32 v[106:107], v101 offset0:64 offset1:96
	v_add_u32_e32 v101, 0x800, v100
	ds_read2_b32 v[114:115], v101 offset1:32
	ds_read2_b32 v[116:117], v101 offset0:64 offset1:96
	v_add_u32_e32 v101, 0xc00, v100
	ds_read2_b32 v[118:119], v101 offset1:32
	ds_read2_b32 v[120:121], v101 offset0:64 offset1:96
	v_add_u32_e32 v101, 0x1000, v100
	ds_read2_b32 v[122:123], v101 offset1:32
	ds_read2_b32 v[124:125], v101 offset0:64 offset1:96
	v_add_u32_e32 v101, 0x1400, v100
	ds_read2_b32 v[158:159], v101 offset1:32
	ds_read2_b32 v[160:161], v101 offset0:64 offset1:96
	v_add_u32_e32 v101, 0x1800, v100
	ds_read2_b32 v[162:163], v101 offset1:32
	ds_read2_b32 v[164:165], v101 offset0:64 offset1:96
	v_add_u32_e32 v101, 0x1c00, v100
	ds_read2_b32 v[166:167], v101 offset1:32
	ds_read2_b32 v[168:169], v101 offset0:64 offset1:96
	v_add_u32_e32 v101, 0x2000, v100
	ds_read2_b32 v[170:171], v101 offset1:32
	ds_read2_b32 v[172:173], v101 offset0:64 offset1:96
	v_add_u32_e32 v101, 0x2400, v100
	ds_read2_b32 v[174:175], v101 offset1:32
	ds_read2_b32 v[176:177], v101 offset0:64 offset1:96
	v_add_u32_e32 v101, 0x2800, v100
	ds_read2_b32 v[178:179], v101 offset1:32
	ds_read2_b32 v[180:181], v101 offset0:64 offset1:96
	v_add_u32_e32 v101, 0x2c00, v100
	ds_read2_b32 v[154:155], v101 offset1:32
	ds_read2_b32 v[182:183], v101 offset0:64 offset1:96
	v_add_u32_e32 v101, 0x3000, v100
	ds_read2_b32 v[148:149], v101 offset1:32
	ds_read2_b32 v[152:153], v101 offset0:64 offset1:96
	v_add_u32_e32 v101, 0x3400, v100
	ds_read2_b32 v[144:145], v101 offset1:32
	ds_read2_b32 v[146:147], v101 offset0:64 offset1:96
	v_add_u32_e32 v101, 0x3c00, v100
	ds_read2_b32 v[102:103], v101 offset1:32
	v_add_u32_e32 v108, 0x3800, v100
	ds_read2_b32 v[142:143], v108 offset1:32
	ds_read2_b32 v[100:101], v101 offset0:64 offset1:96
	ds_read2_b32 v[150:151], v108 offset0:64 offset1:96
	s_waitcnt lgkmcnt(12)
	v_pk_mul_f32 v[176:177], v[210:211], v[176:177]
	v_pk_mul_f32 v[174:175], v[210:211], v[174:175]
	s_waitcnt lgkmcnt(3)
	v_pk_mul_f32 v[102:103], v[210:211], v[102:103]
	v_pk_mul_f32 v[180:181], v[210:211], v[180:181]
	v_pk_fma_f32 v[108:109], v[28:29], v[112:113], v[102:103] op_sel_hi:[1,0,1] neg_lo:[0,0,1] neg_hi:[0,0,1]
	s_waitcnt lgkmcnt(1)
	v_pk_mul_f32 v[28:29], v[210:211], v[100:101]
	v_pk_mul_f32 v[178:179], v[210:211], v[178:179]
	v_pk_fma_f32 v[110:111], v[30:31], v[112:113], v[28:29] op_sel_hi:[1,0,1] neg_lo:[0,0,1] neg_hi:[0,0,1]
	v_pk_mul_f32 v[28:29], v[210:211], v[98:99]
	v_pk_mul_f32 v[182:183], v[210:211], v[182:183]
	v_pk_fma_f32 v[126:127], v[2:3], v[112:113], v[28:29] op_sel_hi:[1,0,1] neg_lo:[0,0,1] neg_hi:[0,0,1]
	v_pk_mul_f32 v[2:3], v[210:211], v[96:97]
	v_pk_mul_f32 v[154:155], v[210:211], v[154:155]
	v_pk_fma_f32 v[130:131], v[0:1], v[112:113], v[2:3] op_sel_hi:[1,0,1] neg_lo:[0,0,1] neg_hi:[0,0,1]
	v_pk_mul_f32 v[0:1], v[210:211], v[106:107]
	v_pk_mul_f32 v[186:187], v[130:131], v[130:131]
	v_pk_fma_f32 v[132:133], v[6:7], v[112:113], v[0:1] op_sel_hi:[1,0,1] neg_lo:[0,0,1] neg_hi:[0,0,1]
	v_pk_mul_f32 v[0:1], v[210:211], v[104:105]
	v_pk_mul_f32 v[152:153], v[210:211], v[152:153]
	v_pk_fma_f32 v[138:139], v[4:5], v[112:113], v[0:1] op_sel_hi:[1,0,1] neg_lo:[0,0,1] neg_hi:[0,0,1]
	v_pk_mul_f32 v[0:1], v[210:211], v[116:117]
	v_pk_mul_f32 v[4:5], v[210:211], v[120:121]
	v_pk_fma_f32 v[136:137], v[10:11], v[112:113], v[0:1] op_sel_hi:[1,0,1] neg_lo:[0,0,1] neg_hi:[0,0,1]
	v_pk_mul_f32 v[0:1], v[210:211], v[114:115]
	v_pk_fma_f32 v[114:115], v[14:15], v[112:113], v[4:5] op_sel_hi:[1,0,1] neg_lo:[0,0,1] neg_hi:[0,0,1]
	v_pk_mul_f32 v[4:5], v[210:211], v[118:119]
	v_pk_mul_f32 v[148:149], v[210:211], v[148:149]
	v_pk_fma_f32 v[116:117], v[12:13], v[112:113], v[4:5] op_sel_hi:[1,0,1] neg_lo:[0,0,1] neg_hi:[0,0,1]
	v_pk_mul_f32 v[4:5], v[210:211], v[124:125]
	v_pk_mul_f32 v[12:13], v[210:211], v[160:161]
	v_pk_fma_f32 v[118:119], v[50:51], v[112:113], v[4:5] op_sel_hi:[1,0,1] neg_lo:[0,0,1] neg_hi:[0,0,1]
	v_pk_mul_f32 v[4:5], v[210:211], v[122:123]
	v_pk_fma_f32 v[54:55], v[54:55], v[112:113], v[12:13] op_sel_hi:[1,0,1] neg_lo:[0,0,1] neg_hi:[0,0,1]
	v_pk_fma_f32 v[120:121], v[48:49], v[112:113], v[4:5] op_sel_hi:[1,0,1] neg_lo:[0,0,1] neg_hi:[0,0,1]
	v_pk_mul_f32 v[48:49], v[210:211], v[168:169]
	v_pk_mul_f32 v[12:13], v[210:211], v[158:159]
	v_pk_fma_f32 v[62:63], v[62:63], v[112:113], v[48:49] op_sel_hi:[1,0,1] neg_lo:[0,0,1] neg_hi:[0,0,1]
	v_pk_mul_f32 v[48:49], v[210:211], v[166:167]
	v_pk_fma_f32 v[52:53], v[52:53], v[112:113], v[12:13] op_sel_hi:[1,0,1] neg_lo:[0,0,1] neg_hi:[0,0,1]
	v_pk_mul_f32 v[12:13], v[210:211], v[164:165]
	v_pk_fma_f32 v[60:61], v[60:61], v[112:113], v[48:49] op_sel_hi:[1,0,1] neg_lo:[0,0,1] neg_hi:[0,0,1]
	v_pk_mul_f32 v[48:49], v[210:211], v[172:173]
	v_pk_fma_f32 v[58:59], v[58:59], v[112:113], v[12:13] op_sel_hi:[1,0,1] neg_lo:[0,0,1] neg_hi:[0,0,1]
	v_pk_mul_f32 v[12:13], v[210:211], v[162:163]
	v_pk_fma_f32 v[122:123], v[34:35], v[112:113], v[48:49] op_sel_hi:[1,0,1] neg_lo:[0,0,1] neg_hi:[0,0,1]
	v_pk_mul_f32 v[34:35], v[210:211], v[170:171]
	v_pk_mul_f32 v[146:147], v[210:211], v[146:147]
	v_pk_mul_f32 v[144:145], v[210:211], v[144:145]
	s_waitcnt lgkmcnt(0)
	v_pk_mul_f32 v[150:151], v[210:211], v[150:151]
	v_pk_mul_f32 v[142:143], v[210:211], v[142:143]
	v_lshlrev_b32_e32 v208, 2, v232
	v_pk_mul_f32 v[184:185], v[126:127], v[126:127]
	v_pk_fma_f32 v[140:141], v[8:9], v[112:113], v[0:1] op_sel_hi:[1,0,1] neg_lo:[0,0,1] neg_hi:[0,0,1]
	v_pk_fma_f32 v[56:57], v[56:57], v[112:113], v[12:13] op_sel_hi:[1,0,1] neg_lo:[0,0,1] neg_hi:[0,0,1]
	v_pk_fma_f32 v[124:125], v[32:33], v[112:113], v[34:35] op_sel_hi:[1,0,1] neg_lo:[0,0,1] neg_hi:[0,0,1]
	v_pk_fma_f32 v[38:39], v[38:39], v[112:113], v[176:177] op_sel_hi:[1,0,1] neg_lo:[0,0,1] neg_hi:[0,0,1]
	v_pk_fma_f32 v[36:37], v[36:37], v[112:113], v[174:175] op_sel_hi:[1,0,1] neg_lo:[0,0,1] neg_hi:[0,0,1]
	v_pk_fma_f32 v[42:43], v[42:43], v[112:113], v[180:181] op_sel_hi:[1,0,1] neg_lo:[0,0,1] neg_hi:[0,0,1]
	v_pk_fma_f32 v[40:41], v[40:41], v[112:113], v[178:179] op_sel_hi:[1,0,1] neg_lo:[0,0,1] neg_hi:[0,0,1]
	v_pk_fma_f32 v[46:47], v[46:47], v[112:113], v[182:183] op_sel_hi:[1,0,1] neg_lo:[0,0,1] neg_hi:[0,0,1]
	v_pk_fma_f32 v[44:45], v[44:45], v[112:113], v[154:155] op_sel_hi:[1,0,1] neg_lo:[0,0,1] neg_hi:[0,0,1]
	v_pk_fma_f32 v[18:19], v[18:19], v[112:113], v[152:153] op_sel_hi:[1,0,1] neg_lo:[0,0,1] neg_hi:[0,0,1]
	v_pk_fma_f32 v[16:17], v[16:17], v[112:113], v[148:149] op_sel_hi:[1,0,1] neg_lo:[0,0,1] neg_hi:[0,0,1]
	v_pk_fma_f32 v[22:23], v[22:23], v[112:113], v[146:147] op_sel_hi:[1,0,1] neg_lo:[0,0,1] neg_hi:[0,0,1]
	v_pk_fma_f32 v[20:21], v[20:21], v[112:113], v[144:145] op_sel_hi:[1,0,1] neg_lo:[0,0,1] neg_hi:[0,0,1]
	v_pk_fma_f32 v[26:27], v[26:27], v[112:113], v[150:151] op_sel_hi:[1,0,1] neg_lo:[0,0,1] neg_hi:[0,0,1]
	v_pk_fma_f32 v[24:25], v[24:25], v[112:113], v[142:143] op_sel_hi:[1,0,1] neg_lo:[0,0,1] neg_hi:[0,0,1]
	v_add_f32_e32 v112, v186, v187
	global_load_dwordx4 v[100:103], v208, s[36:37]
	global_load_dwordx4 v[96:99], v208, s[36:37] offset:32
	v_add_f32_e32 v112, v112, v184
	v_mul_u32_u24_e32 v157, 0x110, v214
	v_pk_mul_f32 v[214:215], v[138:139], v[138:139]
	v_add_f32_e32 v112, v112, v185
	v_add_f32_e32 v112, v112, v214
	v_pk_mul_f32 v[212:213], v[132:133], v[132:133]
	v_add_f32_e32 v112, v112, v215
	v_add_f32_e32 v112, v112, v212
	v_pk_mul_f32 v[230:231], v[140:141], v[140:141]
	v_add_f32_e32 v112, v112, v213
	global_load_dwordx4 v[104:107], v208, s[36:37] offset:64
	global_load_dwordx4 v[0:3], v208, s[36:37] offset:96
	v_add_f32_e32 v112, v112, v230
	v_pk_mul_f32 v[228:229], v[136:137], v[136:137]
	v_add_f32_e32 v112, v112, v231
	v_add_f32_e32 v112, v112, v228
	v_pk_mul_f32 v[236:237], v[116:117], v[116:117]
	v_add_f32_e32 v112, v112, v229
	v_add_f32_e32 v112, v112, v236
	v_pk_mul_f32 v[234:235], v[114:115], v[114:115]
	v_add_f32_e32 v112, v112, v237
	v_add_f32_e32 v112, v112, v234
	v_pk_mul_f32 v[240:241], v[120:121], v[120:121]
	v_add_f32_e32 v112, v112, v235
	v_add_f32_e32 v112, v112, v240
	v_pk_mul_f32 v[238:239], v[118:119], v[118:119]
	v_add_f32_e32 v112, v112, v241
	v_add_f32_e32 v112, v112, v238
	v_pk_mul_f32 v[158:159], v[52:53], v[52:53]
	v_add_f32_e32 v112, v112, v239
	v_add_f32_e32 v112, v112, v158
	v_pk_mul_f32 v[160:161], v[54:55], v[54:55]
	v_add_f32_e32 v112, v112, v159
	v_add_f32_e32 v112, v112, v160
	v_pk_mul_f32 v[162:163], v[56:57], v[56:57]
	v_add_f32_e32 v112, v112, v161
	v_add_f32_e32 v112, v112, v162
	v_pk_mul_f32 v[164:165], v[58:59], v[58:59]
	v_add_f32_e32 v112, v112, v163
	v_add_f32_e32 v112, v112, v164
	v_pk_mul_f32 v[166:167], v[60:61], v[60:61]
	v_add_f32_e32 v112, v112, v165
	v_add_f32_e32 v112, v112, v166
	v_pk_mul_f32 v[168:169], v[62:63], v[62:63]
	v_add_f32_e32 v112, v112, v167
	v_add_f32_e32 v112, v112, v168
	v_pk_mul_f32 v[170:171], v[124:125], v[124:125]
	v_add_f32_e32 v112, v112, v169
	v_add_f32_e32 v112, v112, v170
	v_pk_mul_f32 v[172:173], v[122:123], v[122:123]
	v_add_f32_e32 v112, v112, v171
	v_add_f32_e32 v112, v112, v172
	v_pk_mul_f32 v[174:175], v[36:37], v[36:37]
	v_add_f32_e32 v112, v112, v173
	v_add_f32_e32 v112, v112, v174
	v_pk_mul_f32 v[176:177], v[38:39], v[38:39]
	v_add_f32_e32 v112, v112, v175
	v_add_f32_e32 v112, v112, v176
	v_pk_mul_f32 v[178:179], v[40:41], v[40:41]
	v_add_f32_e32 v112, v112, v177
	v_add_f32_e32 v112, v112, v178
	v_pk_mul_f32 v[180:181], v[42:43], v[42:43]
	v_add_f32_e32 v112, v112, v179
	v_add_f32_e32 v112, v112, v180
	v_pk_mul_f32 v[154:155], v[44:45], v[44:45]
	v_add_f32_e32 v112, v112, v181
	v_add_f32_e32 v112, v112, v154
	v_pk_mul_f32 v[182:183], v[46:47], v[46:47]
	v_add_f32_e32 v112, v112, v155
	v_add_f32_e32 v112, v112, v182
	v_pk_mul_f32 v[148:149], v[16:17], v[16:17]
	v_add_f32_e32 v112, v112, v183
	v_add_f32_e32 v112, v112, v148
	v_pk_mul_f32 v[152:153], v[18:19], v[18:19]
	v_add_f32_e32 v112, v112, v149
	v_add_f32_e32 v112, v112, v152
	v_pk_mul_f32 v[144:145], v[20:21], v[20:21]
	v_add_f32_e32 v112, v112, v153
	v_add_f32_e32 v112, v112, v144
	v_pk_mul_f32 v[146:147], v[22:23], v[22:23]
	v_add_f32_e32 v112, v112, v145
	v_add_f32_e32 v112, v112, v146
	v_pk_mul_f32 v[142:143], v[24:25], v[24:25]
	v_add_f32_e32 v112, v112, v147
	v_add_f32_e32 v112, v112, v142
	v_pk_mul_f32 v[150:151], v[26:27], v[26:27]
	v_add_f32_e32 v112, v112, v143
	v_add_f32_e32 v112, v112, v150
	v_pk_mul_f32 v[128:129], v[108:109], v[108:109]
	v_add_f32_e32 v112, v112, v151
	v_add_f32_e32 v112, v112, v128
	v_pk_mul_f32 v[134:135], v[110:111], v[110:111]
	v_add_f32_e32 v112, v112, v129
	v_add_f32_e32 v112, v112, v134
	global_load_dwordx4 v[8:11], v208, s[36:37] offset:128
	global_load_dwordx4 v[4:7], v208, s[36:37] offset:160
	v_add_f32_e32 v112, v112, v135
	ds_bpermute_b32 v128, v227, v112
	global_load_dwordx4 v[28:31], v208, s[36:37] offset:192
	global_load_dwordx4 v[12:15], v208, s[36:37] offset:224
	global_load_dwordx4 v[48:51], v208, s[36:37] offset:256
	global_load_dwordx4 v[32:35], v208, s[36:37] offset:288
	v_lshlrev_b32_e32 v129, 1, v232
	v_readlane_b32 s7, v254, 43
	s_waitcnt lgkmcnt(0)
	v_add_f32_e32 v112, v112, v128
	v_fmamk_f32 v112, v112, 0x3c000000, v189
	v_mul_f32_e32 v128, 0x4b800000, v112
	v_cmp_gt_f32_e32 vcc, s13, v112
	global_load_dwordx4 v[142:145], v208, s[36:37] offset:320
	global_load_dwordx4 v[146:149], v208, s[36:37] offset:352
	v_cndmask_b32_e32 v112, v112, v128, vcc
	v_rsq_f32_e32 v112, v112
	v_add3_u32 v134, s7, v157, v129
	global_load_dwordx4 v[150:153], v208, s[36:37] offset:384
	global_load_dwordx4 v[158:161], v208, s[36:37] offset:416
	global_load_dwordx4 v[162:165], v208, s[36:37] offset:448
	s_lshl_b32 s1, s46, 1
	v_mul_f32_e32 v128, 0x45800000, v112
	v_cndmask_b32_e32 v112, v112, v128, vcc
	v_mul_f32_e32 v112, v209, v112
	v_pk_mul_f32 v[128:129], v[130:131], v[112:113] op_sel_hi:[1,0]
	v_pk_mul_f32 v[126:127], v[126:127], v[112:113] op_sel_hi:[1,0]
	s_waitcnt vmcnt(14)
	v_pk_mul_f32 v[100:101], v[100:101], v[128:129]
	v_pk_mul_f32 v[102:103], v[102:103], v[126:127]
	v_cvt_pk_bf16_f32 v100, v100, v101
	v_cvt_pk_bf16_f32 v101, v102, v103
	v_pk_mul_f32 v[102:103], v[138:139], v[112:113] op_sel_hi:[1,0]
	s_add_u32 s8, s82, s1
	s_waitcnt vmcnt(13)
	v_pk_mul_f32 v[96:97], v[96:97], v[102:103]
	v_pk_mul_f32 v[102:103], v[132:133], v[112:113] op_sel_hi:[1,0]
	v_cvt_pk_bf16_f32 v96, v96, v97
	v_pk_mul_f32 v[98:99], v[98:99], v[102:103]
	v_pk_mul_f32 v[102:103], v[116:117], v[112:113] op_sel_hi:[1,0]
	v_cvt_pk_bf16_f32 v97, v98, v99
	ds_write2_b64 v134, v[100:101], v[96:97] offset1:2
	v_pk_mul_f32 v[96:97], v[140:141], v[112:113] op_sel_hi:[1,0]
	s_waitcnt vmcnt(11)
	v_pk_mul_f32 v[0:1], v[0:1], v[102:103]
	v_pk_mul_f32 v[96:97], v[104:105], v[96:97]
	v_pk_mul_f32 v[102:103], v[114:115], v[112:113] op_sel_hi:[1,0]
	v_cvt_pk_bf16_f32 v100, v96, v97
	v_pk_mul_f32 v[96:97], v[136:137], v[112:113] op_sel_hi:[1,0]
	v_pk_mul_f32 v[2:3], v[2:3], v[102:103]
	v_pk_mul_f32 v[96:97], v[106:107], v[96:97]
	v_cvt_pk_bf16_f32 v0, v0, v1
	v_cvt_pk_bf16_f32 v101, v96, v97
	global_load_dwordx4 v[96:99], v208, s[36:37] offset:480
	v_cvt_pk_bf16_f32 v1, v2, v3
	ds_write2_b64 v134, v[100:101], v[0:1] offset0:4 offset1:6
	v_pk_mul_f32 v[0:1], v[120:121], v[112:113] op_sel_hi:[1,0]
	v_pk_mul_f32 v[2:3], v[118:119], v[112:113] op_sel_hi:[1,0]
	s_addc_u32 s9, s83, 0
	s_waitcnt vmcnt(11)
	v_pk_mul_f32 v[0:1], v[8:9], v[0:1]
	v_pk_mul_f32 v[2:3], v[10:11], v[2:3]
	v_cvt_pk_bf16_f32 v0, v0, v1
	v_cvt_pk_bf16_f32 v1, v2, v3
	v_pk_mul_f32 v[2:3], v[52:53], v[112:113] op_sel_hi:[1,0]
	v_lshl_add_u64 v[8:9], s[8:9], 0, v[194:195]
	s_waitcnt vmcnt(10)
	v_pk_mul_f32 v[2:3], v[4:5], v[2:3]
	v_pk_mul_f32 v[4:5], v[54:55], v[112:113] op_sel_hi:[1,0]
	v_cvt_pk_bf16_f32 v2, v2, v3
	v_pk_mul_f32 v[4:5], v[6:7], v[4:5]
	v_mad_u64_u32 v[10:11], s[8:9], v113, s14, v[8:9]
	v_cvt_pk_bf16_f32 v3, v4, v5
	ds_write2_b64 v134, v[0:1], v[2:3] offset0:8 offset1:10
	v_pk_mul_f32 v[0:1], v[56:57], v[112:113] op_sel_hi:[1,0]
	v_pk_mul_f32 v[2:3], v[58:59], v[112:113] op_sel_hi:[1,0]
	s_waitcnt vmcnt(9)
	v_pk_mul_f32 v[0:1], v[28:29], v[0:1]
	v_pk_mul_f32 v[2:3], v[30:31], v[2:3]
	v_cvt_pk_bf16_f32 v0, v0, v1
	v_cvt_pk_bf16_f32 v1, v2, v3
	v_pk_mul_f32 v[2:3], v[60:61], v[112:113] op_sel_hi:[1,0]
	v_pk_mul_f32 v[4:5], v[62:63], v[112:113] op_sel_hi:[1,0]
	s_waitcnt vmcnt(8)
	v_pk_mul_f32 v[2:3], v[2:3], v[12:13]
	v_pk_mul_f32 v[4:5], v[4:5], v[14:15]
	v_cvt_pk_bf16_f32 v2, v2, v3
	v_cvt_pk_bf16_f32 v3, v4, v5
	ds_write2_b64 v134, v[0:1], v[2:3] offset0:12 offset1:14
	v_pk_mul_f32 v[0:1], v[124:125], v[112:113] op_sel_hi:[1,0]
	v_pk_mul_f32 v[2:3], v[122:123], v[112:113] op_sel_hi:[1,0]
	s_waitcnt vmcnt(7)
	v_pk_mul_f32 v[0:1], v[0:1], v[48:49]
	v_pk_mul_f32 v[2:3], v[2:3], v[50:51]
	v_cvt_pk_bf16_f32 v0, v0, v1
	v_cvt_pk_bf16_f32 v1, v2, v3
	v_pk_mul_f32 v[2:3], v[36:37], v[112:113] op_sel_hi:[1,0]
	v_pk_mul_f32 v[4:5], v[38:39], v[112:113] op_sel_hi:[1,0]
	s_waitcnt vmcnt(6)
	v_pk_mul_f32 v[2:3], v[2:3], v[32:33]
	v_pk_mul_f32 v[4:5], v[4:5], v[34:35]
	v_cvt_pk_bf16_f32 v2, v2, v3
	v_cvt_pk_bf16_f32 v3, v4, v5
	ds_write2_b64 v134, v[0:1], v[2:3] offset0:16 offset1:18
	v_pk_mul_f32 v[0:1], v[40:41], v[112:113] op_sel_hi:[1,0]
	v_pk_mul_f32 v[2:3], v[42:43], v[112:113] op_sel_hi:[1,0]
	s_waitcnt vmcnt(5)
	v_pk_mul_f32 v[0:1], v[0:1], v[142:143]
	v_pk_mul_f32 v[2:3], v[2:3], v[144:145]
	v_cvt_pk_bf16_f32 v0, v0, v1
	v_cvt_pk_bf16_f32 v1, v2, v3
	v_pk_mul_f32 v[2:3], v[44:45], v[112:113] op_sel_hi:[1,0]
	v_pk_mul_f32 v[4:5], v[46:47], v[112:113] op_sel_hi:[1,0]
	s_waitcnt vmcnt(4)
	v_pk_mul_f32 v[2:3], v[2:3], v[146:147]
	v_pk_mul_f32 v[4:5], v[4:5], v[148:149]
	v_cvt_pk_bf16_f32 v2, v2, v3
	v_cvt_pk_bf16_f32 v3, v4, v5
	ds_write2_b64 v134, v[0:1], v[2:3] offset0:20 offset1:22
	v_pk_mul_f32 v[0:1], v[16:17], v[112:113] op_sel_hi:[1,0]
	v_pk_mul_f32 v[2:3], v[18:19], v[112:113] op_sel_hi:[1,0]
	s_waitcnt vmcnt(3)
	v_pk_mul_f32 v[0:1], v[0:1], v[150:151]
	v_pk_mul_f32 v[2:3], v[2:3], v[152:153]
	v_cvt_pk_bf16_f32 v0, v0, v1
	v_cvt_pk_bf16_f32 v1, v2, v3
	v_pk_mul_f32 v[2:3], v[20:21], v[112:113] op_sel_hi:[1,0]
	v_pk_mul_f32 v[4:5], v[22:23], v[112:113] op_sel_hi:[1,0]
	s_waitcnt vmcnt(2)
	v_pk_mul_f32 v[2:3], v[2:3], v[158:159]
	v_pk_mul_f32 v[4:5], v[4:5], v[160:161]
	v_cvt_pk_bf16_f32 v2, v2, v3
	v_cvt_pk_bf16_f32 v3, v4, v5
	ds_write2_b64 v134, v[0:1], v[2:3] offset0:24 offset1:26
	v_pk_mul_f32 v[0:1], v[24:25], v[112:113] op_sel_hi:[1,0]
	v_pk_mul_f32 v[2:3], v[26:27], v[112:113] op_sel_hi:[1,0]
	s_waitcnt vmcnt(1)
	v_pk_mul_f32 v[0:1], v[0:1], v[162:163]
	v_pk_mul_f32 v[2:3], v[2:3], v[164:165]
	v_cvt_pk_bf16_f32 v0, v0, v1
	v_cvt_pk_bf16_f32 v1, v2, v3
	v_pk_mul_f32 v[2:3], v[108:109], v[112:113] op_sel_hi:[1,0]
	v_pk_mul_f32 v[4:5], v[110:111], v[112:113] op_sel_hi:[1,0]
	s_waitcnt vmcnt(0)
	v_pk_mul_f32 v[2:3], v[2:3], v[96:97]
	v_pk_mul_f32 v[4:5], v[4:5], v[98:99]
	v_cvt_pk_bf16_f32 v2, v2, v3
	v_cvt_pk_bf16_f32 v3, v4, v5
	ds_write2_b64 v134, v[0:1], v[2:3] offset0:28 offset1:30
	v_mul_u32_u24_e32 v0, 0x110, v156
	v_lshlrev_b32_e32 v13, 16, v92
	v_and_b32_e32 v18, 0xffff0000, v92
	v_add3_u32 v12, s7, v194, v0
	v_mul_f32_e32 v0, 0xbfb8aa3b, v13
	v_mul_f32_e32 v1, 0xbfb8aa3b, v18
	v_exp_f32_e32 v0, v0
	v_exp_f32_e32 v1, v1
	s_waitcnt lgkmcnt(0)
	ds_read_b128 v[4:7], v12
	v_and_b32_e32 v23, 0xffff0000, v93
	v_pk_add_f32 v[14:15], v[0:1], 1.0 op_sel_hi:[1,0]
	ds_read_b128 v[0:3], v12 offset:1088
	v_rcp_f32_e32 v20, v15
	s_waitcnt lgkmcnt(1)
	v_lshlrev_b32_e32 v16, 16, v4
	v_and_b32_e32 v17, 0xffff0000, v4
	v_add_u32_e32 v11, s0, v11
	v_rcp_f32_e32 v22, v14
	v_mul_f32_e32 v15, v18, v20
	v_lshlrev_b32_e32 v21, 16, v93
	v_mul_f32_e32 v18, 0xbfb8aa3b, v21
	v_mul_f32_e32 v19, 0xbfb8aa3b, v23
	v_exp_f32_e32 v18, v18
	v_exp_f32_e32 v19, v19
	v_mul_f32_e32 v14, v13, v22
	v_pk_mul_f32 v[14:15], v[14:15], v[16:17]
	v_pk_add_f32 v[16:17], v[18:19], 1.0 op_sel_hi:[1,0]
	v_cvt_pk_bf16_f32 v4, v14, v15
	v_rcp_f32_e32 v18, v17
	v_lshlrev_b32_e32 v14, 16, v5
	v_and_b32_e32 v15, 0xffff0000, v5
	v_rcp_f32_e32 v20, v16
	v_mul_f32_e32 v17, v23, v18
	v_and_b32_e32 v23, 0xffff0000, v94
	v_lshlrev_b32_e32 v13, 16, v94
	v_mul_f32_e32 v18, 0xbfb8aa3b, v13
	v_mul_f32_e32 v19, 0xbfb8aa3b, v23
	v_exp_f32_e32 v18, v18
	v_exp_f32_e32 v19, v19
	v_mul_f32_e32 v16, v21, v20
	v_pk_mul_f32 v[14:15], v[16:17], v[14:15]
	v_pk_add_f32 v[16:17], v[18:19], 1.0 op_sel_hi:[1,0]
	v_cvt_pk_bf16_f32 v5, v14, v15
	v_rcp_f32_e32 v19, v17
	v_lshlrev_b32_e32 v14, 16, v6
	v_and_b32_e32 v15, 0xffff0000, v6
	v_lshlrev_b32_e32 v22, 16, v95
	v_rcp_f32_e32 v21, v16
	v_mul_f32_e32 v17, v23, v19
	v_and_b32_e32 v23, 0xffff0000, v95
	v_mul_f32_e32 v18, 0xbfb8aa3b, v22
	v_mul_f32_e32 v19, 0xbfb8aa3b, v23
	v_exp_f32_e32 v18, v18
	v_exp_f32_e32 v19, v19
	v_mul_f32_e32 v16, v13, v21
	v_pk_mul_f32 v[14:15], v[16:17], v[14:15]
	v_pk_add_f32 v[16:17], v[18:19], 1.0 op_sel_hi:[1,0]
	v_cvt_pk_bf16_f32 v6, v14, v15
	v_rcp_f32_e32 v18, v17
	v_lshlrev_b32_e32 v14, 16, v7
	v_and_b32_e32 v15, 0xffff0000, v7
	v_rcp_f32_e32 v20, v16
	v_mul_f32_e32 v17, v23, v18
	v_and_b32_e32 v23, 0xffff0000, v85
	v_mul_f32_e32 v16, v22, v20
	v_pk_mul_f32 v[14:15], v[16:17], v[14:15]
	v_lshlrev_b32_e32 v13, 16, v88
	v_cvt_pk_bf16_f32 v7, v14, v15
	v_and_b32_e32 v14, 0xffff0000, v88
	global_store_dwordx4 v[10:11], v[4:7], off offset:2048
	s_waitcnt lgkmcnt(0)
	v_lshlrev_b32_e32 v10, 16, v0
	v_and_b32_e32 v11, 0xffff0000, v0
	v_mul_f32_e32 v4, 0xbfb8aa3b, v13
	v_mul_f32_e32 v5, 0xbfb8aa3b, v14
	v_exp_f32_e32 v4, v4
	v_exp_f32_e32 v5, v5
	v_and_b32_e32 v19, 0xffff0000, v89
	v_or_b32_e32 v6, 4, v113
	v_mad_u64_u32 v[6:7], s[8:9], v6, s14, v[8:9]
	v_pk_add_f32 v[4:5], v[4:5], 1.0 op_sel_hi:[1,0]
	v_add_u32_e32 v7, s0, v7
	v_rcp_f32_e32 v16, v5
	s_nop 0
	v_rcp_f32_e32 v18, v4
	v_mul_f32_e32 v5, v14, v16
	v_lshlrev_b32_e32 v17, 16, v89
	v_mul_f32_e32 v14, 0xbfb8aa3b, v17
	v_mul_f32_e32 v15, 0xbfb8aa3b, v19
	v_exp_f32_e32 v14, v14
	v_exp_f32_e32 v15, v15
	v_mul_f32_e32 v4, v13, v18
	v_pk_mul_f32 v[4:5], v[4:5], v[10:11]
	v_pk_add_f32 v[10:11], v[14:15], 1.0 op_sel_hi:[1,0]
	v_cvt_pk_bf16_f32 v0, v4, v5
	v_rcp_f32_e32 v14, v11
	v_lshlrev_b32_e32 v4, 16, v1
	v_and_b32_e32 v5, 0xffff0000, v1
	v_rcp_f32_e32 v16, v10
	v_mul_f32_e32 v11, v19, v14
	v_and_b32_e32 v19, 0xffff0000, v90
	v_lshlrev_b32_e32 v13, 16, v90
	v_mul_f32_e32 v14, 0xbfb8aa3b, v13
	v_mul_f32_e32 v15, 0xbfb8aa3b, v19
	v_exp_f32_e32 v14, v14
	v_exp_f32_e32 v15, v15
	v_mul_f32_e32 v10, v17, v16
	v_pk_mul_f32 v[4:5], v[10:11], v[4:5]
	v_pk_add_f32 v[10:11], v[14:15], 1.0 op_sel_hi:[1,0]
	v_cvt_pk_bf16_f32 v1, v4, v5
	v_rcp_f32_e32 v15, v11
	v_lshlrev_b32_e32 v4, 16, v2
	v_and_b32_e32 v5, 0xffff0000, v2
	v_lshlrev_b32_e32 v18, 16, v91
	v_rcp_f32_e32 v17, v10
	v_mul_f32_e32 v11, v19, v15
	v_and_b32_e32 v19, 0xffff0000, v91
	v_mul_f32_e32 v14, 0xbfb8aa3b, v18
	v_mul_f32_e32 v15, 0xbfb8aa3b, v19
	v_exp_f32_e32 v14, v14
	v_exp_f32_e32 v15, v15
	v_mul_f32_e32 v10, v13, v17
	v_pk_mul_f32 v[4:5], v[10:11], v[4:5]
	v_pk_add_f32 v[10:11], v[14:15], 1.0 op_sel_hi:[1,0]
	v_cvt_pk_bf16_f32 v2, v4, v5
	v_rcp_f32_e32 v14, v11
	v_lshlrev_b32_e32 v4, 16, v3
	v_and_b32_e32 v5, 0xffff0000, v3
	v_rcp_f32_e32 v16, v10
	v_mul_f32_e32 v11, v19, v14
	v_mul_f32_e32 v10, v18, v16
	v_pk_mul_f32 v[4:5], v[10:11], v[4:5]
	v_lshlrev_b32_e32 v13, 16, v84
	v_cvt_pk_bf16_f32 v3, v4, v5
	v_and_b32_e32 v18, 0xffff0000, v84
	global_store_dwordx4 v[6:7], v[0:3], off offset:2048
	ds_read_b128 v[4:7], v12 offset:2176
	s_nop 0
	v_mul_f32_e32 v0, 0xbfb8aa3b, v13
	v_mul_f32_e32 v1, 0xbfb8aa3b, v18
	v_exp_f32_e32 v0, v0
	v_exp_f32_e32 v1, v1
	v_or_b32_e32 v2, 8, v113
	v_mad_u64_u32 v[10:11], s[8:9], v2, s14, v[8:9]
	v_pk_add_f32 v[14:15], v[0:1], 1.0 op_sel_hi:[1,0]
	ds_read_b128 v[0:3], v12 offset:3264
	v_rcp_f32_e32 v20, v15
	s_waitcnt lgkmcnt(1)
	v_lshlrev_b32_e32 v16, 16, v4
	v_and_b32_e32 v17, 0xffff0000, v4
	v_add_u32_e32 v11, s0, v11
	v_rcp_f32_e32 v22, v14
	v_mul_f32_e32 v15, v18, v20
	v_lshlrev_b32_e32 v21, 16, v85
	v_mul_f32_e32 v18, 0xbfb8aa3b, v21
	v_mul_f32_e32 v19, 0xbfb8aa3b, v23
	v_exp_f32_e32 v18, v18
	v_exp_f32_e32 v19, v19
	v_mul_f32_e32 v14, v13, v22
	v_pk_mul_f32 v[14:15], v[14:15], v[16:17]
	v_pk_add_f32 v[16:17], v[18:19], 1.0 op_sel_hi:[1,0]
	v_cvt_pk_bf16_f32 v4, v14, v15
	v_rcp_f32_e32 v18, v17
	v_lshlrev_b32_e32 v14, 16, v5
	v_and_b32_e32 v15, 0xffff0000, v5
	v_rcp_f32_e32 v20, v16
	v_mul_f32_e32 v17, v23, v18
	v_and_b32_e32 v23, 0xffff0000, v86
	v_lshlrev_b32_e32 v13, 16, v86
	v_mul_f32_e32 v18, 0xbfb8aa3b, v13
	v_mul_f32_e32 v19, 0xbfb8aa3b, v23
	v_exp_f32_e32 v18, v18
	v_exp_f32_e32 v19, v19
	v_mul_f32_e32 v16, v21, v20
	v_pk_mul_f32 v[14:15], v[16:17], v[14:15]
	v_pk_add_f32 v[16:17], v[18:19], 1.0 op_sel_hi:[1,0]
	v_cvt_pk_bf16_f32 v5, v14, v15
	v_rcp_f32_e32 v19, v17
	v_lshlrev_b32_e32 v14, 16, v6
	v_and_b32_e32 v15, 0xffff0000, v6
	v_lshlrev_b32_e32 v22, 16, v87
	v_rcp_f32_e32 v21, v16
	v_mul_f32_e32 v17, v23, v19
	v_and_b32_e32 v23, 0xffff0000, v87
	v_mul_f32_e32 v18, 0xbfb8aa3b, v22
	v_mul_f32_e32 v19, 0xbfb8aa3b, v23
	v_exp_f32_e32 v18, v18
	v_exp_f32_e32 v19, v19
	v_mul_f32_e32 v16, v13, v21
	v_pk_mul_f32 v[14:15], v[16:17], v[14:15]
	v_pk_add_f32 v[16:17], v[18:19], 1.0 op_sel_hi:[1,0]
	v_cvt_pk_bf16_f32 v6, v14, v15
	v_rcp_f32_e32 v18, v17
	v_lshlrev_b32_e32 v14, 16, v7
	v_and_b32_e32 v15, 0xffff0000, v7
	v_rcp_f32_e32 v20, v16
	v_mul_f32_e32 v17, v23, v18
	v_and_b32_e32 v23, 0xffff0000, v77
	v_mul_f32_e32 v16, v22, v20
	v_pk_mul_f32 v[14:15], v[16:17], v[14:15]
	v_lshlrev_b32_e32 v13, 16, v80
	v_cvt_pk_bf16_f32 v7, v14, v15
	v_and_b32_e32 v14, 0xffff0000, v80
	global_store_dwordx4 v[10:11], v[4:7], off offset:2048
	s_waitcnt lgkmcnt(0)
	v_lshlrev_b32_e32 v10, 16, v0
	v_and_b32_e32 v11, 0xffff0000, v0
	v_mul_f32_e32 v4, 0xbfb8aa3b, v13
	v_mul_f32_e32 v5, 0xbfb8aa3b, v14
	v_exp_f32_e32 v4, v4
	v_exp_f32_e32 v5, v5
	v_and_b32_e32 v19, 0xffff0000, v81
	v_or_b32_e32 v6, 12, v113
	v_mad_u64_u32 v[6:7], s[8:9], v6, s14, v[8:9]
	v_pk_add_f32 v[4:5], v[4:5], 1.0 op_sel_hi:[1,0]
	v_add_u32_e32 v7, s0, v7
	v_rcp_f32_e32 v16, v5
	s_nop 0
	v_rcp_f32_e32 v18, v4
	v_mul_f32_e32 v5, v14, v16
	v_lshlrev_b32_e32 v17, 16, v81
	v_mul_f32_e32 v14, 0xbfb8aa3b, v17
	v_mul_f32_e32 v15, 0xbfb8aa3b, v19
	v_exp_f32_e32 v14, v14
	v_exp_f32_e32 v15, v15
	v_mul_f32_e32 v4, v13, v18
	v_pk_mul_f32 v[4:5], v[4:5], v[10:11]
	v_pk_add_f32 v[10:11], v[14:15], 1.0 op_sel_hi:[1,0]
	v_cvt_pk_bf16_f32 v0, v4, v5
	v_rcp_f32_e32 v14, v11
	v_lshlrev_b32_e32 v4, 16, v1
	v_and_b32_e32 v5, 0xffff0000, v1
	v_rcp_f32_e32 v16, v10
	v_mul_f32_e32 v11, v19, v14
	v_and_b32_e32 v19, 0xffff0000, v82
	v_lshlrev_b32_e32 v13, 16, v82
	v_mul_f32_e32 v14, 0xbfb8aa3b, v13
	v_mul_f32_e32 v15, 0xbfb8aa3b, v19
	v_exp_f32_e32 v14, v14
	v_exp_f32_e32 v15, v15
	v_mul_f32_e32 v10, v17, v16
	v_pk_mul_f32 v[4:5], v[10:11], v[4:5]
	v_pk_add_f32 v[10:11], v[14:15], 1.0 op_sel_hi:[1,0]
	v_cvt_pk_bf16_f32 v1, v4, v5
	v_rcp_f32_e32 v15, v11
	v_lshlrev_b32_e32 v4, 16, v2
	v_and_b32_e32 v5, 0xffff0000, v2
	v_lshlrev_b32_e32 v18, 16, v83
	v_rcp_f32_e32 v17, v10
	v_mul_f32_e32 v11, v19, v15
	v_and_b32_e32 v19, 0xffff0000, v83
	v_mul_f32_e32 v14, 0xbfb8aa3b, v18
	v_mul_f32_e32 v15, 0xbfb8aa3b, v19
	v_exp_f32_e32 v14, v14
	v_exp_f32_e32 v15, v15
	v_mul_f32_e32 v10, v13, v17
	v_pk_mul_f32 v[4:5], v[10:11], v[4:5]
	v_pk_add_f32 v[10:11], v[14:15], 1.0 op_sel_hi:[1,0]
	v_cvt_pk_bf16_f32 v2, v4, v5
	v_rcp_f32_e32 v14, v11
	v_lshlrev_b32_e32 v4, 16, v3
	v_and_b32_e32 v5, 0xffff0000, v3
	v_rcp_f32_e32 v16, v10
	v_mul_f32_e32 v11, v19, v14
	v_mul_f32_e32 v10, v18, v16
	v_pk_mul_f32 v[4:5], v[10:11], v[4:5]
	v_lshlrev_b32_e32 v13, 16, v76
	v_cvt_pk_bf16_f32 v3, v4, v5
	v_and_b32_e32 v18, 0xffff0000, v76
	global_store_dwordx4 v[6:7], v[0:3], off offset:2048
	ds_read_b128 v[4:7], v12 offset:4352
	s_nop 0
	v_mul_f32_e32 v0, 0xbfb8aa3b, v13
	v_mul_f32_e32 v1, 0xbfb8aa3b, v18
	v_exp_f32_e32 v0, v0
	v_exp_f32_e32 v1, v1
	v_or_b32_e32 v2, 16, v113
	v_mad_u64_u32 v[10:11], s[8:9], v2, s14, v[8:9]
	v_pk_add_f32 v[14:15], v[0:1], 1.0 op_sel_hi:[1,0]
	ds_read_b128 v[0:3], v12 offset:5440
	v_rcp_f32_e32 v20, v15
	s_waitcnt lgkmcnt(1)
	v_lshlrev_b32_e32 v16, 16, v4
	v_and_b32_e32 v17, 0xffff0000, v4
	v_add_u32_e32 v11, s0, v11
	v_rcp_f32_e32 v22, v14
	v_mul_f32_e32 v15, v18, v20
	v_lshlrev_b32_e32 v21, 16, v77
	v_mul_f32_e32 v18, 0xbfb8aa3b, v21
	v_mul_f32_e32 v19, 0xbfb8aa3b, v23
	v_exp_f32_e32 v18, v18
	v_exp_f32_e32 v19, v19
	v_mul_f32_e32 v14, v13, v22
	v_pk_mul_f32 v[14:15], v[14:15], v[16:17]
	v_pk_add_f32 v[16:17], v[18:19], 1.0 op_sel_hi:[1,0]
	v_cvt_pk_bf16_f32 v4, v14, v15
	v_rcp_f32_e32 v18, v17
	v_lshlrev_b32_e32 v14, 16, v5
	v_and_b32_e32 v15, 0xffff0000, v5
	v_rcp_f32_e32 v20, v16
	v_mul_f32_e32 v17, v23, v18
	v_and_b32_e32 v23, 0xffff0000, v78
	v_lshlrev_b32_e32 v13, 16, v78
	v_mul_f32_e32 v18, 0xbfb8aa3b, v13
	v_mul_f32_e32 v19, 0xbfb8aa3b, v23
	v_exp_f32_e32 v18, v18
	v_exp_f32_e32 v19, v19
	v_mul_f32_e32 v16, v21, v20
	v_pk_mul_f32 v[14:15], v[16:17], v[14:15]
	v_pk_add_f32 v[16:17], v[18:19], 1.0 op_sel_hi:[1,0]
	v_cvt_pk_bf16_f32 v5, v14, v15
	v_rcp_f32_e32 v19, v17
	v_lshlrev_b32_e32 v14, 16, v6
	v_and_b32_e32 v15, 0xffff0000, v6
	v_lshlrev_b32_e32 v22, 16, v79
	v_rcp_f32_e32 v21, v16
	v_mul_f32_e32 v17, v23, v19
	v_and_b32_e32 v23, 0xffff0000, v79
	v_mul_f32_e32 v18, 0xbfb8aa3b, v22
	v_mul_f32_e32 v19, 0xbfb8aa3b, v23
	v_exp_f32_e32 v18, v18
	v_exp_f32_e32 v19, v19
	v_mul_f32_e32 v16, v13, v21
	v_pk_mul_f32 v[14:15], v[16:17], v[14:15]
	v_pk_add_f32 v[16:17], v[18:19], 1.0 op_sel_hi:[1,0]
	v_cvt_pk_bf16_f32 v6, v14, v15
	v_rcp_f32_e32 v18, v17
	v_lshlrev_b32_e32 v14, 16, v7
	v_and_b32_e32 v15, 0xffff0000, v7
	v_rcp_f32_e32 v20, v16
	v_mul_f32_e32 v17, v23, v18
	v_mul_f32_e32 v16, v22, v20
	v_pk_mul_f32 v[14:15], v[16:17], v[14:15]
	v_lshlrev_b32_e32 v13, 16, v72
	v_cvt_pk_bf16_f32 v7, v14, v15
	v_and_b32_e32 v14, 0xffff0000, v72
	global_store_dwordx4 v[10:11], v[4:7], off offset:2048
	s_waitcnt lgkmcnt(0)
	v_lshlrev_b32_e32 v10, 16, v0
	v_and_b32_e32 v11, 0xffff0000, v0
	v_mul_f32_e32 v4, 0xbfb8aa3b, v13
	v_mul_f32_e32 v5, 0xbfb8aa3b, v14
	v_exp_f32_e32 v4, v4
	v_exp_f32_e32 v5, v5
	v_and_b32_e32 v19, 0xffff0000, v73
	v_or_b32_e32 v6, 20, v113
	v_mad_u64_u32 v[6:7], s[8:9], v6, s14, v[8:9]
	v_pk_add_f32 v[4:5], v[4:5], 1.0 op_sel_hi:[1,0]
	v_add_u32_e32 v7, s0, v7
	v_rcp_f32_e32 v16, v5
	v_and_b32_e32 v22, 0xffff0000, v69
	v_rcp_f32_e32 v18, v4
	v_mul_f32_e32 v5, v14, v16
	v_lshlrev_b32_e32 v17, 16, v73
	v_mul_f32_e32 v14, 0xbfb8aa3b, v17
	v_mul_f32_e32 v15, 0xbfb8aa3b, v19
	v_exp_f32_e32 v14, v14
	v_exp_f32_e32 v15, v15
	v_mul_f32_e32 v4, v13, v18
	v_pk_mul_f32 v[4:5], v[4:5], v[10:11]
	v_pk_add_f32 v[10:11], v[14:15], 1.0 op_sel_hi:[1,0]
	v_cvt_pk_bf16_f32 v0, v4, v5
	v_rcp_f32_e32 v14, v11
	v_lshlrev_b32_e32 v4, 16, v1
	v_and_b32_e32 v5, 0xffff0000, v1
	v_rcp_f32_e32 v16, v10
	v_mul_f32_e32 v11, v19, v14
	v_and_b32_e32 v19, 0xffff0000, v74
	v_lshlrev_b32_e32 v13, 16, v74
	v_mul_f32_e32 v14, 0xbfb8aa3b, v13
	v_mul_f32_e32 v15, 0xbfb8aa3b, v19
	v_exp_f32_e32 v14, v14
	v_exp_f32_e32 v15, v15
	v_mul_f32_e32 v10, v17, v16
	v_pk_mul_f32 v[4:5], v[10:11], v[4:5]
	v_pk_add_f32 v[10:11], v[14:15], 1.0 op_sel_hi:[1,0]
	v_cvt_pk_bf16_f32 v1, v4, v5
	v_rcp_f32_e32 v15, v11
	v_lshlrev_b32_e32 v4, 16, v2
	v_and_b32_e32 v5, 0xffff0000, v2
	v_lshlrev_b32_e32 v18, 16, v75
	v_rcp_f32_e32 v17, v10
	v_mul_f32_e32 v11, v19, v15
	v_and_b32_e32 v19, 0xffff0000, v75
	v_mul_f32_e32 v14, 0xbfb8aa3b, v18
	v_mul_f32_e32 v15, 0xbfb8aa3b, v19
	v_exp_f32_e32 v14, v14
	v_exp_f32_e32 v15, v15
	v_mul_f32_e32 v10, v13, v17
	v_pk_mul_f32 v[4:5], v[10:11], v[4:5]
	v_pk_add_f32 v[10:11], v[14:15], 1.0 op_sel_hi:[1,0]
	v_cvt_pk_bf16_f32 v2, v4, v5
	v_rcp_f32_e32 v14, v11
	v_lshlrev_b32_e32 v4, 16, v3
	v_and_b32_e32 v5, 0xffff0000, v3
	v_rcp_f32_e32 v16, v10
	v_mul_f32_e32 v11, v19, v14
	v_mul_f32_e32 v10, v18, v16
	v_pk_mul_f32 v[4:5], v[10:11], v[4:5]
	v_lshlrev_b32_e32 v18, 16, v68
	v_cvt_pk_bf16_f32 v3, v4, v5
	v_and_b32_e32 v16, 0xffff0000, v68
	global_store_dwordx4 v[6:7], v[0:3], off offset:2048
	ds_read_b128 v[4:7], v12 offset:6528
	s_nop 0
	v_mul_f32_e32 v0, 0xbfb8aa3b, v18
	v_mul_f32_e32 v1, 0xbfb8aa3b, v16
	v_exp_f32_e32 v0, v0
	v_exp_f32_e32 v1, v1
	v_or_b32_e32 v2, 24, v113
	v_mad_u64_u32 v[10:11], s[8:9], v2, s14, v[8:9]
	v_pk_add_f32 v[14:15], v[0:1], 1.0 op_sel_hi:[1,0]
	ds_read_b128 v[0:3], v12 offset:7616
	v_rcp_f32_e32 v19, v15
	s_waitcnt lgkmcnt(1)
	v_lshlrev_b32_e32 v12, 16, v4
	v_and_b32_e32 v13, 0xffff0000, v4
	v_add_u32_e32 v11, s0, v11
	v_rcp_f32_e32 v21, v14
	v_mul_f32_e32 v15, v16, v19
	v_lshlrev_b32_e32 v20, 16, v69
	v_mul_f32_e32 v16, 0xbfb8aa3b, v20
	v_mul_f32_e32 v17, 0xbfb8aa3b, v22
	v_exp_f32_e32 v16, v16
	v_exp_f32_e32 v17, v17
	v_mul_f32_e32 v14, v18, v21
	v_pk_mul_f32 v[12:13], v[14:15], v[12:13]
	v_pk_add_f32 v[14:15], v[16:17], 1.0 op_sel_hi:[1,0]
	v_cvt_pk_bf16_f32 v4, v12, v13
	v_rcp_f32_e32 v17, v15
	v_lshlrev_b32_e32 v12, 16, v5
	v_and_b32_e32 v13, 0xffff0000, v5
	v_lshlrev_b32_e32 v21, 16, v70
	v_rcp_f32_e32 v19, v14
	v_mul_f32_e32 v15, v22, v17
	v_and_b32_e32 v22, 0xffff0000, v70
	v_mul_f32_e32 v16, 0xbfb8aa3b, v21
	v_mul_f32_e32 v17, 0xbfb8aa3b, v22
	v_exp_f32_e32 v16, v16
	v_exp_f32_e32 v17, v17
	v_mul_f32_e32 v14, v20, v19
	v_pk_mul_f32 v[12:13], v[14:15], v[12:13]
	v_pk_add_f32 v[14:15], v[16:17], 1.0 op_sel_hi:[1,0]
	v_cvt_pk_bf16_f32 v5, v12, v13
	v_rcp_f32_e32 v17, v15
	v_lshlrev_b32_e32 v12, 16, v6
	v_and_b32_e32 v13, 0xffff0000, v6
	v_lshlrev_b32_e32 v20, 16, v71
	v_rcp_f32_e32 v19, v14
	v_mul_f32_e32 v15, v22, v17
	v_and_b32_e32 v22, 0xffff0000, v71
	v_mul_f32_e32 v16, 0xbfb8aa3b, v20
	v_mul_f32_e32 v17, 0xbfb8aa3b, v22
	v_exp_f32_e32 v16, v16
	v_exp_f32_e32 v17, v17
	v_mul_f32_e32 v14, v21, v19
	v_pk_mul_f32 v[12:13], v[14:15], v[12:13]
	v_pk_add_f32 v[14:15], v[16:17], 1.0 op_sel_hi:[1,0]
	v_cvt_pk_bf16_f32 v6, v12, v13
	v_rcp_f32_e32 v17, v15
	v_lshlrev_b32_e32 v12, 16, v7
	v_and_b32_e32 v13, 0xffff0000, v7
	v_rcp_f32_e32 v19, v14
	v_mul_f32_e32 v15, v22, v17
	v_mul_f32_e32 v14, v20, v19
	v_pk_mul_f32 v[12:13], v[14:15], v[12:13]
	v_and_b32_e32 v16, 0xffff0000, v65
	v_cvt_pk_bf16_f32 v7, v12, v13
	global_store_dwordx4 v[10:11], v[4:7], off offset:2048
	v_lshlrev_b32_e32 v12, 16, v64
	v_and_b32_e32 v10, 0xffff0000, v64
	v_mul_f32_e32 v4, 0xbfb8aa3b, v12
	v_mul_f32_e32 v5, 0xbfb8aa3b, v10
	v_exp_f32_e32 v4, v4
	v_exp_f32_e32 v5, v5
	v_or_b32_e32 v6, 28, v113
	v_mad_u64_u32 v[6:7], s[8:9], v6, s14, v[8:9]
	v_pk_add_f32 v[4:5], v[4:5], 1.0 op_sel_hi:[1,0]
	s_waitcnt lgkmcnt(0)
	v_lshlrev_b32_e32 v8, 16, v0
	v_rcp_f32_e32 v13, v5
	v_and_b32_e32 v9, 0xffff0000, v0
	v_add_u32_e32 v7, s0, v7
	v_rcp_f32_e32 v15, v4
	v_mul_f32_e32 v5, v10, v13
	v_lshlrev_b32_e32 v14, 16, v65
	v_mul_f32_e32 v10, 0xbfb8aa3b, v14
	v_mul_f32_e32 v11, 0xbfb8aa3b, v16
	v_exp_f32_e32 v10, v10
	v_exp_f32_e32 v11, v11
	v_mul_f32_e32 v4, v12, v15
	v_pk_mul_f32 v[4:5], v[4:5], v[8:9]
	v_pk_add_f32 v[8:9], v[10:11], 1.0 op_sel_hi:[1,0]
	v_cvt_pk_bf16_f32 v0, v4, v5
	v_rcp_f32_e32 v11, v9
	v_lshlrev_b32_e32 v4, 16, v1
	v_and_b32_e32 v5, 0xffff0000, v1
	v_lshlrev_b32_e32 v15, 16, v66
	v_rcp_f32_e32 v13, v8
	v_mul_f32_e32 v9, v16, v11
	v_and_b32_e32 v16, 0xffff0000, v66
	v_mul_f32_e32 v10, 0xbfb8aa3b, v15
	v_mul_f32_e32 v11, 0xbfb8aa3b, v16
	v_exp_f32_e32 v10, v10
	v_exp_f32_e32 v11, v11
	v_mul_f32_e32 v8, v14, v13
	v_pk_mul_f32 v[4:5], v[8:9], v[4:5]
	v_pk_add_f32 v[8:9], v[10:11], 1.0 op_sel_hi:[1,0]
	v_cvt_pk_bf16_f32 v1, v4, v5
	v_rcp_f32_e32 v11, v9
	v_lshlrev_b32_e32 v4, 16, v2
	v_and_b32_e32 v5, 0xffff0000, v2
	v_lshlrev_b32_e32 v14, 16, v67
	v_rcp_f32_e32 v13, v8
	v_mul_f32_e32 v9, v16, v11
	v_and_b32_e32 v16, 0xffff0000, v67
	v_mul_f32_e32 v10, 0xbfb8aa3b, v14
	v_mul_f32_e32 v11, 0xbfb8aa3b, v16
	v_exp_f32_e32 v10, v10
	v_exp_f32_e32 v11, v11
	v_mul_f32_e32 v8, v15, v13
	v_pk_mul_f32 v[4:5], v[8:9], v[4:5]
	v_pk_add_f32 v[8:9], v[10:11], 1.0 op_sel_hi:[1,0]
	v_cvt_pk_bf16_f32 v2, v4, v5
	v_rcp_f32_e32 v11, v9
	v_lshlrev_b32_e32 v4, 16, v3
	v_and_b32_e32 v5, 0xffff0000, v3
	v_rcp_f32_e32 v13, v8
	v_mul_f32_e32 v9, v16, v11
	v_mul_f32_e32 v8, v14, v13
	v_pk_mul_f32 v[4:5], v[8:9], v[4:5]
	s_nop 0
	v_cvt_pk_bf16_f32 v3, v4, v5
	global_store_dwordx4 v[6:7], v[0:3], off offset:2048

.LBB0_879:
	s_lshl_b32 s1, s9, 15
	s_and_b32 s1, s1, 0x18000
	s_add_i32 s1, s1, 0
	v_add_u32_e32 v112, s1, v229
	v_add_u32_e32 v115, v112, v230
	ds_read_b128 v[116:119], v115 offset:16384
	v_readlane_b32 s1, v254, 40
	s_waitcnt lgkmcnt(0)
	v_mfma_f32_32x32x16_bf16 v[0:15], v[116:119], v[108:111], v[0:15]
	ds_read_b128 v[116:119], v115 offset:20480
	s_waitcnt lgkmcnt(0)
	v_mfma_f32_32x32x16_bf16 v[48:63], v[116:119], v[108:111], v[48:63]
	ds_read_b128 v[116:119], v115 offset:24576
	s_waitcnt lgkmcnt(0)
	v_mfma_f32_32x32x16_bf16 v[32:47], v[116:119], v[108:111], v[32:47]
	ds_read_b128 v[116:119], v115 offset:28672
	v_add_u32_e32 v115, v112, v233
	s_waitcnt lgkmcnt(0)
	v_mfma_f32_32x32x16_bf16 v[16:31], v[116:119], v[108:111], v[16:31]
	ds_read_b128 v[108:111], v115 offset:16384
	s_waitcnt lgkmcnt(0)
	v_mfma_f32_32x32x16_bf16 v[0:15], v[108:111], v[104:107], v[0:15]
	ds_read_b128 v[108:111], v115 offset:20480
	s_waitcnt lgkmcnt(0)
	v_mfma_f32_32x32x16_bf16 v[48:63], v[108:111], v[104:107], v[48:63]
	ds_read_b128 v[108:111], v115 offset:24576
	s_waitcnt lgkmcnt(0)
	v_mfma_f32_32x32x16_bf16 v[32:47], v[108:111], v[104:107], v[32:47]
	ds_read_b128 v[108:111], v115 offset:28672
	ds_bpermute_b32 v115, v227, v114
	s_waitcnt lgkmcnt(1)
	v_mfma_f32_32x32x16_bf16 v[16:31], v[108:111], v[104:107], v[16:31]
	v_add_u32_e32 v108, v112, v232
	ds_read_b128 v[104:107], v108 offset:16384
	v_add_u32_e32 v112, v112, v231
	s_waitcnt lgkmcnt(0)
	v_mfma_f32_32x32x16_bf16 v[0:15], v[104:107], v[100:103], v[0:15]
	ds_read_b128 v[104:107], v108 offset:20480
	s_waitcnt lgkmcnt(0)
	v_mfma_f32_32x32x16_bf16 v[48:63], v[104:107], v[100:103], v[48:63]
	ds_read_b128 v[104:107], v108 offset:24576
	s_waitcnt lgkmcnt(0)
	v_mfma_f32_32x32x16_bf16 v[32:47], v[104:107], v[100:103], v[32:47]
	ds_read_b128 v[104:107], v108 offset:28672
	s_waitcnt lgkmcnt(0)
	v_mfma_f32_32x32x16_bf16 v[16:31], v[104:107], v[100:103], v[16:31]
	ds_read_b128 v[100:103], v112 offset:16384
	ds_read_b128 v[104:107], v112 offset:20480
	ds_read_b128 v[108:111], v112 offset:24576
	ds_read_b128 v[116:119], v112 offset:28672
	s_waitcnt lgkmcnt(0)
	s_barrier
	v_mfma_f32_32x32x16_bf16 v[0:15], v[100:103], v[96:99], v[0:15]
	v_add_f32_e32 v100, v114, v115
	v_rcp_f32_e32 v102, v100
	s_nop 0
	v_mfma_f32_32x32x16_bf16 v[48:63], v[104:107], v[96:99], v[48:63]
	v_mfma_f32_32x32x16_bf16 v[32:47], v[108:111], v[96:99], v[32:47]
	v_mov_b32_e32 v112, v102
	v_lshlrev_b32_e32 v100, 9, v228
	v_lshlrev_b32_e32 v101, 2, v213
	s_and_b64 vcc, exec, s[40:41]
	v_add3_u32 v100, s1, v100, v101
	v_mfma_f32_32x32x16_bf16 v[16:31], v[116:119], v[96:99], v[16:31]
	s_cbranch_vccnz .LBB0_881
	v_mul_f32_e32 v96, v0, v112
	v_mul_f32_e32 v97, v1, v112
	ds_write2_b32 v100, v96, v97 offset1:32
	v_mul_f32_e32 v96, v2, v112
	v_mul_f32_e32 v97, v3, v112
	ds_write2_b32 v100, v96, v97 offset0:64 offset1:96
	v_mul_f32_e32 v96, v4, v112
	v_mul_f32_e32 v97, v5, v112
	v_add_u32_e32 v98, 0x400, v100
	ds_write2_b32 v98, v96, v97 offset1:32
	v_mul_f32_e32 v96, v6, v112
	v_mul_f32_e32 v97, v7, v112
	ds_write2_b32 v98, v96, v97 offset0:64 offset1:96
	v_mul_f32_e32 v96, v8, v112
	v_mul_f32_e32 v97, v9, v112
	v_add_u32_e32 v98, 0x800, v100
	ds_write2_b32 v98, v96, v97 offset1:32
	v_mul_f32_e32 v96, v10, v112
	v_mul_f32_e32 v97, v11, v112
	ds_write2_b32 v98, v96, v97 offset0:64 offset1:96
	v_mul_f32_e32 v96, v12, v112
	v_mul_f32_e32 v97, v13, v112
	v_add_u32_e32 v98, 0xc00, v100
	ds_write2_b32 v98, v96, v97 offset1:32
	v_mul_f32_e32 v96, v14, v112
	v_mul_f32_e32 v97, v15, v112
	ds_write2_b32 v98, v96, v97 offset0:64 offset1:96
	v_mul_f32_e32 v96, v48, v112
	v_mul_f32_e32 v97, v49, v112
	v_add_u32_e32 v98, 0x1000, v100
	ds_write2_b32 v98, v96, v97 offset1:32
	v_mul_f32_e32 v96, v50, v112
	v_mul_f32_e32 v97, v51, v112
	ds_write2_b32 v98, v96, v97 offset0:64 offset1:96
	v_mul_f32_e32 v96, v52, v112
	v_mul_f32_e32 v97, v53, v112
	v_add_u32_e32 v98, 0x1400, v100
	ds_write2_b32 v98, v96, v97 offset1:32
	v_mul_f32_e32 v96, v54, v112
	v_mul_f32_e32 v97, v55, v112
	ds_write2_b32 v98, v96, v97 offset0:64 offset1:96
	v_mul_f32_e32 v96, v56, v112
	v_mul_f32_e32 v97, v57, v112
	v_add_u32_e32 v98, 0x1800, v100
	ds_write2_b32 v98, v96, v97 offset1:32
	v_mul_f32_e32 v96, v58, v112
	v_mul_f32_e32 v97, v59, v112
	ds_write2_b32 v98, v96, v97 offset0:64 offset1:96
	v_mul_f32_e32 v96, v60, v112
	v_mul_f32_e32 v97, v61, v112
	v_add_u32_e32 v98, 0x1c00, v100
	ds_write2_b32 v98, v96, v97 offset1:32
	v_mul_f32_e32 v96, v62, v112
	v_mul_f32_e32 v97, v63, v112
	ds_write2_b32 v98, v96, v97 offset0:64 offset1:96
	v_mul_f32_e32 v96, v32, v112
	v_mul_f32_e32 v97, v33, v112
	v_add_u32_e32 v98, 0x2000, v100
	ds_write2_b32 v98, v96, v97 offset1:32
	v_mul_f32_e32 v96, v34, v112
	v_mul_f32_e32 v97, v35, v112
	ds_write2_b32 v98, v96, v97 offset0:64 offset1:96
	v_mul_f32_e32 v96, v36, v112
	v_mul_f32_e32 v97, v37, v112
	v_add_u32_e32 v98, 0x2400, v100
	ds_write2_b32 v98, v96, v97 offset1:32
	v_mul_f32_e32 v96, v38, v112
	v_mul_f32_e32 v97, v39, v112
	ds_write2_b32 v98, v96, v97 offset0:64 offset1:96
	v_mul_f32_e32 v96, v40, v112
	v_mul_f32_e32 v97, v41, v112
	v_add_u32_e32 v98, 0x2800, v100
	ds_write2_b32 v98, v96, v97 offset1:32
	v_mul_f32_e32 v96, v42, v112
	v_mul_f32_e32 v97, v43, v112
	ds_write2_b32 v98, v96, v97 offset0:64 offset1:96
	v_mul_f32_e32 v96, v44, v112
	v_mul_f32_e32 v97, v45, v112
	v_add_u32_e32 v98, 0x2c00, v100
	ds_write2_b32 v98, v96, v97 offset1:32
	v_mul_f32_e32 v96, v46, v112
	v_mul_f32_e32 v97, v47, v112
	ds_write2_b32 v98, v96, v97 offset0:64 offset1:96
	v_mul_f32_e32 v96, v16, v112
	v_mul_f32_e32 v97, v17, v112
	v_add_u32_e32 v98, 0x3000, v100
	ds_write2_b32 v98, v96, v97 offset1:32
	v_mul_f32_e32 v96, v18, v112
	v_mul_f32_e32 v97, v19, v112
	ds_write2_b32 v98, v96, v97 offset0:64 offset1:96
	v_mul_f32_e32 v96, v20, v112
	v_mul_f32_e32 v97, v21, v112
	v_add_u32_e32 v98, 0x3400, v100
	ds_write2_b32 v98, v96, v97 offset1:32
	v_mul_f32_e32 v96, v22, v112
	v_mul_f32_e32 v97, v23, v112
	ds_write2_b32 v98, v96, v97 offset0:64 offset1:96
	v_mul_f32_e32 v96, v24, v112
	v_mul_f32_e32 v97, v25, v112
	v_add_u32_e32 v98, 0x3800, v100
	ds_write2_b32 v98, v96, v97 offset1:32
	v_mul_f32_e32 v96, v26, v112
	v_mul_f32_e32 v97, v27, v112
	ds_write2_b32 v98, v96, v97 offset0:64 offset1:96
	v_mul_f32_e32 v96, v28, v112
	v_mul_f32_e32 v97, v29, v112
	v_add_u32_e32 v98, 0x3c00, v100
	ds_write2_b32 v98, v96, v97 offset1:32
	v_mul_f32_e32 v96, v30, v112
	v_mul_f32_e32 v97, v31, v112
	ds_write2_b32 v98, v96, v97 offset0:64 offset1:96
.LBB0_881:
	s_and_b64 vcc, exec, s[38:39]
	s_waitcnt lgkmcnt(0)
	s_barrier
	s_cbranch_vccnz .LBB0_828
	v_add_u32_e32 v101, 0x400, v100
	ds_read2_b32 v[96:97], v100 offset1:32
	ds_read2_b32 v[98:99], v100 offset0:64 offset1:96
	ds_read2_b32 v[104:105], v101 offset1:32
	ds_read2_b32 v[106:107], v101 offset0:64 offset1:96
	v_add_u32_e32 v101, 0x800, v100
	ds_read2_b32 v[116:117], v101 offset1:32
	ds_read2_b32 v[118:119], v101 offset0:64 offset1:96
	v_add_u32_e32 v101, 0xc00, v100
	ds_read2_b32 v[120:121], v101 offset1:32
	ds_read2_b32 v[122:123], v101 offset0:64 offset1:96
	v_add_u32_e32 v101, 0x1000, v100
	ds_read2_b32 v[124:125], v101 offset1:32
	ds_read2_b32 v[126:127], v101 offset0:64 offset1:96
	v_add_u32_e32 v101, 0x1400, v100
	ds_read2_b32 v[160:161], v101 offset1:32
	ds_read2_b32 v[162:163], v101 offset0:64 offset1:96
	v_add_u32_e32 v101, 0x1800, v100
	ds_read2_b32 v[164:165], v101 offset1:32
	ds_read2_b32 v[166:167], v101 offset0:64 offset1:96
	v_add_u32_e32 v101, 0x1c00, v100
	ds_read2_b32 v[168:169], v101 offset1:32
	ds_read2_b32 v[170:171], v101 offset0:64 offset1:96
	v_add_u32_e32 v101, 0x2000, v100
	ds_read2_b32 v[172:173], v101 offset1:32
	ds_read2_b32 v[174:175], v101 offset0:64 offset1:96
	v_add_u32_e32 v101, 0x2400, v100
	ds_read2_b32 v[176:177], v101 offset1:32
	ds_read2_b32 v[178:179], v101 offset0:64 offset1:96
	v_add_u32_e32 v101, 0x2800, v100
	ds_read2_b32 v[180:181], v101 offset1:32
	ds_read2_b32 v[182:183], v101 offset0:64 offset1:96
	v_add_u32_e32 v101, 0x2c00, v100
	ds_read2_b32 v[156:157], v101 offset1:32
	ds_read2_b32 v[184:185], v101 offset0:64 offset1:96
	v_add_u32_e32 v101, 0x3000, v100
	ds_read2_b32 v[150:151], v101 offset1:32
	ds_read2_b32 v[154:155], v101 offset0:64 offset1:96
	v_add_u32_e32 v101, 0x3400, v100
	ds_read2_b32 v[146:147], v101 offset1:32
	ds_read2_b32 v[148:149], v101 offset0:64 offset1:96
	v_add_u32_e32 v101, 0x3c00, v100
	ds_read2_b32 v[102:103], v101 offset1:32
	v_add_u32_e32 v108, 0x3800, v100
	ds_read2_b32 v[144:145], v108 offset1:32
	ds_read2_b32 v[100:101], v101 offset0:64 offset1:96
	ds_read2_b32 v[152:153], v108 offset0:64 offset1:96
	v_mul_u32_u24_e32 v159, 0x110, v213
	v_mov_b32_e32 v213, v195
	s_waitcnt lgkmcnt(3)
	v_pk_mul_f32 v[102:103], v[210:211], v[102:103]
	v_pk_mul_f32 v[178:179], v[210:211], v[178:179]
	v_pk_fma_f32 v[108:109], v[28:29], v[112:113], v[102:103] op_sel_hi:[1,0,1] neg_lo:[0,0,1] neg_hi:[0,0,1]
	s_waitcnt lgkmcnt(1)
	v_pk_mul_f32 v[28:29], v[210:211], v[100:101]
	v_pk_mul_f32 v[176:177], v[210:211], v[176:177]
	v_pk_fma_f32 v[110:111], v[30:31], v[112:113], v[28:29] op_sel_hi:[1,0,1] neg_lo:[0,0,1] neg_hi:[0,0,1]
	v_pk_mul_f32 v[28:29], v[210:211], v[98:99]
	v_pk_mul_f32 v[182:183], v[210:211], v[182:183]
	v_pk_fma_f32 v[128:129], v[2:3], v[112:113], v[28:29] op_sel_hi:[1,0,1] neg_lo:[0,0,1] neg_hi:[0,0,1]
	v_pk_mul_f32 v[2:3], v[210:211], v[96:97]
	v_pk_mul_f32 v[180:181], v[210:211], v[180:181]
	v_pk_fma_f32 v[132:133], v[0:1], v[112:113], v[2:3] op_sel_hi:[1,0,1] neg_lo:[0,0,1] neg_hi:[0,0,1]
	v_pk_mul_f32 v[0:1], v[210:211], v[106:107]
	v_pk_mul_f32 v[214:215], v[132:133], v[132:133]
	v_pk_fma_f32 v[134:135], v[6:7], v[112:113], v[0:1] op_sel_hi:[1,0,1] neg_lo:[0,0,1] neg_hi:[0,0,1]
	v_pk_mul_f32 v[0:1], v[210:211], v[104:105]
	v_pk_mul_f32 v[184:185], v[210:211], v[184:185]
	v_pk_fma_f32 v[140:141], v[4:5], v[112:113], v[0:1] op_sel_hi:[1,0,1] neg_lo:[0,0,1] neg_hi:[0,0,1]
	v_pk_mul_f32 v[0:1], v[210:211], v[118:119]
	v_pk_mul_f32 v[4:5], v[210:211], v[122:123]
	v_pk_fma_f32 v[138:139], v[10:11], v[112:113], v[0:1] op_sel_hi:[1,0,1] neg_lo:[0,0,1] neg_hi:[0,0,1]
	v_pk_mul_f32 v[0:1], v[210:211], v[116:117]
	v_pk_fma_f32 v[116:117], v[14:15], v[112:113], v[4:5] op_sel_hi:[1,0,1] neg_lo:[0,0,1] neg_hi:[0,0,1]
	v_pk_mul_f32 v[4:5], v[210:211], v[120:121]
	v_pk_mul_f32 v[156:157], v[210:211], v[156:157]
	v_pk_fma_f32 v[118:119], v[12:13], v[112:113], v[4:5] op_sel_hi:[1,0,1] neg_lo:[0,0,1] neg_hi:[0,0,1]
	v_pk_mul_f32 v[4:5], v[210:211], v[126:127]
	v_pk_mul_f32 v[12:13], v[210:211], v[162:163]
	v_pk_fma_f32 v[120:121], v[50:51], v[112:113], v[4:5] op_sel_hi:[1,0,1] neg_lo:[0,0,1] neg_hi:[0,0,1]
	v_pk_mul_f32 v[4:5], v[210:211], v[124:125]
	v_pk_fma_f32 v[54:55], v[54:55], v[112:113], v[12:13] op_sel_hi:[1,0,1] neg_lo:[0,0,1] neg_hi:[0,0,1]
	v_pk_fma_f32 v[122:123], v[48:49], v[112:113], v[4:5] op_sel_hi:[1,0,1] neg_lo:[0,0,1] neg_hi:[0,0,1]
	v_pk_mul_f32 v[48:49], v[210:211], v[170:171]
	v_pk_mul_f32 v[12:13], v[210:211], v[160:161]
	v_pk_fma_f32 v[62:63], v[62:63], v[112:113], v[48:49] op_sel_hi:[1,0,1] neg_lo:[0,0,1] neg_hi:[0,0,1]
	v_pk_mul_f32 v[48:49], v[210:211], v[168:169]
	v_pk_fma_f32 v[52:53], v[52:53], v[112:113], v[12:13] op_sel_hi:[1,0,1] neg_lo:[0,0,1] neg_hi:[0,0,1]
	v_pk_mul_f32 v[12:13], v[210:211], v[166:167]
	v_pk_fma_f32 v[60:61], v[60:61], v[112:113], v[48:49] op_sel_hi:[1,0,1] neg_lo:[0,0,1] neg_hi:[0,0,1]
	v_pk_mul_f32 v[48:49], v[210:211], v[174:175]
	v_pk_fma_f32 v[58:59], v[58:59], v[112:113], v[12:13] op_sel_hi:[1,0,1] neg_lo:[0,0,1] neg_hi:[0,0,1]
	v_pk_mul_f32 v[12:13], v[210:211], v[164:165]
	v_pk_fma_f32 v[124:125], v[34:35], v[112:113], v[48:49] op_sel_hi:[1,0,1] neg_lo:[0,0,1] neg_hi:[0,0,1]
	v_pk_mul_f32 v[34:35], v[210:211], v[172:173]
	v_pk_mul_f32 v[154:155], v[210:211], v[154:155]
	v_pk_mul_f32 v[150:151], v[210:211], v[150:151]
	v_pk_mul_f32 v[148:149], v[210:211], v[148:149]
	v_pk_mul_f32 v[146:147], v[210:211], v[146:147]
	s_waitcnt lgkmcnt(0)
	v_pk_mul_f32 v[152:153], v[210:211], v[152:153]
	v_pk_mul_f32 v[144:145], v[210:211], v[144:145]
	v_lshl_add_u64 v[114:115], v[212:213], 2, s[36:37]
	v_pk_mul_f32 v[186:187], v[128:129], v[128:129]
	v_pk_fma_f32 v[142:143], v[8:9], v[112:113], v[0:1] op_sel_hi:[1,0,1] neg_lo:[0,0,1] neg_hi:[0,0,1]
	v_pk_fma_f32 v[56:57], v[56:57], v[112:113], v[12:13] op_sel_hi:[1,0,1] neg_lo:[0,0,1] neg_hi:[0,0,1]
	v_pk_fma_f32 v[126:127], v[32:33], v[112:113], v[34:35] op_sel_hi:[1,0,1] neg_lo:[0,0,1] neg_hi:[0,0,1]
	v_pk_fma_f32 v[38:39], v[38:39], v[112:113], v[178:179] op_sel_hi:[1,0,1] neg_lo:[0,0,1] neg_hi:[0,0,1]
	v_pk_fma_f32 v[36:37], v[36:37], v[112:113], v[176:177] op_sel_hi:[1,0,1] neg_lo:[0,0,1] neg_hi:[0,0,1]
	v_pk_fma_f32 v[42:43], v[42:43], v[112:113], v[182:183] op_sel_hi:[1,0,1] neg_lo:[0,0,1] neg_hi:[0,0,1]
	v_pk_fma_f32 v[40:41], v[40:41], v[112:113], v[180:181] op_sel_hi:[1,0,1] neg_lo:[0,0,1] neg_hi:[0,0,1]
	v_pk_fma_f32 v[46:47], v[46:47], v[112:113], v[184:185] op_sel_hi:[1,0,1] neg_lo:[0,0,1] neg_hi:[0,0,1]
	v_pk_fma_f32 v[44:45], v[44:45], v[112:113], v[156:157] op_sel_hi:[1,0,1] neg_lo:[0,0,1] neg_hi:[0,0,1]
	v_pk_fma_f32 v[18:19], v[18:19], v[112:113], v[154:155] op_sel_hi:[1,0,1] neg_lo:[0,0,1] neg_hi:[0,0,1]
	v_pk_fma_f32 v[16:17], v[16:17], v[112:113], v[150:151] op_sel_hi:[1,0,1] neg_lo:[0,0,1] neg_hi:[0,0,1]
	v_pk_fma_f32 v[22:23], v[22:23], v[112:113], v[148:149] op_sel_hi:[1,0,1] neg_lo:[0,0,1] neg_hi:[0,0,1]
	v_pk_fma_f32 v[20:21], v[20:21], v[112:113], v[146:147] op_sel_hi:[1,0,1] neg_lo:[0,0,1] neg_hi:[0,0,1]
	v_pk_fma_f32 v[26:27], v[26:27], v[112:113], v[152:153] op_sel_hi:[1,0,1] neg_lo:[0,0,1] neg_hi:[0,0,1]
	v_pk_fma_f32 v[24:25], v[24:25], v[112:113], v[144:145] op_sel_hi:[1,0,1] neg_lo:[0,0,1] neg_hi:[0,0,1]
	v_add_f32_e32 v112, v214, v215
	global_load_dwordx4 v[100:103], v[114:115], off
	global_load_dwordx4 v[96:99], v[114:115], off offset:32
	v_add_f32_e32 v112, v112, v186
	v_pk_mul_f32 v[230:231], v[140:141], v[140:141]
	v_add_f32_e32 v112, v112, v187
	v_add_f32_e32 v112, v112, v230
	v_pk_mul_f32 v[228:229], v[134:135], v[134:135]
	v_add_f32_e32 v112, v112, v231
	v_add_f32_e32 v112, v112, v228
	v_pk_mul_f32 v[234:235], v[142:143], v[142:143]
	v_add_f32_e32 v112, v112, v229
	global_load_dwordx4 v[104:107], v[114:115], off offset:64
	global_load_dwordx4 v[0:3], v[114:115], off offset:96
	v_add_f32_e32 v112, v112, v234
	v_pk_mul_f32 v[232:233], v[138:139], v[138:139]
	v_add_f32_e32 v112, v112, v235
	v_add_f32_e32 v112, v112, v232
	v_pk_mul_f32 v[238:239], v[118:119], v[118:119]
	v_add_f32_e32 v112, v112, v233
	v_add_f32_e32 v112, v112, v238
	v_pk_mul_f32 v[236:237], v[116:117], v[116:117]
	v_add_f32_e32 v112, v112, v239
	v_add_f32_e32 v112, v112, v236
	v_pk_mul_f32 v[242:243], v[122:123], v[122:123]
	v_add_f32_e32 v112, v112, v237
	v_add_f32_e32 v112, v112, v242
	v_pk_mul_f32 v[240:241], v[120:121], v[120:121]
	v_add_f32_e32 v112, v112, v243
	v_add_f32_e32 v112, v112, v240
	v_pk_mul_f32 v[160:161], v[52:53], v[52:53]
	v_add_f32_e32 v112, v112, v241
	v_add_f32_e32 v112, v112, v160
	v_pk_mul_f32 v[162:163], v[54:55], v[54:55]
	v_add_f32_e32 v112, v112, v161
	v_add_f32_e32 v112, v112, v162
	v_pk_mul_f32 v[164:165], v[56:57], v[56:57]
	v_add_f32_e32 v112, v112, v163
	v_add_f32_e32 v112, v112, v164
	v_pk_mul_f32 v[166:167], v[58:59], v[58:59]
	v_add_f32_e32 v112, v112, v165
	v_add_f32_e32 v112, v112, v166
	v_pk_mul_f32 v[168:169], v[60:61], v[60:61]
	v_add_f32_e32 v112, v112, v167
	v_add_f32_e32 v112, v112, v168
	v_pk_mul_f32 v[170:171], v[62:63], v[62:63]
	v_add_f32_e32 v112, v112, v169
	v_add_f32_e32 v112, v112, v170
	v_pk_mul_f32 v[172:173], v[126:127], v[126:127]
	v_add_f32_e32 v112, v112, v171
	v_add_f32_e32 v112, v112, v172
	v_pk_mul_f32 v[174:175], v[124:125], v[124:125]
	v_add_f32_e32 v112, v112, v173
	v_add_f32_e32 v112, v112, v174
	v_pk_mul_f32 v[176:177], v[36:37], v[36:37]
	v_add_f32_e32 v112, v112, v175
	v_add_f32_e32 v112, v112, v176
	v_pk_mul_f32 v[178:179], v[38:39], v[38:39]
	v_add_f32_e32 v112, v112, v177
	v_add_f32_e32 v112, v112, v178
	v_pk_mul_f32 v[180:181], v[40:41], v[40:41]
	v_add_f32_e32 v112, v112, v179
	v_add_f32_e32 v112, v112, v180
	v_pk_mul_f32 v[182:183], v[42:43], v[42:43]
	v_add_f32_e32 v112, v112, v181
	v_add_f32_e32 v112, v112, v182
	v_pk_mul_f32 v[156:157], v[44:45], v[44:45]
	v_add_f32_e32 v112, v112, v183
	v_add_f32_e32 v112, v112, v156
	v_pk_mul_f32 v[184:185], v[46:47], v[46:47]
	v_add_f32_e32 v112, v112, v157
	v_add_f32_e32 v112, v112, v184
	v_pk_mul_f32 v[150:151], v[16:17], v[16:17]
	v_add_f32_e32 v112, v112, v185
	v_add_f32_e32 v112, v112, v150
	v_pk_mul_f32 v[154:155], v[18:19], v[18:19]
	v_add_f32_e32 v112, v112, v151
	v_add_f32_e32 v112, v112, v154
	v_pk_mul_f32 v[146:147], v[20:21], v[20:21]
	v_add_f32_e32 v112, v112, v155
	v_add_f32_e32 v112, v112, v146
	v_pk_mul_f32 v[148:149], v[22:23], v[22:23]
	v_add_f32_e32 v112, v112, v147
	v_add_f32_e32 v112, v112, v148
	v_pk_mul_f32 v[144:145], v[24:25], v[24:25]
	v_add_f32_e32 v112, v112, v149
	v_add_f32_e32 v112, v112, v144
	v_pk_mul_f32 v[152:153], v[26:27], v[26:27]
	v_add_f32_e32 v112, v112, v145
	v_add_f32_e32 v112, v112, v152
	v_pk_mul_f32 v[130:131], v[108:109], v[108:109]
	v_add_f32_e32 v112, v112, v153
	v_add_f32_e32 v112, v112, v130
	v_pk_mul_f32 v[136:137], v[110:111], v[110:111]
	v_add_f32_e32 v112, v112, v131
	v_add_f32_e32 v112, v112, v136
	global_load_dwordx4 v[8:11], v[114:115], off offset:128
	global_load_dwordx4 v[4:7], v[114:115], off offset:160
	v_add_f32_e32 v112, v112, v137
	ds_bpermute_b32 v130, v227, v112
	global_load_dwordx4 v[28:31], v[114:115], off offset:192
	global_load_dwordx4 v[12:15], v[114:115], off offset:224
	global_load_dwordx4 v[48:51], v[114:115], off offset:256
	global_load_dwordx4 v[32:35], v[114:115], off offset:288
	v_lshlrev_b32_e32 v131, 1, v212
	v_readlane_b32 s1, v254, 43
	s_waitcnt lgkmcnt(0)
	v_add_f32_e32 v112, v112, v130
	v_fmamk_f32 v112, v112, 0x3c000000, v189
	v_mul_f32_e32 v130, 0x4b800000, v112
	v_cmp_gt_f32_e32 vcc, s13, v112
	global_load_dwordx4 v[144:147], v[114:115], off offset:320
	global_load_dwordx4 v[148:151], v[114:115], off offset:352
	v_cndmask_b32_e32 v112, v112, v130, vcc
	v_rsq_f32_e32 v112, v112
	v_add3_u32 v136, s1, v159, v131
	global_load_dwordx4 v[152:155], v[114:115], off offset:384
	global_load_dwordx4 v[160:163], v[114:115], off offset:416
	global_load_dwordx4 v[164:167], v[114:115], off offset:448
	s_add_u32 s8, s82, s92
	v_mul_f32_e32 v130, 0x45800000, v112
	v_cndmask_b32_e32 v112, v112, v130, vcc
	v_mul_f32_e32 v112, v209, v112
	v_pk_mul_f32 v[130:131], v[132:133], v[112:113] op_sel_hi:[1,0]
	v_pk_mul_f32 v[128:129], v[128:129], v[112:113] op_sel_hi:[1,0]
	s_waitcnt vmcnt(14)
	v_pk_mul_f32 v[100:101], v[100:101], v[130:131]
	v_pk_mul_f32 v[102:103], v[102:103], v[128:129]
	v_cvt_pk_bf16_f32 v100, v100, v101
	v_cvt_pk_bf16_f32 v101, v102, v103
	v_pk_mul_f32 v[102:103], v[140:141], v[112:113] op_sel_hi:[1,0]
	s_addc_u32 s9, s83, 0
	s_waitcnt vmcnt(13)
	v_pk_mul_f32 v[96:97], v[96:97], v[102:103]
	v_pk_mul_f32 v[102:103], v[134:135], v[112:113] op_sel_hi:[1,0]
	v_cvt_pk_bf16_f32 v96, v96, v97
	v_pk_mul_f32 v[98:99], v[98:99], v[102:103]
	v_pk_mul_f32 v[102:103], v[118:119], v[112:113] op_sel_hi:[1,0]
	v_cvt_pk_bf16_f32 v97, v98, v99
	ds_write2_b64 v136, v[100:101], v[96:97] offset1:2
	v_pk_mul_f32 v[96:97], v[142:143], v[112:113] op_sel_hi:[1,0]
	s_waitcnt vmcnt(11)
	v_pk_mul_f32 v[0:1], v[0:1], v[102:103]
	v_pk_mul_f32 v[96:97], v[104:105], v[96:97]
	v_pk_mul_f32 v[102:103], v[116:117], v[112:113] op_sel_hi:[1,0]
	v_cvt_pk_bf16_f32 v100, v96, v97
	v_pk_mul_f32 v[96:97], v[138:139], v[112:113] op_sel_hi:[1,0]
	v_pk_mul_f32 v[2:3], v[2:3], v[102:103]
	v_pk_mul_f32 v[96:97], v[106:107], v[96:97]
	v_cvt_pk_bf16_f32 v0, v0, v1
	v_cvt_pk_bf16_f32 v101, v96, v97
	global_load_dwordx4 v[96:99], v[114:115], off offset:480
	v_cvt_pk_bf16_f32 v1, v2, v3
	ds_write2_b64 v136, v[100:101], v[0:1] offset0:4 offset1:6
	v_pk_mul_f32 v[0:1], v[122:123], v[112:113] op_sel_hi:[1,0]
	v_pk_mul_f32 v[2:3], v[120:121], v[112:113] op_sel_hi:[1,0]
	s_waitcnt vmcnt(11)
	v_pk_mul_f32 v[0:1], v[8:9], v[0:1]
	v_pk_mul_f32 v[2:3], v[10:11], v[2:3]
	v_cvt_pk_bf16_f32 v0, v0, v1
	v_cvt_pk_bf16_f32 v1, v2, v3
	v_pk_mul_f32 v[2:3], v[52:53], v[112:113] op_sel_hi:[1,0]
	v_lshl_add_u64 v[8:9], s[8:9], 0, v[194:195]
	s_waitcnt vmcnt(10)
	v_pk_mul_f32 v[2:3], v[4:5], v[2:3]
	v_pk_mul_f32 v[4:5], v[54:55], v[112:113] op_sel_hi:[1,0]
	v_cvt_pk_bf16_f32 v2, v2, v3
	v_pk_mul_f32 v[4:5], v[6:7], v[4:5]
	v_mad_u64_u32 v[10:11], s[8:9], v113, s14, v[8:9]
	v_cvt_pk_bf16_f32 v3, v4, v5
	ds_write2_b64 v136, v[0:1], v[2:3] offset0:8 offset1:10
	v_pk_mul_f32 v[0:1], v[56:57], v[112:113] op_sel_hi:[1,0]
	v_pk_mul_f32 v[2:3], v[58:59], v[112:113] op_sel_hi:[1,0]
	s_waitcnt vmcnt(9)
	v_pk_mul_f32 v[0:1], v[28:29], v[0:1]
	v_pk_mul_f32 v[2:3], v[30:31], v[2:3]
	v_cvt_pk_bf16_f32 v0, v0, v1
	v_cvt_pk_bf16_f32 v1, v2, v3
	v_pk_mul_f32 v[2:3], v[60:61], v[112:113] op_sel_hi:[1,0]
	v_pk_mul_f32 v[4:5], v[62:63], v[112:113] op_sel_hi:[1,0]
	s_waitcnt vmcnt(8)
	v_pk_mul_f32 v[2:3], v[2:3], v[12:13]
	v_pk_mul_f32 v[4:5], v[4:5], v[14:15]
	v_cvt_pk_bf16_f32 v2, v2, v3
	v_cvt_pk_bf16_f32 v3, v4, v5
	ds_write2_b64 v136, v[0:1], v[2:3] offset0:12 offset1:14
	v_pk_mul_f32 v[0:1], v[126:127], v[112:113] op_sel_hi:[1,0]
	v_pk_mul_f32 v[2:3], v[124:125], v[112:113] op_sel_hi:[1,0]
	s_waitcnt vmcnt(7)
	v_pk_mul_f32 v[0:1], v[0:1], v[48:49]
	v_pk_mul_f32 v[2:3], v[2:3], v[50:51]
	v_cvt_pk_bf16_f32 v0, v0, v1
	v_cvt_pk_bf16_f32 v1, v2, v3
	v_pk_mul_f32 v[2:3], v[36:37], v[112:113] op_sel_hi:[1,0]
	v_pk_mul_f32 v[4:5], v[38:39], v[112:113] op_sel_hi:[1,0]
	s_waitcnt vmcnt(6)
	v_pk_mul_f32 v[2:3], v[2:3], v[32:33]
	v_pk_mul_f32 v[4:5], v[4:5], v[34:35]
	v_cvt_pk_bf16_f32 v2, v2, v3
	v_cvt_pk_bf16_f32 v3, v4, v5
	ds_write2_b64 v136, v[0:1], v[2:3] offset0:16 offset1:18
	v_pk_mul_f32 v[0:1], v[40:41], v[112:113] op_sel_hi:[1,0]
	v_pk_mul_f32 v[2:3], v[42:43], v[112:113] op_sel_hi:[1,0]
	s_waitcnt vmcnt(5)
	v_pk_mul_f32 v[0:1], v[0:1], v[144:145]
	v_pk_mul_f32 v[2:3], v[2:3], v[146:147]
	v_cvt_pk_bf16_f32 v0, v0, v1
	v_cvt_pk_bf16_f32 v1, v2, v3
	v_pk_mul_f32 v[2:3], v[44:45], v[112:113] op_sel_hi:[1,0]
	v_pk_mul_f32 v[4:5], v[46:47], v[112:113] op_sel_hi:[1,0]
	s_waitcnt vmcnt(4)
	v_pk_mul_f32 v[2:3], v[2:3], v[148:149]
	v_pk_mul_f32 v[4:5], v[4:5], v[150:151]
	v_cvt_pk_bf16_f32 v2, v2, v3
	v_cvt_pk_bf16_f32 v3, v4, v5
	ds_write2_b64 v136, v[0:1], v[2:3] offset0:20 offset1:22
	v_pk_mul_f32 v[0:1], v[16:17], v[112:113] op_sel_hi:[1,0]
	v_pk_mul_f32 v[2:3], v[18:19], v[112:113] op_sel_hi:[1,0]
	s_waitcnt vmcnt(3)
	v_pk_mul_f32 v[0:1], v[0:1], v[152:153]
	v_pk_mul_f32 v[2:3], v[2:3], v[154:155]
	v_cvt_pk_bf16_f32 v0, v0, v1
	v_cvt_pk_bf16_f32 v1, v2, v3
	v_pk_mul_f32 v[2:3], v[20:21], v[112:113] op_sel_hi:[1,0]
	v_pk_mul_f32 v[4:5], v[22:23], v[112:113] op_sel_hi:[1,0]
	s_waitcnt vmcnt(2)
	v_pk_mul_f32 v[2:3], v[2:3], v[160:161]
	v_pk_mul_f32 v[4:5], v[4:5], v[162:163]
	v_cvt_pk_bf16_f32 v2, v2, v3
	v_cvt_pk_bf16_f32 v3, v4, v5
	ds_write2_b64 v136, v[0:1], v[2:3] offset0:24 offset1:26
	v_pk_mul_f32 v[0:1], v[24:25], v[112:113] op_sel_hi:[1,0]
	v_pk_mul_f32 v[2:3], v[26:27], v[112:113] op_sel_hi:[1,0]
	s_waitcnt vmcnt(1)
	v_pk_mul_f32 v[0:1], v[0:1], v[164:165]
	v_pk_mul_f32 v[2:3], v[2:3], v[166:167]
	v_cvt_pk_bf16_f32 v0, v0, v1
	v_cvt_pk_bf16_f32 v1, v2, v3
	v_pk_mul_f32 v[2:3], v[108:109], v[112:113] op_sel_hi:[1,0]
	v_pk_mul_f32 v[4:5], v[110:111], v[112:113] op_sel_hi:[1,0]
	s_waitcnt vmcnt(0)
	v_pk_mul_f32 v[2:3], v[2:3], v[96:97]
	v_pk_mul_f32 v[4:5], v[4:5], v[98:99]
	v_cvt_pk_bf16_f32 v2, v2, v3
	v_cvt_pk_bf16_f32 v3, v4, v5
	ds_write2_b64 v136, v[0:1], v[2:3] offset0:28 offset1:30
	v_mul_u32_u24_e32 v0, 0x110, v158
	v_lshlrev_b32_e32 v13, 16, v92
	v_and_b32_e32 v18, 0xffff0000, v92
	v_add3_u32 v12, s1, v194, v0
	v_mul_f32_e32 v0, 0xbfb8aa3b, v13
	v_mul_f32_e32 v1, 0xbfb8aa3b, v18
	v_exp_f32_e32 v0, v0
	v_exp_f32_e32 v1, v1
	s_waitcnt lgkmcnt(0)
	ds_read_b128 v[4:7], v12
	v_and_b32_e32 v23, 0xffff0000, v93
	v_pk_add_f32 v[14:15], v[0:1], 1.0 op_sel_hi:[1,0]
	ds_read_b128 v[0:3], v12 offset:1088
	v_rcp_f32_e32 v20, v15
	s_waitcnt lgkmcnt(1)
	v_lshlrev_b32_e32 v16, 16, v4
	v_and_b32_e32 v17, 0xffff0000, v4
	v_add_u32_e32 v11, s0, v11
	v_rcp_f32_e32 v22, v14
	v_mul_f32_e32 v15, v18, v20
	v_lshlrev_b32_e32 v21, 16, v93
	v_mul_f32_e32 v18, 0xbfb8aa3b, v21
	v_mul_f32_e32 v19, 0xbfb8aa3b, v23
	v_exp_f32_e32 v18, v18
	v_exp_f32_e32 v19, v19
	v_mul_f32_e32 v14, v13, v22
	v_pk_mul_f32 v[14:15], v[14:15], v[16:17]
	v_pk_add_f32 v[16:17], v[18:19], 1.0 op_sel_hi:[1,0]
	v_cvt_pk_bf16_f32 v4, v14, v15
	v_rcp_f32_e32 v18, v17
	v_lshlrev_b32_e32 v14, 16, v5
	v_and_b32_e32 v15, 0xffff0000, v5
	v_rcp_f32_e32 v20, v16
	v_mul_f32_e32 v17, v23, v18
	v_and_b32_e32 v23, 0xffff0000, v94
	v_lshlrev_b32_e32 v13, 16, v94
	v_mul_f32_e32 v18, 0xbfb8aa3b, v13
	v_mul_f32_e32 v19, 0xbfb8aa3b, v23
	v_exp_f32_e32 v18, v18
	v_exp_f32_e32 v19, v19
	v_mul_f32_e32 v16, v21, v20
	v_pk_mul_f32 v[14:15], v[16:17], v[14:15]
	v_pk_add_f32 v[16:17], v[18:19], 1.0 op_sel_hi:[1,0]
	v_cvt_pk_bf16_f32 v5, v14, v15
	v_rcp_f32_e32 v19, v17
	v_lshlrev_b32_e32 v14, 16, v6
	v_and_b32_e32 v15, 0xffff0000, v6
	v_lshlrev_b32_e32 v22, 16, v95
	v_rcp_f32_e32 v21, v16
	v_mul_f32_e32 v17, v23, v19
	v_and_b32_e32 v23, 0xffff0000, v95
	v_mul_f32_e32 v18, 0xbfb8aa3b, v22
	v_mul_f32_e32 v19, 0xbfb8aa3b, v23
	v_exp_f32_e32 v18, v18
	v_exp_f32_e32 v19, v19
	v_mul_f32_e32 v16, v13, v21
	v_pk_mul_f32 v[14:15], v[16:17], v[14:15]
	v_pk_add_f32 v[16:17], v[18:19], 1.0 op_sel_hi:[1,0]
	v_cvt_pk_bf16_f32 v6, v14, v15
	v_rcp_f32_e32 v18, v17
	v_lshlrev_b32_e32 v14, 16, v7
	v_and_b32_e32 v15, 0xffff0000, v7
	v_rcp_f32_e32 v20, v16
	v_mul_f32_e32 v17, v23, v18
	v_and_b32_e32 v23, 0xffff0000, v85
	v_mul_f32_e32 v16, v22, v20
	v_pk_mul_f32 v[14:15], v[16:17], v[14:15]
	v_lshlrev_b32_e32 v13, 16, v88
	v_cvt_pk_bf16_f32 v7, v14, v15
	v_and_b32_e32 v14, 0xffff0000, v88
	global_store_dwordx4 v[10:11], v[4:7], off offset:2048
	s_waitcnt lgkmcnt(0)
	v_lshlrev_b32_e32 v10, 16, v0
	v_and_b32_e32 v11, 0xffff0000, v0
	v_mul_f32_e32 v4, 0xbfb8aa3b, v13
	v_mul_f32_e32 v5, 0xbfb8aa3b, v14
	v_exp_f32_e32 v4, v4
	v_exp_f32_e32 v5, v5
	v_and_b32_e32 v19, 0xffff0000, v89
	v_or_b32_e32 v6, 4, v113
	v_mad_u64_u32 v[6:7], s[8:9], v6, s14, v[8:9]
	v_pk_add_f32 v[4:5], v[4:5], 1.0 op_sel_hi:[1,0]
	v_add_u32_e32 v7, s0, v7
	v_rcp_f32_e32 v16, v5
	s_nop 0
	v_rcp_f32_e32 v18, v4
	v_mul_f32_e32 v5, v14, v16
	v_lshlrev_b32_e32 v17, 16, v89
	v_mul_f32_e32 v14, 0xbfb8aa3b, v17
	v_mul_f32_e32 v15, 0xbfb8aa3b, v19
	v_exp_f32_e32 v14, v14
	v_exp_f32_e32 v15, v15
	v_mul_f32_e32 v4, v13, v18
	v_pk_mul_f32 v[4:5], v[4:5], v[10:11]
	v_pk_add_f32 v[10:11], v[14:15], 1.0 op_sel_hi:[1,0]
	v_cvt_pk_bf16_f32 v0, v4, v5
	v_rcp_f32_e32 v14, v11
	v_lshlrev_b32_e32 v4, 16, v1
	v_and_b32_e32 v5, 0xffff0000, v1
	v_rcp_f32_e32 v16, v10
	v_mul_f32_e32 v11, v19, v14
	v_and_b32_e32 v19, 0xffff0000, v90
	v_lshlrev_b32_e32 v13, 16, v90
	v_mul_f32_e32 v14, 0xbfb8aa3b, v13
	v_mul_f32_e32 v15, 0xbfb8aa3b, v19
	v_exp_f32_e32 v14, v14
	v_exp_f32_e32 v15, v15
	v_mul_f32_e32 v10, v17, v16
	v_pk_mul_f32 v[4:5], v[10:11], v[4:5]
	v_pk_add_f32 v[10:11], v[14:15], 1.0 op_sel_hi:[1,0]
	v_cvt_pk_bf16_f32 v1, v4, v5
	v_rcp_f32_e32 v15, v11
	v_lshlrev_b32_e32 v4, 16, v2
	v_and_b32_e32 v5, 0xffff0000, v2
	v_lshlrev_b32_e32 v18, 16, v91
	v_rcp_f32_e32 v17, v10
	v_mul_f32_e32 v11, v19, v15
	v_and_b32_e32 v19, 0xffff0000, v91
	v_mul_f32_e32 v14, 0xbfb8aa3b, v18
	v_mul_f32_e32 v15, 0xbfb8aa3b, v19
	v_exp_f32_e32 v14, v14
	v_exp_f32_e32 v15, v15
	v_mul_f32_e32 v10, v13, v17
	v_pk_mul_f32 v[4:5], v[10:11], v[4:5]
	v_pk_add_f32 v[10:11], v[14:15], 1.0 op_sel_hi:[1,0]
	v_cvt_pk_bf16_f32 v2, v4, v5
	v_rcp_f32_e32 v14, v11
	v_lshlrev_b32_e32 v4, 16, v3
	v_and_b32_e32 v5, 0xffff0000, v3
	v_rcp_f32_e32 v16, v10
	v_mul_f32_e32 v11, v19, v14
	v_mul_f32_e32 v10, v18, v16
	v_pk_mul_f32 v[4:5], v[10:11], v[4:5]
	v_lshlrev_b32_e32 v13, 16, v84
	v_cvt_pk_bf16_f32 v3, v4, v5
	v_and_b32_e32 v18, 0xffff0000, v84
	global_store_dwordx4 v[6:7], v[0:3], off offset:2048
	ds_read_b128 v[4:7], v12 offset:2176
	s_nop 0
	v_mul_f32_e32 v0, 0xbfb8aa3b, v13
	v_mul_f32_e32 v1, 0xbfb8aa3b, v18
	v_exp_f32_e32 v0, v0
	v_exp_f32_e32 v1, v1
	v_or_b32_e32 v2, 8, v113
	v_mad_u64_u32 v[10:11], s[8:9], v2, s14, v[8:9]
	v_pk_add_f32 v[14:15], v[0:1], 1.0 op_sel_hi:[1,0]
	ds_read_b128 v[0:3], v12 offset:3264
	v_rcp_f32_e32 v20, v15
	s_waitcnt lgkmcnt(1)
	v_lshlrev_b32_e32 v16, 16, v4
	v_and_b32_e32 v17, 0xffff0000, v4
	v_add_u32_e32 v11, s0, v11
	v_rcp_f32_e32 v22, v14
	v_mul_f32_e32 v15, v18, v20
	v_lshlrev_b32_e32 v21, 16, v85
	v_mul_f32_e32 v18, 0xbfb8aa3b, v21
	v_mul_f32_e32 v19, 0xbfb8aa3b, v23
	v_exp_f32_e32 v18, v18
	v_exp_f32_e32 v19, v19
	v_mul_f32_e32 v14, v13, v22
	v_pk_mul_f32 v[14:15], v[14:15], v[16:17]
	v_pk_add_f32 v[16:17], v[18:19], 1.0 op_sel_hi:[1,0]
	v_cvt_pk_bf16_f32 v4, v14, v15
	v_rcp_f32_e32 v18, v17
	v_lshlrev_b32_e32 v14, 16, v5
	v_and_b32_e32 v15, 0xffff0000, v5
	v_rcp_f32_e32 v20, v16
	v_mul_f32_e32 v17, v23, v18
	v_and_b32_e32 v23, 0xffff0000, v86
	v_lshlrev_b32_e32 v13, 16, v86
	v_mul_f32_e32 v18, 0xbfb8aa3b, v13
	v_mul_f32_e32 v19, 0xbfb8aa3b, v23
	v_exp_f32_e32 v18, v18
	v_exp_f32_e32 v19, v19
	v_mul_f32_e32 v16, v21, v20
	v_pk_mul_f32 v[14:15], v[16:17], v[14:15]
	v_pk_add_f32 v[16:17], v[18:19], 1.0 op_sel_hi:[1,0]
	v_cvt_pk_bf16_f32 v5, v14, v15
	v_rcp_f32_e32 v19, v17
	v_lshlrev_b32_e32 v14, 16, v6
	v_and_b32_e32 v15, 0xffff0000, v6
	v_lshlrev_b32_e32 v22, 16, v87
	v_rcp_f32_e32 v21, v16
	v_mul_f32_e32 v17, v23, v19
	v_and_b32_e32 v23, 0xffff0000, v87
	v_mul_f32_e32 v18, 0xbfb8aa3b, v22
	v_mul_f32_e32 v19, 0xbfb8aa3b, v23
	v_exp_f32_e32 v18, v18
	v_exp_f32_e32 v19, v19
	v_mul_f32_e32 v16, v13, v21
	v_pk_mul_f32 v[14:15], v[16:17], v[14:15]
	v_pk_add_f32 v[16:17], v[18:19], 1.0 op_sel_hi:[1,0]
	v_cvt_pk_bf16_f32 v6, v14, v15
	v_rcp_f32_e32 v18, v17
	v_lshlrev_b32_e32 v14, 16, v7
	v_and_b32_e32 v15, 0xffff0000, v7
	v_rcp_f32_e32 v20, v16
	v_mul_f32_e32 v17, v23, v18
	v_and_b32_e32 v23, 0xffff0000, v77
	v_mul_f32_e32 v16, v22, v20
	v_pk_mul_f32 v[14:15], v[16:17], v[14:15]
	v_lshlrev_b32_e32 v13, 16, v80
	v_cvt_pk_bf16_f32 v7, v14, v15
	v_and_b32_e32 v14, 0xffff0000, v80
	global_store_dwordx4 v[10:11], v[4:7], off offset:2048
	s_waitcnt lgkmcnt(0)
	v_lshlrev_b32_e32 v10, 16, v0
	v_and_b32_e32 v11, 0xffff0000, v0
	v_mul_f32_e32 v4, 0xbfb8aa3b, v13
	v_mul_f32_e32 v5, 0xbfb8aa3b, v14
	v_exp_f32_e32 v4, v4
	v_exp_f32_e32 v5, v5
	v_and_b32_e32 v19, 0xffff0000, v81
	v_or_b32_e32 v6, 12, v113
	v_mad_u64_u32 v[6:7], s[8:9], v6, s14, v[8:9]
	v_pk_add_f32 v[4:5], v[4:5], 1.0 op_sel_hi:[1,0]
	v_add_u32_e32 v7, s0, v7
	v_rcp_f32_e32 v16, v5
	s_nop 0
	v_rcp_f32_e32 v18, v4
	v_mul_f32_e32 v5, v14, v16
	v_lshlrev_b32_e32 v17, 16, v81
	v_mul_f32_e32 v14, 0xbfb8aa3b, v17
	v_mul_f32_e32 v15, 0xbfb8aa3b, v19
	v_exp_f32_e32 v14, v14
	v_exp_f32_e32 v15, v15
	v_mul_f32_e32 v4, v13, v18
	v_pk_mul_f32 v[4:5], v[4:5], v[10:11]
	v_pk_add_f32 v[10:11], v[14:15], 1.0 op_sel_hi:[1,0]
	v_cvt_pk_bf16_f32 v0, v4, v5
	v_rcp_f32_e32 v14, v11
	v_lshlrev_b32_e32 v4, 16, v1
	v_and_b32_e32 v5, 0xffff0000, v1
	v_rcp_f32_e32 v16, v10
	v_mul_f32_e32 v11, v19, v14
	v_and_b32_e32 v19, 0xffff0000, v82
	v_lshlrev_b32_e32 v13, 16, v82
	v_mul_f32_e32 v14, 0xbfb8aa3b, v13
	v_mul_f32_e32 v15, 0xbfb8aa3b, v19
	v_exp_f32_e32 v14, v14
	v_exp_f32_e32 v15, v15
	v_mul_f32_e32 v10, v17, v16
	v_pk_mul_f32 v[4:5], v[10:11], v[4:5]
	v_pk_add_f32 v[10:11], v[14:15], 1.0 op_sel_hi:[1,0]
	v_cvt_pk_bf16_f32 v1, v4, v5
	v_rcp_f32_e32 v15, v11
	v_lshlrev_b32_e32 v4, 16, v2
	v_and_b32_e32 v5, 0xffff0000, v2
	v_lshlrev_b32_e32 v18, 16, v83
	v_rcp_f32_e32 v17, v10
	v_mul_f32_e32 v11, v19, v15
	v_and_b32_e32 v19, 0xffff0000, v83
	v_mul_f32_e32 v14, 0xbfb8aa3b, v18
	v_mul_f32_e32 v15, 0xbfb8aa3b, v19
	v_exp_f32_e32 v14, v14
	v_exp_f32_e32 v15, v15
	v_mul_f32_e32 v10, v13, v17
	v_pk_mul_f32 v[4:5], v[10:11], v[4:5]
	v_pk_add_f32 v[10:11], v[14:15], 1.0 op_sel_hi:[1,0]
	v_cvt_pk_bf16_f32 v2, v4, v5
	v_rcp_f32_e32 v14, v11
	v_lshlrev_b32_e32 v4, 16, v3
	v_and_b32_e32 v5, 0xffff0000, v3
	v_rcp_f32_e32 v16, v10
	v_mul_f32_e32 v11, v19, v14
	v_mul_f32_e32 v10, v18, v16
	v_pk_mul_f32 v[4:5], v[10:11], v[4:5]
	v_lshlrev_b32_e32 v13, 16, v76
	v_cvt_pk_bf16_f32 v3, v4, v5
	v_and_b32_e32 v18, 0xffff0000, v76
	global_store_dwordx4 v[6:7], v[0:3], off offset:2048
	ds_read_b128 v[4:7], v12 offset:4352
	s_nop 0
	v_mul_f32_e32 v0, 0xbfb8aa3b, v13
	v_mul_f32_e32 v1, 0xbfb8aa3b, v18
	v_exp_f32_e32 v0, v0
	v_exp_f32_e32 v1, v1
	v_or_b32_e32 v2, 16, v113
	v_mad_u64_u32 v[10:11], s[8:9], v2, s14, v[8:9]
	v_pk_add_f32 v[14:15], v[0:1], 1.0 op_sel_hi:[1,0]
	ds_read_b128 v[0:3], v12 offset:5440
	v_rcp_f32_e32 v20, v15
	s_waitcnt lgkmcnt(1)
	v_lshlrev_b32_e32 v16, 16, v4
	v_and_b32_e32 v17, 0xffff0000, v4
	v_add_u32_e32 v11, s0, v11
	v_rcp_f32_e32 v22, v14
	v_mul_f32_e32 v15, v18, v20
	v_lshlrev_b32_e32 v21, 16, v77
	v_mul_f32_e32 v18, 0xbfb8aa3b, v21
	v_mul_f32_e32 v19, 0xbfb8aa3b, v23
	v_exp_f32_e32 v18, v18
	v_exp_f32_e32 v19, v19
	v_mul_f32_e32 v14, v13, v22
	v_pk_mul_f32 v[14:15], v[14:15], v[16:17]
	v_pk_add_f32 v[16:17], v[18:19], 1.0 op_sel_hi:[1,0]
	v_cvt_pk_bf16_f32 v4, v14, v15
	v_rcp_f32_e32 v18, v17
	v_lshlrev_b32_e32 v14, 16, v5
	v_and_b32_e32 v15, 0xffff0000, v5
	v_rcp_f32_e32 v20, v16
	v_mul_f32_e32 v17, v23, v18
	v_and_b32_e32 v23, 0xffff0000, v78
	v_lshlrev_b32_e32 v13, 16, v78
	v_mul_f32_e32 v18, 0xbfb8aa3b, v13
	v_mul_f32_e32 v19, 0xbfb8aa3b, v23
	v_exp_f32_e32 v18, v18
	v_exp_f32_e32 v19, v19
	v_mul_f32_e32 v16, v21, v20
	v_pk_mul_f32 v[14:15], v[16:17], v[14:15]
	v_pk_add_f32 v[16:17], v[18:19], 1.0 op_sel_hi:[1,0]
	v_cvt_pk_bf16_f32 v5, v14, v15
	v_rcp_f32_e32 v19, v17
	v_lshlrev_b32_e32 v14, 16, v6
	v_and_b32_e32 v15, 0xffff0000, v6
	v_lshlrev_b32_e32 v22, 16, v79
	v_rcp_f32_e32 v21, v16
	v_mul_f32_e32 v17, v23, v19
	v_and_b32_e32 v23, 0xffff0000, v79
	v_mul_f32_e32 v18, 0xbfb8aa3b, v22
	v_mul_f32_e32 v19, 0xbfb8aa3b, v23
	v_exp_f32_e32 v18, v18
	v_exp_f32_e32 v19, v19
	v_mul_f32_e32 v16, v13, v21
	v_pk_mul_f32 v[14:15], v[16:17], v[14:15]
	v_pk_add_f32 v[16:17], v[18:19], 1.0 op_sel_hi:[1,0]
	v_cvt_pk_bf16_f32 v6, v14, v15
	v_rcp_f32_e32 v18, v17
	v_lshlrev_b32_e32 v14, 16, v7
	v_and_b32_e32 v15, 0xffff0000, v7
	v_rcp_f32_e32 v20, v16
	v_mul_f32_e32 v17, v23, v18
	v_mul_f32_e32 v16, v22, v20
	v_pk_mul_f32 v[14:15], v[16:17], v[14:15]
	v_lshlrev_b32_e32 v13, 16, v72
	v_cvt_pk_bf16_f32 v7, v14, v15
	v_and_b32_e32 v14, 0xffff0000, v72
	global_store_dwordx4 v[10:11], v[4:7], off offset:2048
	s_waitcnt lgkmcnt(0)
	v_lshlrev_b32_e32 v10, 16, v0
	v_and_b32_e32 v11, 0xffff0000, v0
	v_mul_f32_e32 v4, 0xbfb8aa3b, v13
	v_mul_f32_e32 v5, 0xbfb8aa3b, v14
	v_exp_f32_e32 v4, v4
	v_exp_f32_e32 v5, v5
	v_and_b32_e32 v19, 0xffff0000, v73
	v_or_b32_e32 v6, 20, v113
	v_mad_u64_u32 v[6:7], s[8:9], v6, s14, v[8:9]
	v_pk_add_f32 v[4:5], v[4:5], 1.0 op_sel_hi:[1,0]
	v_add_u32_e32 v7, s0, v7
	v_rcp_f32_e32 v16, v5
	v_and_b32_e32 v22, 0xffff0000, v69
	v_rcp_f32_e32 v18, v4
	v_mul_f32_e32 v5, v14, v16
	v_lshlrev_b32_e32 v17, 16, v73
	v_mul_f32_e32 v14, 0xbfb8aa3b, v17
	v_mul_f32_e32 v15, 0xbfb8aa3b, v19
	v_exp_f32_e32 v14, v14
	v_exp_f32_e32 v15, v15
	v_mul_f32_e32 v4, v13, v18
	v_pk_mul_f32 v[4:5], v[4:5], v[10:11]
	v_pk_add_f32 v[10:11], v[14:15], 1.0 op_sel_hi:[1,0]
	v_cvt_pk_bf16_f32 v0, v4, v5
	v_rcp_f32_e32 v14, v11
	v_lshlrev_b32_e32 v4, 16, v1
	v_and_b32_e32 v5, 0xffff0000, v1
	v_rcp_f32_e32 v16, v10
	v_mul_f32_e32 v11, v19, v14
	v_and_b32_e32 v19, 0xffff0000, v74
	v_lshlrev_b32_e32 v13, 16, v74
	v_mul_f32_e32 v14, 0xbfb8aa3b, v13
	v_mul_f32_e32 v15, 0xbfb8aa3b, v19
	v_exp_f32_e32 v14, v14
	v_exp_f32_e32 v15, v15
	v_mul_f32_e32 v10, v17, v16
	v_pk_mul_f32 v[4:5], v[10:11], v[4:5]
	v_pk_add_f32 v[10:11], v[14:15], 1.0 op_sel_hi:[1,0]
	v_cvt_pk_bf16_f32 v1, v4, v5
	v_rcp_f32_e32 v15, v11
	v_lshlrev_b32_e32 v4, 16, v2
	v_and_b32_e32 v5, 0xffff0000, v2
	v_lshlrev_b32_e32 v18, 16, v75
	v_rcp_f32_e32 v17, v10
	v_mul_f32_e32 v11, v19, v15
	v_and_b32_e32 v19, 0xffff0000, v75
	v_mul_f32_e32 v14, 0xbfb8aa3b, v18
	v_mul_f32_e32 v15, 0xbfb8aa3b, v19
	v_exp_f32_e32 v14, v14
	v_exp_f32_e32 v15, v15
	v_mul_f32_e32 v10, v13, v17
	v_pk_mul_f32 v[4:5], v[10:11], v[4:5]
	v_pk_add_f32 v[10:11], v[14:15], 1.0 op_sel_hi:[1,0]
	v_cvt_pk_bf16_f32 v2, v4, v5
	v_rcp_f32_e32 v14, v11
	v_lshlrev_b32_e32 v4, 16, v3
	v_and_b32_e32 v5, 0xffff0000, v3
	v_rcp_f32_e32 v16, v10
	v_mul_f32_e32 v11, v19, v14
	v_mul_f32_e32 v10, v18, v16
	v_pk_mul_f32 v[4:5], v[10:11], v[4:5]
	v_lshlrev_b32_e32 v18, 16, v68
	v_cvt_pk_bf16_f32 v3, v4, v5
	v_and_b32_e32 v16, 0xffff0000, v68
	global_store_dwordx4 v[6:7], v[0:3], off offset:2048
	ds_read_b128 v[4:7], v12 offset:6528
	s_nop 0
	v_mul_f32_e32 v0, 0xbfb8aa3b, v18
	v_mul_f32_e32 v1, 0xbfb8aa3b, v16
	v_exp_f32_e32 v0, v0
	v_exp_f32_e32 v1, v1
	v_or_b32_e32 v2, 24, v113
	v_mad_u64_u32 v[10:11], s[8:9], v2, s14, v[8:9]
	v_pk_add_f32 v[14:15], v[0:1], 1.0 op_sel_hi:[1,0]
	ds_read_b128 v[0:3], v12 offset:7616
	v_rcp_f32_e32 v19, v15
	s_waitcnt lgkmcnt(1)
	v_lshlrev_b32_e32 v12, 16, v4
	v_and_b32_e32 v13, 0xffff0000, v4
	v_add_u32_e32 v11, s0, v11
	v_rcp_f32_e32 v21, v14
	v_mul_f32_e32 v15, v16, v19
	v_lshlrev_b32_e32 v20, 16, v69
	v_mul_f32_e32 v16, 0xbfb8aa3b, v20
	v_mul_f32_e32 v17, 0xbfb8aa3b, v22
	v_exp_f32_e32 v16, v16
	v_exp_f32_e32 v17, v17
	v_mul_f32_e32 v14, v18, v21
	v_pk_mul_f32 v[12:13], v[14:15], v[12:13]
	v_pk_add_f32 v[14:15], v[16:17], 1.0 op_sel_hi:[1,0]
	v_cvt_pk_bf16_f32 v4, v12, v13
	v_rcp_f32_e32 v17, v15
	v_lshlrev_b32_e32 v12, 16, v5
	v_and_b32_e32 v13, 0xffff0000, v5
	v_lshlrev_b32_e32 v21, 16, v70
	v_rcp_f32_e32 v19, v14
	v_mul_f32_e32 v15, v22, v17
	v_and_b32_e32 v22, 0xffff0000, v70
	v_mul_f32_e32 v16, 0xbfb8aa3b, v21
	v_mul_f32_e32 v17, 0xbfb8aa3b, v22
	v_exp_f32_e32 v16, v16
	v_exp_f32_e32 v17, v17
	v_mul_f32_e32 v14, v20, v19
	v_pk_mul_f32 v[12:13], v[14:15], v[12:13]
	v_pk_add_f32 v[14:15], v[16:17], 1.0 op_sel_hi:[1,0]
	v_cvt_pk_bf16_f32 v5, v12, v13
	v_rcp_f32_e32 v17, v15
	v_lshlrev_b32_e32 v12, 16, v6
	v_and_b32_e32 v13, 0xffff0000, v6
	v_lshlrev_b32_e32 v20, 16, v71
	v_rcp_f32_e32 v19, v14
	v_mul_f32_e32 v15, v22, v17
	v_and_b32_e32 v22, 0xffff0000, v71
	v_mul_f32_e32 v16, 0xbfb8aa3b, v20
	v_mul_f32_e32 v17, 0xbfb8aa3b, v22
	v_exp_f32_e32 v16, v16
	v_exp_f32_e32 v17, v17
	v_mul_f32_e32 v14, v21, v19
	v_pk_mul_f32 v[12:13], v[14:15], v[12:13]
	v_pk_add_f32 v[14:15], v[16:17], 1.0 op_sel_hi:[1,0]
	v_cvt_pk_bf16_f32 v6, v12, v13
	v_rcp_f32_e32 v17, v15
	v_lshlrev_b32_e32 v12, 16, v7
	v_and_b32_e32 v13, 0xffff0000, v7
	v_rcp_f32_e32 v19, v14
	v_mul_f32_e32 v15, v22, v17
	v_mul_f32_e32 v14, v20, v19
	v_pk_mul_f32 v[12:13], v[14:15], v[12:13]
	v_and_b32_e32 v16, 0xffff0000, v65
	v_cvt_pk_bf16_f32 v7, v12, v13
	global_store_dwordx4 v[10:11], v[4:7], off offset:2048
	v_lshlrev_b32_e32 v12, 16, v64
	v_and_b32_e32 v10, 0xffff0000, v64
	v_mul_f32_e32 v4, 0xbfb8aa3b, v12
	v_mul_f32_e32 v5, 0xbfb8aa3b, v10
	v_exp_f32_e32 v4, v4
	v_exp_f32_e32 v5, v5
	v_or_b32_e32 v6, 28, v113
	v_mad_u64_u32 v[6:7], s[8:9], v6, s14, v[8:9]
	v_pk_add_f32 v[4:5], v[4:5], 1.0 op_sel_hi:[1,0]
	s_waitcnt lgkmcnt(0)
	v_lshlrev_b32_e32 v8, 16, v0
	v_rcp_f32_e32 v13, v5
	v_and_b32_e32 v9, 0xffff0000, v0
	v_add_u32_e32 v7, s0, v7
	v_rcp_f32_e32 v15, v4
	v_mul_f32_e32 v5, v10, v13
	v_lshlrev_b32_e32 v14, 16, v65
	v_mul_f32_e32 v10, 0xbfb8aa3b, v14
	v_mul_f32_e32 v11, 0xbfb8aa3b, v16
	v_exp_f32_e32 v10, v10
	v_exp_f32_e32 v11, v11
	v_mul_f32_e32 v4, v12, v15
	v_pk_mul_f32 v[4:5], v[4:5], v[8:9]
	v_pk_add_f32 v[8:9], v[10:11], 1.0 op_sel_hi:[1,0]
	v_cvt_pk_bf16_f32 v0, v4, v5
	v_rcp_f32_e32 v11, v9
	v_lshlrev_b32_e32 v4, 16, v1
	v_and_b32_e32 v5, 0xffff0000, v1
	v_lshlrev_b32_e32 v15, 16, v66
	v_rcp_f32_e32 v13, v8
	v_mul_f32_e32 v9, v16, v11
	v_and_b32_e32 v16, 0xffff0000, v66
	v_mul_f32_e32 v10, 0xbfb8aa3b, v15
	v_mul_f32_e32 v11, 0xbfb8aa3b, v16
	v_exp_f32_e32 v10, v10
	v_exp_f32_e32 v11, v11
	v_mul_f32_e32 v8, v14, v13
	v_pk_mul_f32 v[4:5], v[8:9], v[4:5]
	v_pk_add_f32 v[8:9], v[10:11], 1.0 op_sel_hi:[1,0]
	v_cvt_pk_bf16_f32 v1, v4, v5
	v_rcp_f32_e32 v11, v9
	v_lshlrev_b32_e32 v4, 16, v2
	v_and_b32_e32 v5, 0xffff0000, v2
	v_lshlrev_b32_e32 v14, 16, v67
	v_rcp_f32_e32 v13, v8
	v_mul_f32_e32 v9, v16, v11
	v_and_b32_e32 v16, 0xffff0000, v67
	v_mul_f32_e32 v10, 0xbfb8aa3b, v14
	v_mul_f32_e32 v11, 0xbfb8aa3b, v16
	v_exp_f32_e32 v10, v10
	v_exp_f32_e32 v11, v11
	v_mul_f32_e32 v8, v15, v13
	v_pk_mul_f32 v[4:5], v[8:9], v[4:5]
	v_pk_add_f32 v[8:9], v[10:11], 1.0 op_sel_hi:[1,0]
	v_cvt_pk_bf16_f32 v2, v4, v5
	v_rcp_f32_e32 v11, v9
	v_lshlrev_b32_e32 v4, 16, v3
	v_and_b32_e32 v5, 0xffff0000, v3
	v_rcp_f32_e32 v13, v8
	v_mul_f32_e32 v9, v16, v11
	v_mul_f32_e32 v8, v14, v13
	v_pk_mul_f32 v[4:5], v[8:9], v[4:5]
	s_nop 0
	v_cvt_pk_bf16_f32 v3, v4, v5
	global_store_dwordx4 v[6:7], v[0:3], off offset:2048
	s_branch .LBB0_828

.LBB0_916:
	v_lshl_or_b32 v130, s7, 8, v152
	v_lshl_add_u32 v154, s8, 8, v150
	v_mov_b64_e32 v[144:145], s[82:83]
	v_ashrrev_i32_e32 v131, 31, v130
	v_mad_i64_i32 v[128:129], s[0:1], v154, s14, v[144:145]
	v_lshlrev_b64 v[146:147], 1, v[130:131]
	v_lshl_add_u64 v[148:149], v[128:129], 0, v[146:147]
	v_add_co_u32_e32 v128, vcc, 0x1000, v148
	v_lshl_add_u64 v[142:143], v[130:131], 2, s[72:73]
	s_nop 0
	v_addc_co_u32_e32 v129, vcc, 0, v149, vcc
	global_load_dwordx4 v[156:159], v[128:129], off
	global_load_dwordx4 v[160:163], v[148:149], off
	global_load_dwordx4 v[164:167], v[142:143], off offset:16
	global_load_dwordx4 v[168:171], v[142:143], off
	global_load_dwordx4 v[176:179], v[128:129], off offset:256
	global_load_dwordx4 v[180:183], v[148:149], off offset:256
	global_load_dwordx4 v[184:187], v[142:143], off offset:528
	global_load_dwordx4 v[208:211], v[142:143], off offset:512
	s_waitcnt vmcnt(4)
	v_pk_add_f32 v[130:131], v[122:123], v[166:167]
	v_pk_add_f32 v[124:125], v[124:125], v[168:169]
	v_pk_add_f32 v[122:123], v[120:121], v[164:165]
	v_mul_f32_e32 v120, 0xbfb8aa3b, v124
	v_mul_f32_e32 v121, 0xbfb8aa3b, v125
	v_exp_f32_e32 v120, v120
	v_exp_f32_e32 v121, v121
	v_lshlrev_b32_e32 v164, 16, v156
	v_and_b32_e32 v165, 0xffff0000, v156
	v_lshlrev_b32_e32 v155, 16, v160
	v_pk_add_f32 v[120:121], v[120:121], 1.0 op_sel_hi:[1,0]
	v_and_b32_e32 v160, 0xffff0000, v160
	v_rcp_f32_e32 v156, v121
	v_mul_f32_e32 v124, 0xbfb8aa3b, v155
	v_exp_f32_e32 v124, v124
	v_pk_add_f32 v[126:127], v[126:127], v[170:171]
	v_mov_b32_e32 v121, v156
	v_rcp_f32_e32 v156, v120
	v_mul_f32_e32 v122, 0xbfb8aa3b, v122
	v_mul_f32_e32 v123, 0xbfb8aa3b, v123
	v_exp_f32_e32 v122, v122
	v_mov_b32_e32 v120, v156
	v_mul_f32_e32 v125, 0xbfb8aa3b, v160
	v_exp_f32_e32 v125, v125
	v_pk_mul_f32 v[120:121], v[120:121], v[164:165]
	v_exp_f32_e32 v123, v123
	v_pk_add_f32 v[124:125], v[124:125], 1.0 op_sel_hi:[1,0]
	s_nop 0
	v_rcp_f32_e32 v164, v125
	v_pk_add_f32 v[122:123], v[122:123], 1.0 op_sel_hi:[1,0]
	v_mul_f32_e32 v125, v160, v164
	v_rcp_f32_e32 v160, v124
	s_nop 0
	v_mul_f32_e32 v124, v155, v160
	v_pk_mul_f32 v[120:121], v[124:125], v[120:121]
	v_and_b32_e32 v155, 0xffff0000, v161
	v_cvt_pk_bf16_f32 v120, v120, v121
	v_mul_f32_e32 v121, 0xbfb8aa3b, v126
	v_exp_f32_e32 v124, v121
	v_mul_f32_e32 v121, 0xbfb8aa3b, v127
	v_exp_f32_e32 v125, v121
	v_lshlrev_b32_e32 v121, 16, v161
	v_mul_f32_e32 v126, 0xbfb8aa3b, v121
	v_exp_f32_e32 v126, v126
	v_pk_add_f32 v[124:125], v[124:125], 1.0 op_sel_hi:[1,0]
	v_lshlrev_b32_e32 v156, 16, v157
	v_rcp_f32_e32 v160, v125
	v_and_b32_e32 v157, 0xffff0000, v157
	v_mov_b32_e32 v125, v160
	v_rcp_f32_e32 v160, v124
	s_nop 0
	v_mov_b32_e32 v124, v160
	v_mul_f32_e32 v127, 0xbfb8aa3b, v155
	v_exp_f32_e32 v127, v127
	v_pk_mul_f32 v[124:125], v[124:125], v[156:157]
	v_pk_add_f32 v[126:127], v[126:127], 1.0 op_sel_hi:[1,0]
	s_nop 0
	v_rcp_f32_e32 v157, v127
	s_nop 0
	v_mul_f32_e32 v127, v155, v157
	v_rcp_f32_e32 v156, v126
	s_nop 0
	v_mul_f32_e32 v126, v121, v156
	v_pk_mul_f32 v[124:125], v[126:127], v[124:125]
	v_lshlrev_b32_e32 v126, 16, v158
	v_cvt_pk_bf16_f32 v121, v124, v125
	v_rcp_f32_e32 v157, v123
	v_and_b32_e32 v127, 0xffff0000, v158
	v_lshlrev_b32_e32 v155, 16, v162
	v_and_b32_e32 v156, 0xffff0000, v162
	v_mov_b32_e32 v123, v157
	v_rcp_f32_e32 v157, v122
	v_mul_f32_e32 v124, 0xbfb8aa3b, v155
	v_exp_f32_e32 v124, v124
	v_mov_b32_e32 v122, v157
	v_mul_f32_e32 v125, 0xbfb8aa3b, v156
	v_exp_f32_e32 v125, v125
	v_pk_mul_f32 v[122:123], v[122:123], v[126:127]
	v_pk_add_f32 v[124:125], v[124:125], 1.0 op_sel_hi:[1,0]
	s_nop 0
	v_rcp_f32_e32 v127, v125
	s_nop 0
	v_mul_f32_e32 v125, v156, v127
	v_rcp_f32_e32 v127, v124
	s_nop 0
	v_mul_f32_e32 v124, v155, v127
	v_pk_mul_f32 v[122:123], v[124:125], v[122:123]
	v_and_b32_e32 v155, 0xffff0000, v163
	v_cvt_pk_bf16_f32 v122, v122, v123
	v_mul_f32_e32 v123, 0xbfb8aa3b, v130
	v_exp_f32_e32 v124, v123
	v_mul_f32_e32 v123, 0xbfb8aa3b, v131
	v_exp_f32_e32 v125, v123
	v_lshlrev_b32_e32 v130, 16, v159
	v_and_b32_e32 v131, 0xffff0000, v159
	v_lshlrev_b32_e32 v123, 16, v163
	v_pk_add_f32 v[124:125], v[124:125], 1.0 op_sel_hi:[1,0]
	v_mul_f32_e32 v126, 0xbfb8aa3b, v123
	v_rcp_f32_e32 v156, v125
	v_exp_f32_e32 v126, v126
	v_mov_b32_e32 v125, v156
	v_rcp_f32_e32 v156, v124
	s_nop 0
	v_mov_b32_e32 v124, v156
	v_mul_f32_e32 v127, 0xbfb8aa3b, v155
	v_exp_f32_e32 v127, v127
	v_pk_mul_f32 v[124:125], v[124:125], v[130:131]
	v_pk_add_f32 v[126:127], v[126:127], 1.0 op_sel_hi:[1,0]
	s_nop 0
	v_rcp_f32_e32 v131, v127
	s_nop 0
	v_mul_f32_e32 v127, v155, v131
	v_rcp_f32_e32 v131, v126
	s_nop 0
	v_mul_f32_e32 v126, v123, v131
	v_pk_mul_f32 v[124:125], v[126:127], v[124:125]
	s_nop 0
	v_cvt_pk_bf16_f32 v123, v124, v125
	global_store_dwordx4 v[148:149], v[120:123], off
	s_nop 1
	v_or_b32_e32 v248, 16, v154
	v_mad_i64_i32 v[248:249], s[0:1], v248, s14, v[144:145]
	v_lshl_add_u64 v[250:251], v[248:249], 0, v[146:147]
	v_add_co_u32_e32 v174, vcc, s15, v250
	s_nop 1
	v_addc_co_u32_e32 v175, vcc, 0, v251, vcc
	global_load_dwordx4 v[228:231], v[174:175], off
	global_load_dwordx4 v[232:235], v[250:251], off
	global_load_dwordx4 v[236:239], v[142:143], off offset:16
	global_load_dwordx4 v[240:243], v[142:143], off
	s_waitcnt vmcnt(5)
	v_lshlrev_b32_e32 v155, 16, v180
	v_and_b32_e32 v124, 0xffff0000, v180
	v_pk_add_f32 v[156:157], v[116:117], v[208:209]
	v_pk_add_f32 v[116:117], v[114:115], v[186:187]
	v_pk_add_f32 v[114:115], v[112:113], v[184:185]
	v_mul_f32_e32 v112, 0xbfb8aa3b, v156
	v_mul_f32_e32 v113, 0xbfb8aa3b, v157
	v_exp_f32_e32 v112, v112
	v_exp_f32_e32 v113, v113
	v_lshlrev_b32_e32 v130, 16, v176
	v_and_b32_e32 v131, 0xffff0000, v176
	v_pk_add_f32 v[118:119], v[118:119], v[210:211]
	v_pk_add_f32 v[112:113], v[112:113], 1.0 op_sel_hi:[1,0]
	v_mul_f32_e32 v128, 0xbfb8aa3b, v155
	v_rcp_f32_e32 v129, v113
	v_exp_f32_e32 v128, v128
	v_mul_f32_e32 v114, 0xbfb8aa3b, v114
	v_mul_f32_e32 v115, 0xbfb8aa3b, v115
	v_mov_b32_e32 v113, v129
	v_rcp_f32_e32 v129, v112
	v_exp_f32_e32 v114, v114
	v_exp_f32_e32 v115, v115
	v_mov_b32_e32 v112, v129
	v_mul_f32_e32 v120, 0xbfb8aa3b, v124
	v_exp_f32_e32 v129, v120
	v_pk_mul_f32 v[112:113], v[112:113], v[130:131]
	v_pk_add_f32 v[114:115], v[114:115], 1.0 op_sel_hi:[1,0]
	v_pk_add_f32 v[128:129], v[128:129], 1.0 op_sel_hi:[1,0]
	s_nop 0
	v_rcp_f32_e32 v130, v129
	s_nop 0
	v_mul_f32_e32 v129, v124, v130
	v_rcp_f32_e32 v124, v128
	s_nop 0
	v_mul_f32_e32 v128, v155, v124
	v_pk_mul_f32 v[112:113], v[128:129], v[112:113]
	v_and_b32_e32 v128, 0xffff0000, v181
	v_cvt_pk_bf16_f32 v112, v112, v113
	v_mul_f32_e32 v113, 0xbfb8aa3b, v118
	v_exp_f32_e32 v118, v113
	v_mul_f32_e32 v113, 0xbfb8aa3b, v119
	v_exp_f32_e32 v119, v113
	v_lshlrev_b32_e32 v113, 16, v181
	v_lshlrev_b32_e32 v124, 16, v177
	v_and_b32_e32 v125, 0xffff0000, v177
	v_pk_add_f32 v[118:119], v[118:119], 1.0 op_sel_hi:[1,0]
	v_mul_f32_e32 v120, 0xbfb8aa3b, v113
	v_rcp_f32_e32 v129, v119
	v_exp_f32_e32 v120, v120
	v_mov_b32_e32 v119, v129
	v_rcp_f32_e32 v129, v118
	s_nop 0
	v_mov_b32_e32 v118, v129
	v_mul_f32_e32 v121, 0xbfb8aa3b, v128
	v_exp_f32_e32 v121, v121
	v_pk_mul_f32 v[118:119], v[118:119], v[124:125]
	v_pk_add_f32 v[120:121], v[120:121], 1.0 op_sel_hi:[1,0]
	s_nop 0
	v_rcp_f32_e32 v125, v121
	s_nop 0
	v_mul_f32_e32 v121, v128, v125
	v_rcp_f32_e32 v125, v120
	s_nop 0
	v_mul_f32_e32 v120, v113, v125
	v_pk_mul_f32 v[118:119], v[120:121], v[118:119]
	v_lshlrev_b32_e32 v120, 16, v178
	v_cvt_pk_bf16_f32 v113, v118, v119
	v_and_b32_e32 v121, 0xffff0000, v178
	v_rcp_f32_e32 v122, v115
	v_lshlrev_b32_e32 v124, 16, v182
	v_and_b32_e32 v125, 0xffff0000, v182
	v_mul_f32_e32 v118, 0xbfb8aa3b, v124
	v_mov_b32_e32 v115, v122
	v_rcp_f32_e32 v122, v114
	v_exp_f32_e32 v118, v118
	v_mov_b32_e32 v114, v122
	v_mul_f32_e32 v119, 0xbfb8aa3b, v125
	v_exp_f32_e32 v119, v119
	v_pk_mul_f32 v[114:115], v[114:115], v[120:121]
	v_pk_add_f32 v[118:119], v[118:119], 1.0 op_sel_hi:[1,0]
	s_nop 0
	v_rcp_f32_e32 v121, v119
	s_nop 0
	v_mul_f32_e32 v119, v125, v121
	v_rcp_f32_e32 v121, v118
	s_nop 0
	v_mul_f32_e32 v118, v124, v121
	v_pk_mul_f32 v[114:115], v[118:119], v[114:115]
	v_lshlrev_b32_e32 v120, 16, v179
	v_cvt_pk_bf16_f32 v114, v114, v115
	v_mul_f32_e32 v115, 0xbfb8aa3b, v116
	v_exp_f32_e32 v116, v115
	v_mul_f32_e32 v115, 0xbfb8aa3b, v117
	v_exp_f32_e32 v117, v115
	v_and_b32_e32 v121, 0xffff0000, v179
	v_lshlrev_b32_e32 v115, 16, v183
	v_and_b32_e32 v122, 0xffff0000, v183
	v_pk_add_f32 v[116:117], v[116:117], 1.0 op_sel_hi:[1,0]
	v_mul_f32_e32 v118, 0xbfb8aa3b, v115
	v_rcp_f32_e32 v123, v117
	v_exp_f32_e32 v118, v118
	v_mov_b32_e32 v117, v123
	v_rcp_f32_e32 v123, v116
	s_nop 0
	v_mov_b32_e32 v116, v123
	v_mul_f32_e32 v119, 0xbfb8aa3b, v122
	v_exp_f32_e32 v119, v119
	v_pk_mul_f32 v[116:117], v[116:117], v[120:121]
	v_pk_add_f32 v[118:119], v[118:119], 1.0 op_sel_hi:[1,0]
	s_nop 0
	v_rcp_f32_e32 v121, v119
	s_nop 0
	v_mul_f32_e32 v119, v122, v121
	v_rcp_f32_e32 v121, v118
	s_nop 0
	v_mul_f32_e32 v120, v115, v121
	v_mov_b32_e32 v118, v120
	v_pk_mul_f32 v[116:117], v[118:119], v[116:117]
	s_nop 0
	v_cvt_pk_bf16_f32 v115, v116, v117
	global_store_dwordx4 v[148:149], v[112:115], off offset:256
	global_load_dwordx4 v[176:179], v[174:175], off offset:256
	global_load_dwordx4 v[180:183], v[250:251], off offset:256
	global_load_dwordx4 v[184:187], v[142:143], off offset:528
	global_load_dwordx4 v[208:211], v[142:143], off offset:512
	s_waitcnt vmcnt(5)
	v_pk_add_f32 v[126:127], v[106:107], v[238:239]
	v_pk_add_f32 v[108:109], v[108:109], v[240:241]
	v_pk_add_f32 v[106:107], v[104:105], v[236:237]
	v_mul_f32_e32 v104, 0xbfb8aa3b, v108
	v_mul_f32_e32 v105, 0xbfb8aa3b, v109
	v_exp_f32_e32 v104, v104
	v_exp_f32_e32 v105, v105
	v_lshlrev_b32_e32 v124, 16, v228
	v_and_b32_e32 v125, 0xffff0000, v228
	v_pk_add_f32 v[110:111], v[110:111], v[242:243]
	v_pk_add_f32 v[104:105], v[104:105], 1.0 op_sel_hi:[1,0]
	v_lshlrev_b32_e32 v128, 16, v232
	v_rcp_f32_e32 v112, v105
	v_and_b32_e32 v116, 0xffff0000, v232
	v_mul_f32_e32 v108, 0xbfb8aa3b, v128
	v_exp_f32_e32 v108, v108
	v_mov_b32_e32 v105, v112
	v_rcp_f32_e32 v112, v104
	v_mul_f32_e32 v106, 0xbfb8aa3b, v106
	v_mul_f32_e32 v107, 0xbfb8aa3b, v107
	v_exp_f32_e32 v106, v106
	v_mov_b32_e32 v104, v112
	v_mul_f32_e32 v109, 0xbfb8aa3b, v116
	v_exp_f32_e32 v109, v109
	v_pk_mul_f32 v[104:105], v[104:105], v[124:125]
	v_exp_f32_e32 v107, v107
	v_pk_add_f32 v[108:109], v[108:109], 1.0 op_sel_hi:[1,0]
	s_nop 0
	v_rcp_f32_e32 v124, v109
	v_pk_add_f32 v[106:107], v[106:107], 1.0 op_sel_hi:[1,0]
	v_mul_f32_e32 v109, v116, v124
	v_rcp_f32_e32 v116, v108
	s_nop 0
	v_mul_f32_e32 v108, v128, v116
	v_pk_mul_f32 v[104:105], v[108:109], v[104:105]
	v_and_b32_e32 v116, 0xffff0000, v233
	v_cvt_pk_bf16_f32 v104, v104, v105
	v_mul_f32_e32 v105, 0xbfb8aa3b, v110
	v_exp_f32_e32 v108, v105
	v_mul_f32_e32 v105, 0xbfb8aa3b, v111
	v_exp_f32_e32 v109, v105
	v_lshlrev_b32_e32 v105, 16, v233
	v_mul_f32_e32 v110, 0xbfb8aa3b, v105
	v_exp_f32_e32 v110, v110
	v_pk_add_f32 v[108:109], v[108:109], 1.0 op_sel_hi:[1,0]
	v_lshlrev_b32_e32 v112, 16, v229
	v_rcp_f32_e32 v117, v109
	v_and_b32_e32 v113, 0xffff0000, v229
	v_mov_b32_e32 v109, v117
	v_rcp_f32_e32 v117, v108
	s_nop 0
	v_mov_b32_e32 v108, v117
	v_mul_f32_e32 v111, 0xbfb8aa3b, v116
	v_exp_f32_e32 v111, v111
	v_pk_mul_f32 v[108:109], v[108:109], v[112:113]
	v_pk_add_f32 v[110:111], v[110:111], 1.0 op_sel_hi:[1,0]
	s_nop 0
	v_rcp_f32_e32 v113, v111
	s_nop 0
	v_mul_f32_e32 v111, v116, v113
	v_rcp_f32_e32 v113, v110
	s_nop 0
	v_mul_f32_e32 v110, v105, v113
	v_pk_mul_f32 v[108:109], v[110:111], v[108:109]
	v_lshlrev_b32_e32 v110, 16, v230
	v_cvt_pk_bf16_f32 v105, v108, v109
	v_and_b32_e32 v111, 0xffff0000, v230
	v_rcp_f32_e32 v114, v107
	v_lshlrev_b32_e32 v112, 16, v234
	v_and_b32_e32 v113, 0xffff0000, v234
	v_mul_f32_e32 v108, 0xbfb8aa3b, v112
	v_mov_b32_e32 v107, v114
	v_rcp_f32_e32 v114, v106
	v_exp_f32_e32 v108, v108
	v_mov_b32_e32 v106, v114
	v_mul_f32_e32 v109, 0xbfb8aa3b, v113
	v_exp_f32_e32 v109, v109
	v_pk_mul_f32 v[106:107], v[106:107], v[110:111]
	v_pk_add_f32 v[108:109], v[108:109], 1.0 op_sel_hi:[1,0]
	s_nop 0
	v_rcp_f32_e32 v111, v109
	s_nop 0
	v_mul_f32_e32 v109, v113, v111
	v_rcp_f32_e32 v111, v108
	s_nop 0
	v_mul_f32_e32 v108, v112, v111
	v_pk_mul_f32 v[106:107], v[108:109], v[106:107]
	v_lshlrev_b32_e32 v112, 16, v231
	v_cvt_pk_bf16_f32 v106, v106, v107
	v_mul_f32_e32 v107, 0xbfb8aa3b, v126
	v_exp_f32_e32 v108, v107
	v_mul_f32_e32 v107, 0xbfb8aa3b, v127
	v_exp_f32_e32 v109, v107
	v_and_b32_e32 v113, 0xffff0000, v231
	v_lshlrev_b32_e32 v107, 16, v235
	v_and_b32_e32 v114, 0xffff0000, v235
	v_pk_add_f32 v[108:109], v[108:109], 1.0 op_sel_hi:[1,0]
	v_mul_f32_e32 v110, 0xbfb8aa3b, v107
	v_rcp_f32_e32 v115, v109
	v_exp_f32_e32 v110, v110
	v_mov_b32_e32 v109, v115
	v_rcp_f32_e32 v115, v108
	s_nop 0
	v_mov_b32_e32 v108, v115
	v_mul_f32_e32 v111, 0xbfb8aa3b, v114
	v_exp_f32_e32 v111, v111
	v_pk_mul_f32 v[108:109], v[108:109], v[112:113]
	v_pk_add_f32 v[110:111], v[110:111], 1.0 op_sel_hi:[1,0]
	s_nop 0
	v_rcp_f32_e32 v113, v111
	s_nop 0
	v_mul_f32_e32 v111, v114, v113
	v_rcp_f32_e32 v113, v110
	s_nop 0
	v_mul_f32_e32 v110, v107, v113
	v_pk_mul_f32 v[108:109], v[110:111], v[108:109]
	s_nop 0
	v_cvt_pk_bf16_f32 v107, v108, v109
	global_store_dwordx4 v[250:251], v[104:107], off
	s_nop 1
	v_or_b32_e32 v212, 32, v154
	v_mad_i64_i32 v[212:213], s[0:1], v212, s14, v[144:145]
	v_lshl_add_u64 v[214:215], v[212:213], 0, v[146:147]
	v_add_co_u32_e32 v246, vcc, s15, v214
	s_nop 1
	v_addc_co_u32_e32 v247, vcc, 0, v215, vcc
	global_load_dwordx4 v[228:231], v[246:247], off
	global_load_dwordx4 v[232:235], v[214:215], off
	global_load_dwordx4 v[236:239], v[142:143], off offset:16
	global_load_dwordx4 v[240:243], v[142:143], off
	s_waitcnt vmcnt(5)
	v_pk_add_f32 v[116:117], v[100:101], v[208:209]
	v_pk_add_f32 v[100:101], v[98:99], v[186:187]
	v_pk_add_f32 v[98:99], v[96:97], v[184:185]
	v_mul_f32_e32 v96, 0xbfb8aa3b, v116
	v_mul_f32_e32 v97, 0xbfb8aa3b, v117
	v_exp_f32_e32 v96, v96
	v_exp_f32_e32 v97, v97
	v_lshlrev_b32_e32 v114, 16, v176
	v_and_b32_e32 v115, 0xffff0000, v176
	v_pk_add_f32 v[102:103], v[102:103], v[210:211]
	v_pk_add_f32 v[96:97], v[96:97], 1.0 op_sel_hi:[1,0]
	v_lshlrev_b32_e32 v116, 16, v180
	v_rcp_f32_e32 v113, v97
	v_and_b32_e32 v108, 0xffff0000, v180
	v_mul_f32_e32 v112, 0xbfb8aa3b, v116
	v_exp_f32_e32 v112, v112
	v_mov_b32_e32 v97, v113
	v_rcp_f32_e32 v113, v96
	v_mul_f32_e32 v98, 0xbfb8aa3b, v98
	v_mul_f32_e32 v99, 0xbfb8aa3b, v99
	v_exp_f32_e32 v98, v98
	v_mov_b32_e32 v96, v113
	v_mul_f32_e32 v104, 0xbfb8aa3b, v108
	v_exp_f32_e32 v113, v104
	v_pk_mul_f32 v[96:97], v[96:97], v[114:115]
	v_exp_f32_e32 v99, v99
	v_pk_add_f32 v[112:113], v[112:113], 1.0 op_sel_hi:[1,0]
	s_nop 0
	v_rcp_f32_e32 v114, v113
	v_pk_add_f32 v[98:99], v[98:99], 1.0 op_sel_hi:[1,0]
	v_mul_f32_e32 v113, v108, v114
	v_rcp_f32_e32 v108, v112
	s_nop 0
	v_mul_f32_e32 v112, v116, v108
	v_pk_mul_f32 v[96:97], v[112:113], v[96:97]
	v_and_b32_e32 v112, 0xffff0000, v181
	v_cvt_pk_bf16_f32 v96, v96, v97
	v_mul_f32_e32 v97, 0xbfb8aa3b, v102
	v_exp_f32_e32 v102, v97
	v_mul_f32_e32 v97, 0xbfb8aa3b, v103
	v_exp_f32_e32 v103, v97
	v_lshlrev_b32_e32 v97, 16, v181
	v_lshlrev_b32_e32 v108, 16, v177
	v_and_b32_e32 v109, 0xffff0000, v177
	v_pk_add_f32 v[102:103], v[102:103], 1.0 op_sel_hi:[1,0]
	v_mul_f32_e32 v104, 0xbfb8aa3b, v97
	v_rcp_f32_e32 v113, v103
	v_exp_f32_e32 v104, v104
	v_mov_b32_e32 v103, v113
	v_rcp_f32_e32 v113, v102
	s_nop 0
	v_mov_b32_e32 v102, v113
	v_mul_f32_e32 v105, 0xbfb8aa3b, v112
	v_exp_f32_e32 v105, v105
	v_pk_mul_f32 v[102:103], v[102:103], v[108:109]
	v_pk_add_f32 v[104:105], v[104:105], 1.0 op_sel_hi:[1,0]
	s_nop 0
	v_rcp_f32_e32 v109, v105
	s_nop 0
	v_mul_f32_e32 v105, v112, v109
	v_rcp_f32_e32 v109, v104
	s_nop 0
	v_mul_f32_e32 v104, v97, v109
	v_pk_mul_f32 v[102:103], v[104:105], v[102:103]
	v_lshlrev_b32_e32 v104, 16, v178
	v_cvt_pk_bf16_f32 v97, v102, v103
	v_and_b32_e32 v105, 0xffff0000, v178
	v_rcp_f32_e32 v106, v99
	v_lshlrev_b32_e32 v108, 16, v182
	v_and_b32_e32 v109, 0xffff0000, v182
	v_mul_f32_e32 v102, 0xbfb8aa3b, v108
	v_mov_b32_e32 v99, v106
	v_rcp_f32_e32 v106, v98
	v_exp_f32_e32 v102, v102
	v_mov_b32_e32 v98, v106
	v_mul_f32_e32 v103, 0xbfb8aa3b, v109
	v_exp_f32_e32 v103, v103
	v_pk_mul_f32 v[98:99], v[98:99], v[104:105]
	v_pk_add_f32 v[102:103], v[102:103], 1.0 op_sel_hi:[1,0]
	s_nop 0
	v_rcp_f32_e32 v105, v103
	s_nop 0
	v_mul_f32_e32 v103, v109, v105
	v_rcp_f32_e32 v105, v102
	s_nop 0
	v_mul_f32_e32 v102, v108, v105
	v_pk_mul_f32 v[98:99], v[102:103], v[98:99]
	v_lshlrev_b32_e32 v104, 16, v179
	v_cvt_pk_bf16_f32 v98, v98, v99
	v_mul_f32_e32 v99, 0xbfb8aa3b, v100
	v_exp_f32_e32 v100, v99
	v_mul_f32_e32 v99, 0xbfb8aa3b, v101
	v_exp_f32_e32 v101, v99
	v_and_b32_e32 v105, 0xffff0000, v179
	v_lshlrev_b32_e32 v99, 16, v183
	v_and_b32_e32 v106, 0xffff0000, v183
	v_pk_add_f32 v[100:101], v[100:101], 1.0 op_sel_hi:[1,0]
	v_mul_f32_e32 v102, 0xbfb8aa3b, v99
	v_rcp_f32_e32 v107, v101
	v_exp_f32_e32 v102, v102
	v_mov_b32_e32 v101, v107
	v_rcp_f32_e32 v107, v100
	s_nop 0
	v_mov_b32_e32 v100, v107
	v_mul_f32_e32 v103, 0xbfb8aa3b, v106
	v_exp_f32_e32 v103, v103
	v_pk_mul_f32 v[100:101], v[100:101], v[104:105]
	v_pk_add_f32 v[102:103], v[102:103], 1.0 op_sel_hi:[1,0]
	s_nop 0
	v_rcp_f32_e32 v105, v103
	s_nop 0
	v_mul_f32_e32 v103, v106, v105
	v_rcp_f32_e32 v105, v102
	s_nop 0
	v_mul_f32_e32 v104, v99, v105
	v_mov_b32_e32 v102, v104
	v_pk_mul_f32 v[100:101], v[102:103], v[100:101]
	s_nop 0
	v_cvt_pk_bf16_f32 v99, v100, v101
	global_store_dwordx4 v[250:251], v[96:99], off offset:256
	global_load_dwordx4 v[176:179], v[246:247], off offset:256
	global_load_dwordx4 v[180:183], v[214:215], off offset:256
	global_load_dwordx4 v[184:187], v[142:143], off offset:528
	global_load_dwordx4 v[208:211], v[142:143], off offset:512
	s_waitcnt vmcnt(5)
	v_pk_add_f32 v[110:111], v[90:91], v[238:239]
	v_pk_add_f32 v[92:93], v[92:93], v[240:241]
	v_pk_add_f32 v[90:91], v[88:89], v[236:237]
	v_mul_f32_e32 v88, 0xbfb8aa3b, v92
	v_mul_f32_e32 v89, 0xbfb8aa3b, v93
	v_exp_f32_e32 v88, v88
	v_exp_f32_e32 v89, v89
	v_lshlrev_b32_e32 v108, 16, v228
	v_and_b32_e32 v109, 0xffff0000, v228
	v_pk_add_f32 v[94:95], v[94:95], v[242:243]
	v_pk_add_f32 v[88:89], v[88:89], 1.0 op_sel_hi:[1,0]
	v_lshlrev_b32_e32 v112, 16, v232
	v_rcp_f32_e32 v96, v89
	v_and_b32_e32 v100, 0xffff0000, v232
	v_mul_f32_e32 v92, 0xbfb8aa3b, v112
	v_exp_f32_e32 v92, v92
	v_mov_b32_e32 v89, v96
	v_rcp_f32_e32 v96, v88
	v_mul_f32_e32 v90, 0xbfb8aa3b, v90
	v_mul_f32_e32 v91, 0xbfb8aa3b, v91
	v_exp_f32_e32 v90, v90
	v_mov_b32_e32 v88, v96
	v_mul_f32_e32 v93, 0xbfb8aa3b, v100
	v_exp_f32_e32 v93, v93
	v_pk_mul_f32 v[88:89], v[88:89], v[108:109]
	v_exp_f32_e32 v91, v91
	v_pk_add_f32 v[92:93], v[92:93], 1.0 op_sel_hi:[1,0]
	s_nop 0
	v_rcp_f32_e32 v108, v93
	v_pk_add_f32 v[90:91], v[90:91], 1.0 op_sel_hi:[1,0]
	v_mul_f32_e32 v93, v100, v108
	v_rcp_f32_e32 v100, v92
	s_nop 0
	v_mul_f32_e32 v92, v112, v100
	v_pk_mul_f32 v[88:89], v[92:93], v[88:89]
	v_and_b32_e32 v100, 0xffff0000, v233
	v_cvt_pk_bf16_f32 v88, v88, v89
	v_mul_f32_e32 v89, 0xbfb8aa3b, v94
	v_exp_f32_e32 v92, v89
	v_mul_f32_e32 v89, 0xbfb8aa3b, v95
	v_exp_f32_e32 v93, v89
	v_lshlrev_b32_e32 v89, 16, v233
	v_mul_f32_e32 v94, 0xbfb8aa3b, v89
	v_exp_f32_e32 v94, v94
	v_pk_add_f32 v[92:93], v[92:93], 1.0 op_sel_hi:[1,0]
	v_lshlrev_b32_e32 v96, 16, v229
	v_rcp_f32_e32 v101, v93
	v_and_b32_e32 v97, 0xffff0000, v229
	v_mov_b32_e32 v93, v101
	v_rcp_f32_e32 v101, v92
	s_nop 0
	v_mov_b32_e32 v92, v101
	v_mul_f32_e32 v95, 0xbfb8aa3b, v100
	v_exp_f32_e32 v95, v95
	v_pk_mul_f32 v[92:93], v[92:93], v[96:97]
	v_pk_add_f32 v[94:95], v[94:95], 1.0 op_sel_hi:[1,0]
	s_nop 0
	v_rcp_f32_e32 v97, v95
	s_nop 0
	v_mul_f32_e32 v95, v100, v97
	v_rcp_f32_e32 v97, v94
	s_nop 0
	v_mul_f32_e32 v94, v89, v97
	v_pk_mul_f32 v[92:93], v[94:95], v[92:93]
	v_lshlrev_b32_e32 v94, 16, v230
	v_cvt_pk_bf16_f32 v89, v92, v93
	v_and_b32_e32 v95, 0xffff0000, v230
	v_rcp_f32_e32 v98, v91
	v_lshlrev_b32_e32 v96, 16, v234
	v_and_b32_e32 v97, 0xffff0000, v234
	v_mul_f32_e32 v92, 0xbfb8aa3b, v96
	v_mov_b32_e32 v91, v98
	v_rcp_f32_e32 v98, v90
	v_exp_f32_e32 v92, v92
	v_mov_b32_e32 v90, v98
	v_mul_f32_e32 v93, 0xbfb8aa3b, v97
	v_exp_f32_e32 v93, v93
	v_pk_mul_f32 v[90:91], v[90:91], v[94:95]
	v_pk_add_f32 v[92:93], v[92:93], 1.0 op_sel_hi:[1,0]
	s_nop 0
	v_rcp_f32_e32 v95, v93
	s_nop 0
	v_mul_f32_e32 v93, v97, v95
	v_rcp_f32_e32 v95, v92
	s_nop 0
	v_mul_f32_e32 v92, v96, v95
	v_pk_mul_f32 v[90:91], v[92:93], v[90:91]
	v_lshlrev_b32_e32 v96, 16, v231
	v_cvt_pk_bf16_f32 v90, v90, v91
	v_mul_f32_e32 v91, 0xbfb8aa3b, v110
	v_exp_f32_e32 v92, v91
	v_mul_f32_e32 v91, 0xbfb8aa3b, v111
	v_exp_f32_e32 v93, v91
	v_and_b32_e32 v97, 0xffff0000, v231
	v_lshlrev_b32_e32 v91, 16, v235
	v_and_b32_e32 v98, 0xffff0000, v235
	v_pk_add_f32 v[92:93], v[92:93], 1.0 op_sel_hi:[1,0]
	v_mul_f32_e32 v94, 0xbfb8aa3b, v91
	v_rcp_f32_e32 v99, v93
	v_exp_f32_e32 v94, v94
	v_mov_b32_e32 v93, v99
	v_rcp_f32_e32 v99, v92
	s_nop 0
	v_mov_b32_e32 v92, v99
	v_mul_f32_e32 v95, 0xbfb8aa3b, v98
	v_exp_f32_e32 v95, v95
	v_pk_mul_f32 v[92:93], v[92:93], v[96:97]
	v_pk_add_f32 v[94:95], v[94:95], 1.0 op_sel_hi:[1,0]
	s_nop 0
	v_rcp_f32_e32 v97, v95
	s_nop 0
	v_mul_f32_e32 v95, v98, v97
	v_rcp_f32_e32 v97, v94
	s_nop 0
	v_mul_f32_e32 v94, v91, v97
	v_pk_mul_f32 v[92:93], v[94:95], v[92:93]
	s_nop 0
	v_cvt_pk_bf16_f32 v91, v92, v93
	global_store_dwordx4 v[214:215], v[88:91], off
	s_nop 1
	v_or_b32_e32 v248, 48, v154
	v_mad_i64_i32 v[248:249], s[0:1], v248, s14, v[144:145]
	v_lshl_add_u64 v[250:251], v[248:249], 0, v[146:147]
	v_add_co_u32_e32 v174, vcc, s15, v250
	s_nop 1
	v_addc_co_u32_e32 v175, vcc, 0, v251, vcc
	global_load_dwordx4 v[228:231], v[174:175], off
	global_load_dwordx4 v[232:235], v[250:251], off
	global_load_dwordx4 v[236:239], v[142:143], off offset:16
	global_load_dwordx4 v[240:243], v[142:143], off
	s_waitcnt vmcnt(5)
	v_pk_add_f32 v[100:101], v[84:85], v[208:209]
	v_pk_add_f32 v[84:85], v[82:83], v[186:187]
	v_pk_add_f32 v[82:83], v[80:81], v[184:185]
	v_mul_f32_e32 v80, 0xbfb8aa3b, v100
	v_mul_f32_e32 v81, 0xbfb8aa3b, v101
	v_exp_f32_e32 v80, v80
	v_exp_f32_e32 v81, v81
	v_lshlrev_b32_e32 v98, 16, v176
	v_and_b32_e32 v99, 0xffff0000, v176
	v_pk_add_f32 v[86:87], v[86:87], v[210:211]
	v_pk_add_f32 v[80:81], v[80:81], 1.0 op_sel_hi:[1,0]
	v_lshlrev_b32_e32 v100, 16, v180
	v_rcp_f32_e32 v97, v81
	v_and_b32_e32 v92, 0xffff0000, v180
	v_mul_f32_e32 v96, 0xbfb8aa3b, v100
	v_exp_f32_e32 v96, v96
	v_mov_b32_e32 v81, v97
	v_rcp_f32_e32 v97, v80
	v_mul_f32_e32 v82, 0xbfb8aa3b, v82
	v_mul_f32_e32 v83, 0xbfb8aa3b, v83
	v_exp_f32_e32 v82, v82
	v_mov_b32_e32 v80, v97
	v_mul_f32_e32 v88, 0xbfb8aa3b, v92
	v_exp_f32_e32 v97, v88
	v_pk_mul_f32 v[80:81], v[80:81], v[98:99]
	v_exp_f32_e32 v83, v83
	v_pk_add_f32 v[96:97], v[96:97], 1.0 op_sel_hi:[1,0]
	s_nop 0
	v_rcp_f32_e32 v98, v97
	v_pk_add_f32 v[82:83], v[82:83], 1.0 op_sel_hi:[1,0]
	v_mul_f32_e32 v97, v92, v98
	v_rcp_f32_e32 v92, v96
	s_nop 0
	v_mul_f32_e32 v96, v100, v92
	v_pk_mul_f32 v[80:81], v[96:97], v[80:81]
	v_and_b32_e32 v96, 0xffff0000, v181
	v_cvt_pk_bf16_f32 v80, v80, v81
	v_mul_f32_e32 v81, 0xbfb8aa3b, v86
	v_exp_f32_e32 v86, v81
	v_mul_f32_e32 v81, 0xbfb8aa3b, v87
	v_exp_f32_e32 v87, v81
	v_lshlrev_b32_e32 v81, 16, v181
	v_lshlrev_b32_e32 v92, 16, v177
	v_and_b32_e32 v93, 0xffff0000, v177
	v_pk_add_f32 v[86:87], v[86:87], 1.0 op_sel_hi:[1,0]
	v_mul_f32_e32 v88, 0xbfb8aa3b, v81
	v_rcp_f32_e32 v97, v87
	v_exp_f32_e32 v88, v88
	v_mov_b32_e32 v87, v97
	v_rcp_f32_e32 v97, v86
	s_nop 0
	v_mov_b32_e32 v86, v97
	v_mul_f32_e32 v89, 0xbfb8aa3b, v96
	v_exp_f32_e32 v89, v89
	v_pk_mul_f32 v[86:87], v[86:87], v[92:93]
	v_pk_add_f32 v[88:89], v[88:89], 1.0 op_sel_hi:[1,0]
	s_nop 0
	v_rcp_f32_e32 v93, v89
	s_nop 0
	v_mul_f32_e32 v89, v96, v93
	v_rcp_f32_e32 v93, v88
	s_nop 0
	v_mul_f32_e32 v88, v81, v93
	v_pk_mul_f32 v[86:87], v[88:89], v[86:87]
	v_lshlrev_b32_e32 v88, 16, v178
	v_cvt_pk_bf16_f32 v81, v86, v87
	v_and_b32_e32 v89, 0xffff0000, v178
	v_rcp_f32_e32 v90, v83
	v_lshlrev_b32_e32 v92, 16, v182
	v_and_b32_e32 v93, 0xffff0000, v182
	v_mul_f32_e32 v86, 0xbfb8aa3b, v92
	v_mov_b32_e32 v83, v90
	v_rcp_f32_e32 v90, v82
	v_exp_f32_e32 v86, v86
	v_mov_b32_e32 v82, v90
	v_mul_f32_e32 v87, 0xbfb8aa3b, v93
	v_exp_f32_e32 v87, v87
	v_pk_mul_f32 v[82:83], v[82:83], v[88:89]
	v_pk_add_f32 v[86:87], v[86:87], 1.0 op_sel_hi:[1,0]
	s_nop 0
	v_rcp_f32_e32 v89, v87
	s_nop 0
	v_mul_f32_e32 v87, v93, v89
	v_rcp_f32_e32 v89, v86
	s_nop 0
	v_mul_f32_e32 v86, v92, v89
	v_pk_mul_f32 v[82:83], v[86:87], v[82:83]
	v_lshlrev_b32_e32 v88, 16, v179
	v_cvt_pk_bf16_f32 v82, v82, v83
	v_mul_f32_e32 v83, 0xbfb8aa3b, v84
	v_exp_f32_e32 v84, v83
	v_mul_f32_e32 v83, 0xbfb8aa3b, v85
	v_exp_f32_e32 v85, v83
	v_and_b32_e32 v89, 0xffff0000, v179
	v_lshlrev_b32_e32 v83, 16, v183
	v_and_b32_e32 v90, 0xffff0000, v183
	v_pk_add_f32 v[84:85], v[84:85], 1.0 op_sel_hi:[1,0]
	v_mul_f32_e32 v86, 0xbfb8aa3b, v83
	v_rcp_f32_e32 v91, v85
	v_exp_f32_e32 v86, v86
	v_mov_b32_e32 v85, v91
	v_rcp_f32_e32 v91, v84
	s_nop 0
	v_mov_b32_e32 v84, v91
	v_mul_f32_e32 v87, 0xbfb8aa3b, v90
	v_exp_f32_e32 v87, v87
	v_pk_mul_f32 v[84:85], v[84:85], v[88:89]
	v_pk_add_f32 v[86:87], v[86:87], 1.0 op_sel_hi:[1,0]
	s_nop 0
	v_rcp_f32_e32 v89, v87
	s_nop 0
	v_mul_f32_e32 v87, v90, v89
	v_rcp_f32_e32 v89, v86
	s_nop 0
	v_mul_f32_e32 v88, v83, v89
	v_mov_b32_e32 v86, v88
	v_pk_mul_f32 v[84:85], v[86:87], v[84:85]
	s_nop 0
	v_cvt_pk_bf16_f32 v83, v84, v85
	global_store_dwordx4 v[214:215], v[80:83], off offset:256
	global_load_dwordx4 v[176:179], v[174:175], off offset:256
	global_load_dwordx4 v[180:183], v[250:251], off offset:256
	global_load_dwordx4 v[184:187], v[142:143], off offset:528
	global_load_dwordx4 v[208:211], v[142:143], off offset:512
	s_waitcnt vmcnt(5)
	v_pk_add_f32 v[94:95], v[74:75], v[238:239]
	v_pk_add_f32 v[76:77], v[76:77], v[240:241]
	v_pk_add_f32 v[74:75], v[72:73], v[236:237]
	v_mul_f32_e32 v72, 0xbfb8aa3b, v76
	v_mul_f32_e32 v73, 0xbfb8aa3b, v77
	v_exp_f32_e32 v72, v72
	v_exp_f32_e32 v73, v73
	v_lshlrev_b32_e32 v92, 16, v228
	v_and_b32_e32 v93, 0xffff0000, v228
	v_pk_add_f32 v[78:79], v[78:79], v[242:243]
	v_pk_add_f32 v[72:73], v[72:73], 1.0 op_sel_hi:[1,0]
	v_lshlrev_b32_e32 v96, 16, v232
	v_rcp_f32_e32 v80, v73
	v_and_b32_e32 v84, 0xffff0000, v232
	v_mul_f32_e32 v76, 0xbfb8aa3b, v96
	v_exp_f32_e32 v76, v76
	v_mov_b32_e32 v73, v80
	v_rcp_f32_e32 v80, v72
	v_mul_f32_e32 v74, 0xbfb8aa3b, v74
	v_mul_f32_e32 v75, 0xbfb8aa3b, v75
	v_exp_f32_e32 v74, v74
	v_mov_b32_e32 v72, v80
	v_mul_f32_e32 v77, 0xbfb8aa3b, v84
	v_exp_f32_e32 v77, v77
	v_pk_mul_f32 v[72:73], v[72:73], v[92:93]
	v_exp_f32_e32 v75, v75
	v_pk_add_f32 v[76:77], v[76:77], 1.0 op_sel_hi:[1,0]
	s_nop 0
	v_rcp_f32_e32 v92, v77
	v_pk_add_f32 v[74:75], v[74:75], 1.0 op_sel_hi:[1,0]
	v_mul_f32_e32 v77, v84, v92
	v_rcp_f32_e32 v84, v76
	s_nop 0
	v_mul_f32_e32 v76, v96, v84
	v_pk_mul_f32 v[72:73], v[76:77], v[72:73]
	v_and_b32_e32 v84, 0xffff0000, v233
	v_cvt_pk_bf16_f32 v72, v72, v73
	v_mul_f32_e32 v73, 0xbfb8aa3b, v78
	v_exp_f32_e32 v76, v73
	v_mul_f32_e32 v73, 0xbfb8aa3b, v79
	v_exp_f32_e32 v77, v73
	v_lshlrev_b32_e32 v73, 16, v233
	v_mul_f32_e32 v78, 0xbfb8aa3b, v73
	v_exp_f32_e32 v78, v78
	v_pk_add_f32 v[76:77], v[76:77], 1.0 op_sel_hi:[1,0]
	v_lshlrev_b32_e32 v80, 16, v229
	v_rcp_f32_e32 v85, v77
	v_and_b32_e32 v81, 0xffff0000, v229
	v_mov_b32_e32 v77, v85
	v_rcp_f32_e32 v85, v76
	s_nop 0
	v_mov_b32_e32 v76, v85
	v_mul_f32_e32 v79, 0xbfb8aa3b, v84
	v_exp_f32_e32 v79, v79
	v_pk_mul_f32 v[76:77], v[76:77], v[80:81]
	v_pk_add_f32 v[78:79], v[78:79], 1.0 op_sel_hi:[1,0]
	s_nop 0
	v_rcp_f32_e32 v81, v79
	s_nop 0
	v_mul_f32_e32 v79, v84, v81
	v_rcp_f32_e32 v81, v78
	s_nop 0
	v_mul_f32_e32 v78, v73, v81
	v_pk_mul_f32 v[76:77], v[78:79], v[76:77]
	v_lshlrev_b32_e32 v78, 16, v230
	v_cvt_pk_bf16_f32 v73, v76, v77
	v_and_b32_e32 v79, 0xffff0000, v230
	v_rcp_f32_e32 v82, v75
	v_lshlrev_b32_e32 v80, 16, v234
	v_and_b32_e32 v81, 0xffff0000, v234
	v_mul_f32_e32 v76, 0xbfb8aa3b, v80
	v_mov_b32_e32 v75, v82
	v_rcp_f32_e32 v82, v74
	v_exp_f32_e32 v76, v76
	v_mov_b32_e32 v74, v82
	v_mul_f32_e32 v77, 0xbfb8aa3b, v81
	v_exp_f32_e32 v77, v77
	v_pk_mul_f32 v[74:75], v[74:75], v[78:79]
	v_pk_add_f32 v[76:77], v[76:77], 1.0 op_sel_hi:[1,0]
	s_nop 0
	v_rcp_f32_e32 v79, v77
	s_nop 0
	v_mul_f32_e32 v77, v81, v79
	v_rcp_f32_e32 v79, v76
	s_nop 0
	v_mul_f32_e32 v76, v80, v79
	v_pk_mul_f32 v[74:75], v[76:77], v[74:75]
	v_lshlrev_b32_e32 v80, 16, v231
	v_cvt_pk_bf16_f32 v74, v74, v75
	v_mul_f32_e32 v75, 0xbfb8aa3b, v94
	v_exp_f32_e32 v76, v75
	v_mul_f32_e32 v75, 0xbfb8aa3b, v95
	v_exp_f32_e32 v77, v75
	v_and_b32_e32 v81, 0xffff0000, v231
	v_lshlrev_b32_e32 v75, 16, v235
	v_and_b32_e32 v82, 0xffff0000, v235
	v_pk_add_f32 v[76:77], v[76:77], 1.0 op_sel_hi:[1,0]
	v_mul_f32_e32 v78, 0xbfb8aa3b, v75
	v_rcp_f32_e32 v83, v77
	v_exp_f32_e32 v78, v78
	v_mov_b32_e32 v77, v83
	v_rcp_f32_e32 v83, v76
	s_nop 0
	v_mov_b32_e32 v76, v83
	v_mul_f32_e32 v79, 0xbfb8aa3b, v82
	v_exp_f32_e32 v79, v79
	v_pk_mul_f32 v[76:77], v[76:77], v[80:81]
	v_pk_add_f32 v[78:79], v[78:79], 1.0 op_sel_hi:[1,0]
	s_nop 0
	v_rcp_f32_e32 v81, v79
	s_nop 0
	v_mul_f32_e32 v79, v82, v81
	v_rcp_f32_e32 v81, v78
	s_nop 0
	v_mul_f32_e32 v78, v75, v81
	v_pk_mul_f32 v[76:77], v[78:79], v[76:77]
	s_nop 0
	v_cvt_pk_bf16_f32 v75, v76, v77
	global_store_dwordx4 v[250:251], v[72:75], off
	s_nop 1
	v_add_u32_e32 v212, 0x80, v154
	v_mad_i64_i32 v[212:213], s[0:1], v212, s14, v[144:145]
	v_lshl_add_u64 v[214:215], v[212:213], 0, v[146:147]
	v_add_co_u32_e32 v246, vcc, s15, v214
	s_nop 1
	v_addc_co_u32_e32 v247, vcc, 0, v215, vcc
	global_load_dwordx4 v[228:231], v[246:247], off
	global_load_dwordx4 v[232:235], v[214:215], off
	global_load_dwordx4 v[236:239], v[142:143], off offset:16
	global_load_dwordx4 v[240:243], v[142:143], off
	s_waitcnt vmcnt(5)
	v_pk_add_f32 v[84:85], v[68:69], v[208:209]
	v_pk_add_f32 v[68:69], v[66:67], v[186:187]
	v_pk_add_f32 v[66:67], v[64:65], v[184:185]
	v_mul_f32_e32 v64, 0xbfb8aa3b, v84
	v_mul_f32_e32 v65, 0xbfb8aa3b, v85
	v_exp_f32_e32 v64, v64
	v_exp_f32_e32 v65, v65
	v_lshlrev_b32_e32 v82, 16, v176
	v_and_b32_e32 v83, 0xffff0000, v176
	v_pk_add_f32 v[70:71], v[70:71], v[210:211]
	v_pk_add_f32 v[64:65], v[64:65], 1.0 op_sel_hi:[1,0]
	v_lshlrev_b32_e32 v84, 16, v180
	v_rcp_f32_e32 v81, v65
	v_and_b32_e32 v76, 0xffff0000, v180
	v_mul_f32_e32 v80, 0xbfb8aa3b, v84
	v_exp_f32_e32 v80, v80
	v_mov_b32_e32 v65, v81
	v_rcp_f32_e32 v81, v64
	v_mul_f32_e32 v66, 0xbfb8aa3b, v66
	v_mul_f32_e32 v67, 0xbfb8aa3b, v67
	v_exp_f32_e32 v66, v66
	v_mov_b32_e32 v64, v81
	v_mul_f32_e32 v72, 0xbfb8aa3b, v76
	v_exp_f32_e32 v81, v72
	v_pk_mul_f32 v[64:65], v[64:65], v[82:83]
	v_exp_f32_e32 v67, v67
	v_pk_add_f32 v[80:81], v[80:81], 1.0 op_sel_hi:[1,0]
	s_nop 0
	v_rcp_f32_e32 v82, v81
	v_pk_add_f32 v[66:67], v[66:67], 1.0 op_sel_hi:[1,0]
	v_mul_f32_e32 v81, v76, v82
	v_rcp_f32_e32 v76, v80
	s_nop 0
	v_mul_f32_e32 v80, v84, v76
	v_pk_mul_f32 v[64:65], v[80:81], v[64:65]
	v_and_b32_e32 v80, 0xffff0000, v181
	v_cvt_pk_bf16_f32 v64, v64, v65
	v_mul_f32_e32 v65, 0xbfb8aa3b, v70
	v_exp_f32_e32 v70, v65
	v_mul_f32_e32 v65, 0xbfb8aa3b, v71
	v_exp_f32_e32 v71, v65
	v_lshlrev_b32_e32 v65, 16, v181
	v_lshlrev_b32_e32 v76, 16, v177
	v_and_b32_e32 v77, 0xffff0000, v177
	v_pk_add_f32 v[70:71], v[70:71], 1.0 op_sel_hi:[1,0]
	v_mul_f32_e32 v72, 0xbfb8aa3b, v65
	v_rcp_f32_e32 v81, v71
	v_exp_f32_e32 v72, v72
	v_mov_b32_e32 v71, v81
	v_rcp_f32_e32 v81, v70
	s_nop 0
	v_mov_b32_e32 v70, v81
	v_mul_f32_e32 v73, 0xbfb8aa3b, v80
	v_exp_f32_e32 v73, v73
	v_pk_mul_f32 v[70:71], v[70:71], v[76:77]
	v_pk_add_f32 v[72:73], v[72:73], 1.0 op_sel_hi:[1,0]
	s_nop 0
	v_rcp_f32_e32 v77, v73
	s_nop 0
	v_mul_f32_e32 v73, v80, v77
	v_rcp_f32_e32 v77, v72
	s_nop 0
	v_mul_f32_e32 v72, v65, v77
	v_pk_mul_f32 v[70:71], v[72:73], v[70:71]
	v_lshlrev_b32_e32 v72, 16, v178
	v_cvt_pk_bf16_f32 v65, v70, v71
	v_and_b32_e32 v73, 0xffff0000, v178
	v_rcp_f32_e32 v74, v67
	v_lshlrev_b32_e32 v76, 16, v182
	v_and_b32_e32 v77, 0xffff0000, v182
	v_mul_f32_e32 v70, 0xbfb8aa3b, v76
	v_mov_b32_e32 v67, v74
	v_rcp_f32_e32 v74, v66
	v_exp_f32_e32 v70, v70
	v_mov_b32_e32 v66, v74
	v_mul_f32_e32 v71, 0xbfb8aa3b, v77
	v_exp_f32_e32 v71, v71
	v_pk_mul_f32 v[66:67], v[66:67], v[72:73]
	v_pk_add_f32 v[70:71], v[70:71], 1.0 op_sel_hi:[1,0]
	s_nop 0
	v_rcp_f32_e32 v73, v71
	s_nop 0
	v_mul_f32_e32 v71, v77, v73
	v_rcp_f32_e32 v73, v70
	s_nop 0
	v_mul_f32_e32 v70, v76, v73
	v_pk_mul_f32 v[66:67], v[70:71], v[66:67]
	v_lshlrev_b32_e32 v72, 16, v179
	v_cvt_pk_bf16_f32 v66, v66, v67
	v_mul_f32_e32 v67, 0xbfb8aa3b, v68
	v_exp_f32_e32 v68, v67
	v_mul_f32_e32 v67, 0xbfb8aa3b, v69
	v_exp_f32_e32 v69, v67
	v_and_b32_e32 v73, 0xffff0000, v179
	v_lshlrev_b32_e32 v67, 16, v183
	v_and_b32_e32 v74, 0xffff0000, v183
	v_pk_add_f32 v[68:69], v[68:69], 1.0 op_sel_hi:[1,0]
	v_mul_f32_e32 v70, 0xbfb8aa3b, v67
	v_rcp_f32_e32 v75, v69
	v_exp_f32_e32 v70, v70
	v_mov_b32_e32 v69, v75
	v_rcp_f32_e32 v75, v68
	s_nop 0
	v_mov_b32_e32 v68, v75
	v_mul_f32_e32 v71, 0xbfb8aa3b, v74
	v_exp_f32_e32 v71, v71
	v_pk_mul_f32 v[68:69], v[68:69], v[72:73]
	v_pk_add_f32 v[70:71], v[70:71], 1.0 op_sel_hi:[1,0]
	s_nop 0
	v_rcp_f32_e32 v73, v71
	s_nop 0
	v_mul_f32_e32 v71, v74, v73
	v_rcp_f32_e32 v73, v70
	s_nop 0
	v_mul_f32_e32 v72, v67, v73
	v_mov_b32_e32 v70, v72
	v_pk_mul_f32 v[68:69], v[70:71], v[68:69]
	s_nop 0
	v_cvt_pk_bf16_f32 v67, v68, v69
	global_store_dwordx4 v[250:251], v[64:67], off offset:256
	global_load_dwordx4 v[176:179], v[246:247], off offset:256
	global_load_dwordx4 v[180:183], v[214:215], off offset:256
	global_load_dwordx4 v[184:187], v[142:143], off offset:528
	global_load_dwordx4 v[208:211], v[142:143], off offset:512
	s_waitcnt vmcnt(5)
	v_pk_add_f32 v[78:79], v[58:59], v[238:239]
	v_pk_add_f32 v[60:61], v[60:61], v[240:241]
	v_pk_add_f32 v[58:59], v[56:57], v[236:237]
	v_mul_f32_e32 v56, 0xbfb8aa3b, v60
	v_mul_f32_e32 v57, 0xbfb8aa3b, v61
	v_exp_f32_e32 v56, v56
	v_exp_f32_e32 v57, v57
	v_lshlrev_b32_e32 v76, 16, v228
	v_and_b32_e32 v77, 0xffff0000, v228
	v_pk_add_f32 v[62:63], v[62:63], v[242:243]
	v_pk_add_f32 v[56:57], v[56:57], 1.0 op_sel_hi:[1,0]
	v_lshlrev_b32_e32 v80, 16, v232
	v_rcp_f32_e32 v64, v57
	v_and_b32_e32 v68, 0xffff0000, v232
	v_mul_f32_e32 v60, 0xbfb8aa3b, v80
	v_exp_f32_e32 v60, v60
	v_mov_b32_e32 v57, v64
	v_rcp_f32_e32 v64, v56
	v_mul_f32_e32 v58, 0xbfb8aa3b, v58
	v_mul_f32_e32 v59, 0xbfb8aa3b, v59
	v_exp_f32_e32 v58, v58
	v_mov_b32_e32 v56, v64
	v_mul_f32_e32 v61, 0xbfb8aa3b, v68
	v_exp_f32_e32 v61, v61
	v_pk_mul_f32 v[56:57], v[56:57], v[76:77]
	v_exp_f32_e32 v59, v59
	v_pk_add_f32 v[60:61], v[60:61], 1.0 op_sel_hi:[1,0]
	s_nop 0
	v_rcp_f32_e32 v76, v61
	v_pk_add_f32 v[58:59], v[58:59], 1.0 op_sel_hi:[1,0]
	v_mul_f32_e32 v61, v68, v76
	v_rcp_f32_e32 v68, v60
	s_nop 0
	v_mul_f32_e32 v60, v80, v68
	v_pk_mul_f32 v[56:57], v[60:61], v[56:57]
	v_and_b32_e32 v68, 0xffff0000, v233
	v_cvt_pk_bf16_f32 v56, v56, v57
	v_mul_f32_e32 v57, 0xbfb8aa3b, v62
	v_exp_f32_e32 v60, v57
	v_mul_f32_e32 v57, 0xbfb8aa3b, v63
	v_exp_f32_e32 v61, v57
	v_lshlrev_b32_e32 v57, 16, v233
	v_mul_f32_e32 v62, 0xbfb8aa3b, v57
	v_exp_f32_e32 v62, v62
	v_pk_add_f32 v[60:61], v[60:61], 1.0 op_sel_hi:[1,0]
	v_lshlrev_b32_e32 v64, 16, v229
	v_rcp_f32_e32 v69, v61
	v_and_b32_e32 v65, 0xffff0000, v229
	v_mov_b32_e32 v61, v69
	v_rcp_f32_e32 v69, v60
	s_nop 0
	v_mov_b32_e32 v60, v69
	v_mul_f32_e32 v63, 0xbfb8aa3b, v68
	v_exp_f32_e32 v63, v63
	v_pk_mul_f32 v[60:61], v[60:61], v[64:65]
	v_pk_add_f32 v[62:63], v[62:63], 1.0 op_sel_hi:[1,0]
	s_nop 0
	v_rcp_f32_e32 v65, v63
	s_nop 0
	v_mul_f32_e32 v63, v68, v65
	v_rcp_f32_e32 v65, v62
	s_nop 0
	v_mul_f32_e32 v62, v57, v65
	v_pk_mul_f32 v[60:61], v[62:63], v[60:61]
	v_lshlrev_b32_e32 v62, 16, v230
	v_cvt_pk_bf16_f32 v57, v60, v61
	v_and_b32_e32 v63, 0xffff0000, v230
	v_rcp_f32_e32 v66, v59
	v_lshlrev_b32_e32 v64, 16, v234
	v_and_b32_e32 v65, 0xffff0000, v234
	v_mul_f32_e32 v60, 0xbfb8aa3b, v64
	v_mov_b32_e32 v59, v66
	v_rcp_f32_e32 v66, v58
	v_exp_f32_e32 v60, v60
	v_mov_b32_e32 v58, v66
	v_mul_f32_e32 v61, 0xbfb8aa3b, v65
	v_exp_f32_e32 v61, v61
	v_pk_mul_f32 v[58:59], v[58:59], v[62:63]
	v_pk_add_f32 v[60:61], v[60:61], 1.0 op_sel_hi:[1,0]
	s_nop 0
	v_rcp_f32_e32 v63, v61
	s_nop 0
	v_mul_f32_e32 v61, v65, v63
	v_rcp_f32_e32 v63, v60
	s_nop 0
	v_mul_f32_e32 v60, v64, v63
	v_pk_mul_f32 v[58:59], v[60:61], v[58:59]
	v_lshlrev_b32_e32 v64, 16, v231
	v_cvt_pk_bf16_f32 v58, v58, v59
	v_mul_f32_e32 v59, 0xbfb8aa3b, v78
	v_exp_f32_e32 v60, v59
	v_mul_f32_e32 v59, 0xbfb8aa3b, v79
	v_exp_f32_e32 v61, v59
	v_and_b32_e32 v65, 0xffff0000, v231
	v_lshlrev_b32_e32 v59, 16, v235
	v_and_b32_e32 v66, 0xffff0000, v235
	v_pk_add_f32 v[60:61], v[60:61], 1.0 op_sel_hi:[1,0]
	v_mul_f32_e32 v62, 0xbfb8aa3b, v59
	v_rcp_f32_e32 v67, v61
	v_exp_f32_e32 v62, v62
	v_mov_b32_e32 v61, v67
	v_rcp_f32_e32 v67, v60
	s_nop 0
	v_mov_b32_e32 v60, v67
	v_mul_f32_e32 v63, 0xbfb8aa3b, v66
	v_exp_f32_e32 v63, v63
	v_pk_mul_f32 v[60:61], v[60:61], v[64:65]
	v_pk_add_f32 v[62:63], v[62:63], 1.0 op_sel_hi:[1,0]
	s_nop 0
	v_rcp_f32_e32 v65, v63
	s_nop 0
	v_mul_f32_e32 v63, v66, v65
	v_rcp_f32_e32 v65, v62
	s_nop 0
	v_mul_f32_e32 v62, v59, v65
	v_pk_mul_f32 v[60:61], v[62:63], v[60:61]
	s_nop 0
	v_cvt_pk_bf16_f32 v59, v60, v61
	global_store_dwordx4 v[214:215], v[56:59], off
	s_nop 1
	v_add_u32_e32 v248, 0x90, v154
	v_mad_i64_i32 v[248:249], s[0:1], v248, s14, v[144:145]
	v_lshl_add_u64 v[250:251], v[248:249], 0, v[146:147]
	v_add_co_u32_e32 v174, vcc, s15, v250
	s_nop 1
	v_addc_co_u32_e32 v175, vcc, 0, v251, vcc
	global_load_dwordx4 v[228:231], v[174:175], off
	global_load_dwordx4 v[232:235], v[250:251], off
	global_load_dwordx4 v[236:239], v[142:143], off offset:16
	global_load_dwordx4 v[240:243], v[142:143], off
	s_waitcnt vmcnt(5)
	v_pk_add_f32 v[68:69], v[52:53], v[208:209]
	v_pk_add_f32 v[52:53], v[50:51], v[186:187]
	v_pk_add_f32 v[50:51], v[48:49], v[184:185]
	v_mul_f32_e32 v48, 0xbfb8aa3b, v68
	v_mul_f32_e32 v49, 0xbfb8aa3b, v69
	v_exp_f32_e32 v48, v48
	v_exp_f32_e32 v49, v49
	v_lshlrev_b32_e32 v66, 16, v176
	v_and_b32_e32 v67, 0xffff0000, v176
	v_pk_add_f32 v[54:55], v[54:55], v[210:211]
	v_pk_add_f32 v[48:49], v[48:49], 1.0 op_sel_hi:[1,0]
	v_lshlrev_b32_e32 v68, 16, v180
	v_rcp_f32_e32 v65, v49
	v_and_b32_e32 v60, 0xffff0000, v180
	v_mul_f32_e32 v64, 0xbfb8aa3b, v68
	v_exp_f32_e32 v64, v64
	v_mov_b32_e32 v49, v65
	v_rcp_f32_e32 v65, v48
	v_mul_f32_e32 v50, 0xbfb8aa3b, v50
	v_mul_f32_e32 v51, 0xbfb8aa3b, v51
	v_exp_f32_e32 v50, v50
	v_mov_b32_e32 v48, v65
	v_mul_f32_e32 v56, 0xbfb8aa3b, v60
	v_exp_f32_e32 v65, v56
	v_pk_mul_f32 v[48:49], v[48:49], v[66:67]
	v_exp_f32_e32 v51, v51
	v_pk_add_f32 v[64:65], v[64:65], 1.0 op_sel_hi:[1,0]
	s_nop 0
	v_rcp_f32_e32 v66, v65
	v_pk_add_f32 v[50:51], v[50:51], 1.0 op_sel_hi:[1,0]
	v_mul_f32_e32 v65, v60, v66
	v_rcp_f32_e32 v60, v64
	s_nop 0
	v_mul_f32_e32 v64, v68, v60
	v_pk_mul_f32 v[48:49], v[64:65], v[48:49]
	v_and_b32_e32 v64, 0xffff0000, v181
	v_cvt_pk_bf16_f32 v48, v48, v49
	v_mul_f32_e32 v49, 0xbfb8aa3b, v54
	v_exp_f32_e32 v54, v49
	v_mul_f32_e32 v49, 0xbfb8aa3b, v55
	v_exp_f32_e32 v55, v49
	v_lshlrev_b32_e32 v49, 16, v181
	v_lshlrev_b32_e32 v60, 16, v177
	v_and_b32_e32 v61, 0xffff0000, v177
	v_pk_add_f32 v[54:55], v[54:55], 1.0 op_sel_hi:[1,0]
	v_mul_f32_e32 v56, 0xbfb8aa3b, v49
	v_rcp_f32_e32 v65, v55
	v_exp_f32_e32 v56, v56
	v_mov_b32_e32 v55, v65
	v_rcp_f32_e32 v65, v54
	s_nop 0
	v_mov_b32_e32 v54, v65
	v_mul_f32_e32 v57, 0xbfb8aa3b, v64
	v_exp_f32_e32 v57, v57
	v_pk_mul_f32 v[54:55], v[54:55], v[60:61]
	v_pk_add_f32 v[56:57], v[56:57], 1.0 op_sel_hi:[1,0]
	s_nop 0
	v_rcp_f32_e32 v61, v57
	s_nop 0
	v_mul_f32_e32 v57, v64, v61
	v_rcp_f32_e32 v61, v56
	s_nop 0
	v_mul_f32_e32 v56, v49, v61
	v_pk_mul_f32 v[54:55], v[56:57], v[54:55]
	v_lshlrev_b32_e32 v56, 16, v178
	v_cvt_pk_bf16_f32 v49, v54, v55
	v_and_b32_e32 v57, 0xffff0000, v178
	v_rcp_f32_e32 v58, v51
	v_lshlrev_b32_e32 v60, 16, v182
	v_and_b32_e32 v61, 0xffff0000, v182
	v_mul_f32_e32 v54, 0xbfb8aa3b, v60
	v_mov_b32_e32 v51, v58
	v_rcp_f32_e32 v58, v50
	v_exp_f32_e32 v54, v54
	v_mov_b32_e32 v50, v58
	v_mul_f32_e32 v55, 0xbfb8aa3b, v61
	v_exp_f32_e32 v55, v55
	v_pk_mul_f32 v[50:51], v[50:51], v[56:57]
	v_pk_add_f32 v[54:55], v[54:55], 1.0 op_sel_hi:[1,0]
	s_nop 0
	v_rcp_f32_e32 v57, v55
	s_nop 0
	v_mul_f32_e32 v55, v61, v57
	v_rcp_f32_e32 v57, v54
	s_nop 0
	v_mul_f32_e32 v54, v60, v57
	v_pk_mul_f32 v[50:51], v[54:55], v[50:51]
	v_lshlrev_b32_e32 v56, 16, v179
	v_cvt_pk_bf16_f32 v50, v50, v51
	v_mul_f32_e32 v51, 0xbfb8aa3b, v52
	v_exp_f32_e32 v52, v51
	v_mul_f32_e32 v51, 0xbfb8aa3b, v53
	v_exp_f32_e32 v53, v51
	v_and_b32_e32 v57, 0xffff0000, v179
	v_lshlrev_b32_e32 v51, 16, v183
	v_and_b32_e32 v58, 0xffff0000, v183
	v_pk_add_f32 v[52:53], v[52:53], 1.0 op_sel_hi:[1,0]
	v_mul_f32_e32 v54, 0xbfb8aa3b, v51
	v_rcp_f32_e32 v59, v53
	v_exp_f32_e32 v54, v54
	v_mov_b32_e32 v53, v59
	v_rcp_f32_e32 v59, v52
	s_nop 0
	v_mov_b32_e32 v52, v59
	v_mul_f32_e32 v55, 0xbfb8aa3b, v58
	v_exp_f32_e32 v55, v55
	v_pk_mul_f32 v[52:53], v[52:53], v[56:57]
	v_pk_add_f32 v[54:55], v[54:55], 1.0 op_sel_hi:[1,0]
	s_nop 0
	v_rcp_f32_e32 v57, v55
	s_nop 0
	v_mul_f32_e32 v55, v58, v57
	v_rcp_f32_e32 v57, v54
	s_nop 0
	v_mul_f32_e32 v56, v51, v57
	v_mov_b32_e32 v54, v56
	v_pk_mul_f32 v[52:53], v[54:55], v[52:53]
	s_nop 0
	v_cvt_pk_bf16_f32 v51, v52, v53
	global_store_dwordx4 v[214:215], v[48:51], off offset:256
	global_load_dwordx4 v[176:179], v[174:175], off offset:256
	global_load_dwordx4 v[180:183], v[250:251], off offset:256
	global_load_dwordx4 v[184:187], v[142:143], off offset:528
	global_load_dwordx4 v[208:211], v[142:143], off offset:512
	s_waitcnt vmcnt(5)
	v_pk_add_f32 v[62:63], v[42:43], v[238:239]
	v_pk_add_f32 v[44:45], v[44:45], v[240:241]
	v_pk_add_f32 v[42:43], v[40:41], v[236:237]
	v_mul_f32_e32 v40, 0xbfb8aa3b, v44
	v_mul_f32_e32 v41, 0xbfb8aa3b, v45
	v_exp_f32_e32 v40, v40
	v_exp_f32_e32 v41, v41
	v_lshlrev_b32_e32 v60, 16, v228
	v_and_b32_e32 v61, 0xffff0000, v228
	v_pk_add_f32 v[46:47], v[46:47], v[242:243]
	v_pk_add_f32 v[40:41], v[40:41], 1.0 op_sel_hi:[1,0]
	v_lshlrev_b32_e32 v64, 16, v232
	v_rcp_f32_e32 v48, v41
	v_and_b32_e32 v52, 0xffff0000, v232
	v_mul_f32_e32 v44, 0xbfb8aa3b, v64
	v_exp_f32_e32 v44, v44
	v_mov_b32_e32 v41, v48
	v_rcp_f32_e32 v48, v40
	v_mul_f32_e32 v42, 0xbfb8aa3b, v42
	v_mul_f32_e32 v43, 0xbfb8aa3b, v43
	v_exp_f32_e32 v42, v42
	v_mov_b32_e32 v40, v48
	v_mul_f32_e32 v45, 0xbfb8aa3b, v52
	v_exp_f32_e32 v45, v45
	v_pk_mul_f32 v[40:41], v[40:41], v[60:61]
	v_exp_f32_e32 v43, v43
	v_pk_add_f32 v[44:45], v[44:45], 1.0 op_sel_hi:[1,0]
	s_nop 0
	v_rcp_f32_e32 v60, v45
	v_pk_add_f32 v[42:43], v[42:43], 1.0 op_sel_hi:[1,0]
	v_mul_f32_e32 v45, v52, v60
	v_rcp_f32_e32 v52, v44
	s_nop 0
	v_mul_f32_e32 v44, v64, v52
	v_pk_mul_f32 v[40:41], v[44:45], v[40:41]
	v_and_b32_e32 v52, 0xffff0000, v233
	v_cvt_pk_bf16_f32 v40, v40, v41
	v_mul_f32_e32 v41, 0xbfb8aa3b, v46
	v_exp_f32_e32 v44, v41
	v_mul_f32_e32 v41, 0xbfb8aa3b, v47
	v_exp_f32_e32 v45, v41
	v_lshlrev_b32_e32 v41, 16, v233
	v_mul_f32_e32 v46, 0xbfb8aa3b, v41
	v_exp_f32_e32 v46, v46
	v_pk_add_f32 v[44:45], v[44:45], 1.0 op_sel_hi:[1,0]
	v_lshlrev_b32_e32 v48, 16, v229
	v_rcp_f32_e32 v53, v45
	v_and_b32_e32 v49, 0xffff0000, v229
	v_mov_b32_e32 v45, v53
	v_rcp_f32_e32 v53, v44
	s_nop 0
	v_mov_b32_e32 v44, v53
	v_mul_f32_e32 v47, 0xbfb8aa3b, v52
	v_exp_f32_e32 v47, v47
	v_pk_mul_f32 v[44:45], v[44:45], v[48:49]
	v_pk_add_f32 v[46:47], v[46:47], 1.0 op_sel_hi:[1,0]
	s_nop 0
	v_rcp_f32_e32 v49, v47
	s_nop 0
	v_mul_f32_e32 v47, v52, v49
	v_rcp_f32_e32 v49, v46
	s_nop 0
	v_mul_f32_e32 v46, v41, v49
	v_pk_mul_f32 v[44:45], v[46:47], v[44:45]
	v_lshlrev_b32_e32 v46, 16, v230
	v_cvt_pk_bf16_f32 v41, v44, v45
	v_and_b32_e32 v47, 0xffff0000, v230
	v_rcp_f32_e32 v50, v43
	v_lshlrev_b32_e32 v48, 16, v234
	v_and_b32_e32 v49, 0xffff0000, v234
	v_mul_f32_e32 v44, 0xbfb8aa3b, v48
	v_mov_b32_e32 v43, v50
	v_rcp_f32_e32 v50, v42
	v_exp_f32_e32 v44, v44
	v_mov_b32_e32 v42, v50
	v_mul_f32_e32 v45, 0xbfb8aa3b, v49
	v_exp_f32_e32 v45, v45
	v_pk_mul_f32 v[42:43], v[42:43], v[46:47]
	v_pk_add_f32 v[44:45], v[44:45], 1.0 op_sel_hi:[1,0]
	s_nop 0
	v_rcp_f32_e32 v47, v45
	s_nop 0
	v_mul_f32_e32 v45, v49, v47
	v_rcp_f32_e32 v47, v44
	s_nop 0
	v_mul_f32_e32 v44, v48, v47
	v_pk_mul_f32 v[42:43], v[44:45], v[42:43]
	v_lshlrev_b32_e32 v48, 16, v231
	v_cvt_pk_bf16_f32 v42, v42, v43
	v_mul_f32_e32 v43, 0xbfb8aa3b, v62
	v_exp_f32_e32 v44, v43
	v_mul_f32_e32 v43, 0xbfb8aa3b, v63
	v_exp_f32_e32 v45, v43
	v_and_b32_e32 v49, 0xffff0000, v231
	v_lshlrev_b32_e32 v43, 16, v235
	v_and_b32_e32 v50, 0xffff0000, v235
	v_pk_add_f32 v[44:45], v[44:45], 1.0 op_sel_hi:[1,0]
	v_mul_f32_e32 v46, 0xbfb8aa3b, v43
	v_rcp_f32_e32 v51, v45
	v_exp_f32_e32 v46, v46
	v_mov_b32_e32 v45, v51
	v_rcp_f32_e32 v51, v44
	s_nop 0
	v_mov_b32_e32 v44, v51
	v_mul_f32_e32 v47, 0xbfb8aa3b, v50
	v_exp_f32_e32 v47, v47
	v_pk_mul_f32 v[44:45], v[44:45], v[48:49]
	v_pk_add_f32 v[46:47], v[46:47], 1.0 op_sel_hi:[1,0]
	s_nop 0
	v_rcp_f32_e32 v49, v47
	s_nop 0
	v_mul_f32_e32 v47, v50, v49
	v_rcp_f32_e32 v49, v46
	s_nop 0
	v_mul_f32_e32 v46, v43, v49
	v_pk_mul_f32 v[44:45], v[46:47], v[44:45]
	s_nop 0
	v_cvt_pk_bf16_f32 v43, v44, v45
	global_store_dwordx4 v[250:251], v[40:43], off
	s_nop 1
	v_add_u32_e32 v212, 0xa0, v154
	v_mad_i64_i32 v[212:213], s[0:1], v212, s14, v[144:145]
	v_lshl_add_u64 v[214:215], v[212:213], 0, v[146:147]
	v_add_co_u32_e32 v246, vcc, s15, v214
	s_nop 1
	v_addc_co_u32_e32 v247, vcc, 0, v215, vcc
	global_load_dwordx4 v[228:231], v[246:247], off
	global_load_dwordx4 v[232:235], v[214:215], off
	global_load_dwordx4 v[236:239], v[142:143], off offset:16
	global_load_dwordx4 v[240:243], v[142:143], off
	s_waitcnt vmcnt(5)
	v_pk_add_f32 v[52:53], v[36:37], v[208:209]
	v_pk_add_f32 v[36:37], v[34:35], v[186:187]
	v_pk_add_f32 v[34:35], v[32:33], v[184:185]
	v_mul_f32_e32 v32, 0xbfb8aa3b, v52
	v_mul_f32_e32 v33, 0xbfb8aa3b, v53
	v_exp_f32_e32 v32, v32
	v_exp_f32_e32 v33, v33
	v_lshlrev_b32_e32 v50, 16, v176
	v_and_b32_e32 v51, 0xffff0000, v176
	v_pk_add_f32 v[38:39], v[38:39], v[210:211]
	v_pk_add_f32 v[32:33], v[32:33], 1.0 op_sel_hi:[1,0]
	v_lshlrev_b32_e32 v52, 16, v180
	v_rcp_f32_e32 v49, v33
	v_and_b32_e32 v44, 0xffff0000, v180
	v_mul_f32_e32 v48, 0xbfb8aa3b, v52
	v_exp_f32_e32 v48, v48
	v_mov_b32_e32 v33, v49
	v_rcp_f32_e32 v49, v32
	v_mul_f32_e32 v34, 0xbfb8aa3b, v34
	v_mul_f32_e32 v35, 0xbfb8aa3b, v35
	v_exp_f32_e32 v34, v34
	v_mov_b32_e32 v32, v49
	v_mul_f32_e32 v40, 0xbfb8aa3b, v44
	v_exp_f32_e32 v49, v40
	v_pk_mul_f32 v[32:33], v[32:33], v[50:51]
	v_exp_f32_e32 v35, v35
	v_pk_add_f32 v[48:49], v[48:49], 1.0 op_sel_hi:[1,0]
	s_nop 0
	v_rcp_f32_e32 v50, v49
	v_pk_add_f32 v[34:35], v[34:35], 1.0 op_sel_hi:[1,0]
	v_mul_f32_e32 v49, v44, v50
	v_rcp_f32_e32 v44, v48
	s_nop 0
	v_mul_f32_e32 v48, v52, v44
	v_pk_mul_f32 v[32:33], v[48:49], v[32:33]
	v_and_b32_e32 v48, 0xffff0000, v181
	v_cvt_pk_bf16_f32 v32, v32, v33
	v_mul_f32_e32 v33, 0xbfb8aa3b, v38
	v_exp_f32_e32 v38, v33
	v_mul_f32_e32 v33, 0xbfb8aa3b, v39
	v_exp_f32_e32 v39, v33
	v_lshlrev_b32_e32 v33, 16, v181
	v_lshlrev_b32_e32 v44, 16, v177
	v_and_b32_e32 v45, 0xffff0000, v177
	v_pk_add_f32 v[38:39], v[38:39], 1.0 op_sel_hi:[1,0]
	v_mul_f32_e32 v40, 0xbfb8aa3b, v33
	v_rcp_f32_e32 v49, v39
	v_exp_f32_e32 v40, v40
	v_mov_b32_e32 v39, v49
	v_rcp_f32_e32 v49, v38
	s_nop 0
	v_mov_b32_e32 v38, v49
	v_mul_f32_e32 v41, 0xbfb8aa3b, v48
	v_exp_f32_e32 v41, v41
	v_pk_mul_f32 v[38:39], v[38:39], v[44:45]
	v_pk_add_f32 v[40:41], v[40:41], 1.0 op_sel_hi:[1,0]
	s_nop 0
	v_rcp_f32_e32 v45, v41
	s_nop 0
	v_mul_f32_e32 v41, v48, v45
	v_rcp_f32_e32 v45, v40
	s_nop 0
	v_mul_f32_e32 v40, v33, v45
	v_pk_mul_f32 v[38:39], v[40:41], v[38:39]
	v_lshlrev_b32_e32 v40, 16, v178
	v_cvt_pk_bf16_f32 v33, v38, v39
	v_and_b32_e32 v41, 0xffff0000, v178
	v_rcp_f32_e32 v42, v35
	v_lshlrev_b32_e32 v44, 16, v182
	v_and_b32_e32 v45, 0xffff0000, v182
	v_mul_f32_e32 v38, 0xbfb8aa3b, v44
	v_mov_b32_e32 v35, v42
	v_rcp_f32_e32 v42, v34
	v_exp_f32_e32 v38, v38
	v_mov_b32_e32 v34, v42
	v_mul_f32_e32 v39, 0xbfb8aa3b, v45
	v_exp_f32_e32 v39, v39
	v_pk_mul_f32 v[34:35], v[34:35], v[40:41]
	v_pk_add_f32 v[38:39], v[38:39], 1.0 op_sel_hi:[1,0]
	s_nop 0
	v_rcp_f32_e32 v41, v39
	s_nop 0
	v_mul_f32_e32 v39, v45, v41
	v_rcp_f32_e32 v41, v38
	s_nop 0
	v_mul_f32_e32 v38, v44, v41
	v_pk_mul_f32 v[34:35], v[38:39], v[34:35]
	v_lshlrev_b32_e32 v40, 16, v179
	v_cvt_pk_bf16_f32 v34, v34, v35
	v_mul_f32_e32 v35, 0xbfb8aa3b, v36
	v_exp_f32_e32 v36, v35
	v_mul_f32_e32 v35, 0xbfb8aa3b, v37
	v_exp_f32_e32 v37, v35
	v_and_b32_e32 v41, 0xffff0000, v179
	v_lshlrev_b32_e32 v35, 16, v183
	v_and_b32_e32 v42, 0xffff0000, v183
	v_pk_add_f32 v[36:37], v[36:37], 1.0 op_sel_hi:[1,0]
	v_mul_f32_e32 v38, 0xbfb8aa3b, v35
	v_rcp_f32_e32 v43, v37
	v_exp_f32_e32 v38, v38
	v_mov_b32_e32 v37, v43
	v_rcp_f32_e32 v43, v36
	s_nop 0
	v_mov_b32_e32 v36, v43
	v_mul_f32_e32 v39, 0xbfb8aa3b, v42
	v_exp_f32_e32 v39, v39
	v_pk_mul_f32 v[36:37], v[36:37], v[40:41]
	v_pk_add_f32 v[38:39], v[38:39], 1.0 op_sel_hi:[1,0]
	s_nop 0
	v_rcp_f32_e32 v41, v39
	s_nop 0
	v_mul_f32_e32 v39, v42, v41
	v_rcp_f32_e32 v41, v38
	s_nop 0
	v_mul_f32_e32 v40, v35, v41
	v_mov_b32_e32 v38, v40
	v_pk_mul_f32 v[36:37], v[38:39], v[36:37]
	s_nop 0
	v_cvt_pk_bf16_f32 v35, v36, v37
	global_store_dwordx4 v[250:251], v[32:35], off offset:256
	global_load_dwordx4 v[176:179], v[246:247], off offset:256
	global_load_dwordx4 v[180:183], v[214:215], off offset:256
	global_load_dwordx4 v[184:187], v[142:143], off offset:528
	global_load_dwordx4 v[208:211], v[142:143], off offset:512
	s_waitcnt vmcnt(5)
	v_pk_add_f32 v[46:47], v[26:27], v[238:239]
	v_pk_add_f32 v[28:29], v[28:29], v[240:241]
	v_pk_add_f32 v[26:27], v[24:25], v[236:237]
	v_mul_f32_e32 v24, 0xbfb8aa3b, v28
	v_mul_f32_e32 v25, 0xbfb8aa3b, v29
	v_exp_f32_e32 v24, v24
	v_exp_f32_e32 v25, v25
	v_lshlrev_b32_e32 v44, 16, v228
	v_and_b32_e32 v45, 0xffff0000, v228
	v_pk_add_f32 v[30:31], v[30:31], v[242:243]
	v_pk_add_f32 v[24:25], v[24:25], 1.0 op_sel_hi:[1,0]
	v_lshlrev_b32_e32 v48, 16, v232
	v_rcp_f32_e32 v32, v25
	v_and_b32_e32 v36, 0xffff0000, v232
	v_mul_f32_e32 v28, 0xbfb8aa3b, v48
	v_exp_f32_e32 v28, v28
	v_mov_b32_e32 v25, v32
	v_rcp_f32_e32 v32, v24
	v_mul_f32_e32 v26, 0xbfb8aa3b, v26
	v_mul_f32_e32 v27, 0xbfb8aa3b, v27
	v_exp_f32_e32 v26, v26
	v_mov_b32_e32 v24, v32
	v_mul_f32_e32 v29, 0xbfb8aa3b, v36
	v_exp_f32_e32 v29, v29
	v_pk_mul_f32 v[24:25], v[24:25], v[44:45]
	v_exp_f32_e32 v27, v27
	v_pk_add_f32 v[28:29], v[28:29], 1.0 op_sel_hi:[1,0]
	s_nop 0
	v_rcp_f32_e32 v44, v29
	v_pk_add_f32 v[26:27], v[26:27], 1.0 op_sel_hi:[1,0]
	v_mul_f32_e32 v29, v36, v44
	v_rcp_f32_e32 v36, v28
	s_nop 0
	v_mul_f32_e32 v28, v48, v36
	v_pk_mul_f32 v[24:25], v[28:29], v[24:25]
	v_and_b32_e32 v36, 0xffff0000, v233
	v_cvt_pk_bf16_f32 v24, v24, v25
	v_mul_f32_e32 v25, 0xbfb8aa3b, v30
	v_exp_f32_e32 v28, v25
	v_mul_f32_e32 v25, 0xbfb8aa3b, v31
	v_exp_f32_e32 v29, v25
	v_lshlrev_b32_e32 v25, 16, v233
	v_mul_f32_e32 v30, 0xbfb8aa3b, v25
	v_exp_f32_e32 v30, v30
	v_pk_add_f32 v[28:29], v[28:29], 1.0 op_sel_hi:[1,0]
	v_lshlrev_b32_e32 v32, 16, v229
	v_rcp_f32_e32 v37, v29
	v_and_b32_e32 v33, 0xffff0000, v229
	v_mov_b32_e32 v29, v37
	v_rcp_f32_e32 v37, v28
	s_nop 0
	v_mov_b32_e32 v28, v37
	v_mul_f32_e32 v31, 0xbfb8aa3b, v36
	v_exp_f32_e32 v31, v31
	v_pk_mul_f32 v[28:29], v[28:29], v[32:33]
	v_pk_add_f32 v[30:31], v[30:31], 1.0 op_sel_hi:[1,0]
	s_nop 0
	v_rcp_f32_e32 v33, v31
	s_nop 0
	v_mul_f32_e32 v31, v36, v33
	v_rcp_f32_e32 v33, v30
	s_nop 0
	v_mul_f32_e32 v30, v25, v33
	v_pk_mul_f32 v[28:29], v[30:31], v[28:29]
	v_lshlrev_b32_e32 v30, 16, v230
	v_cvt_pk_bf16_f32 v25, v28, v29
	v_and_b32_e32 v31, 0xffff0000, v230
	v_rcp_f32_e32 v34, v27
	v_lshlrev_b32_e32 v32, 16, v234
	v_and_b32_e32 v33, 0xffff0000, v234
	v_mul_f32_e32 v28, 0xbfb8aa3b, v32
	v_mov_b32_e32 v27, v34
	v_rcp_f32_e32 v34, v26
	v_exp_f32_e32 v28, v28
	v_mov_b32_e32 v26, v34
	v_mul_f32_e32 v29, 0xbfb8aa3b, v33
	v_exp_f32_e32 v29, v29
	v_pk_mul_f32 v[26:27], v[26:27], v[30:31]
	v_pk_add_f32 v[28:29], v[28:29], 1.0 op_sel_hi:[1,0]
	s_nop 0
	v_rcp_f32_e32 v31, v29
	s_nop 0
	v_mul_f32_e32 v29, v33, v31
	v_rcp_f32_e32 v31, v28
	s_nop 0
	v_mul_f32_e32 v28, v32, v31
	v_pk_mul_f32 v[26:27], v[28:29], v[26:27]
	v_lshlrev_b32_e32 v32, 16, v231
	v_cvt_pk_bf16_f32 v26, v26, v27
	v_mul_f32_e32 v27, 0xbfb8aa3b, v46
	v_exp_f32_e32 v28, v27
	v_mul_f32_e32 v27, 0xbfb8aa3b, v47
	v_exp_f32_e32 v29, v27
	v_and_b32_e32 v33, 0xffff0000, v231
	v_lshlrev_b32_e32 v27, 16, v235
	v_and_b32_e32 v34, 0xffff0000, v235
	v_pk_add_f32 v[28:29], v[28:29], 1.0 op_sel_hi:[1,0]
	v_mul_f32_e32 v30, 0xbfb8aa3b, v27
	v_rcp_f32_e32 v35, v29
	v_exp_f32_e32 v30, v30
	v_mov_b32_e32 v29, v35
	v_rcp_f32_e32 v35, v28
	s_nop 0
	v_mov_b32_e32 v28, v35
	v_mul_f32_e32 v31, 0xbfb8aa3b, v34
	v_exp_f32_e32 v31, v31
	v_pk_mul_f32 v[28:29], v[28:29], v[32:33]
	v_pk_add_f32 v[30:31], v[30:31], 1.0 op_sel_hi:[1,0]
	s_nop 0
	v_rcp_f32_e32 v33, v31
	s_nop 0
	v_mul_f32_e32 v31, v34, v33
	v_rcp_f32_e32 v33, v30
	s_nop 0
	v_mul_f32_e32 v30, v27, v33
	v_pk_mul_f32 v[28:29], v[30:31], v[28:29]
	s_nop 0
	v_cvt_pk_bf16_f32 v27, v28, v29
	global_store_dwordx4 v[214:215], v[24:27], off
	s_nop 1
	v_add_u32_e32 v248, 0xb0, v154
	v_mad_i64_i32 v[248:249], s[0:1], v248, s14, v[144:145]
	v_lshl_add_u64 v[250:251], v[248:249], 0, v[146:147]
	v_add_co_u32_e32 v174, vcc, s15, v250
	s_nop 1
	v_addc_co_u32_e32 v175, vcc, 0, v251, vcc
	global_load_dwordx4 v[228:231], v[174:175], off
	global_load_dwordx4 v[232:235], v[250:251], off
	global_load_dwordx4 v[236:239], v[142:143], off offset:16
	global_load_dwordx4 v[240:243], v[142:143], off
	s_waitcnt vmcnt(5)
	v_pk_add_f32 v[36:37], v[20:21], v[208:209]
	v_pk_add_f32 v[20:21], v[18:19], v[186:187]
	v_pk_add_f32 v[18:19], v[16:17], v[184:185]
	v_mul_f32_e32 v16, 0xbfb8aa3b, v36
	v_mul_f32_e32 v17, 0xbfb8aa3b, v37
	v_exp_f32_e32 v16, v16
	v_exp_f32_e32 v17, v17
	v_lshlrev_b32_e32 v34, 16, v176
	v_and_b32_e32 v35, 0xffff0000, v176
	v_pk_add_f32 v[22:23], v[22:23], v[210:211]
	v_pk_add_f32 v[16:17], v[16:17], 1.0 op_sel_hi:[1,0]
	v_lshlrev_b32_e32 v36, 16, v180
	v_rcp_f32_e32 v33, v17
	v_and_b32_e32 v28, 0xffff0000, v180
	v_mul_f32_e32 v32, 0xbfb8aa3b, v36
	v_exp_f32_e32 v32, v32
	v_mov_b32_e32 v17, v33
	v_rcp_f32_e32 v33, v16
	v_mul_f32_e32 v18, 0xbfb8aa3b, v18
	v_mul_f32_e32 v19, 0xbfb8aa3b, v19
	v_exp_f32_e32 v18, v18
	v_mov_b32_e32 v16, v33
	v_mul_f32_e32 v24, 0xbfb8aa3b, v28
	v_exp_f32_e32 v33, v24
	v_pk_mul_f32 v[16:17], v[16:17], v[34:35]
	v_exp_f32_e32 v19, v19
	v_pk_add_f32 v[32:33], v[32:33], 1.0 op_sel_hi:[1,0]
	s_nop 0
	v_rcp_f32_e32 v34, v33
	v_pk_add_f32 v[18:19], v[18:19], 1.0 op_sel_hi:[1,0]
	v_mul_f32_e32 v33, v28, v34
	v_rcp_f32_e32 v28, v32
	s_nop 0
	v_mul_f32_e32 v32, v36, v28
	v_pk_mul_f32 v[16:17], v[32:33], v[16:17]
	v_and_b32_e32 v32, 0xffff0000, v181
	v_cvt_pk_bf16_f32 v16, v16, v17
	v_mul_f32_e32 v17, 0xbfb8aa3b, v22
	v_exp_f32_e32 v22, v17
	v_mul_f32_e32 v17, 0xbfb8aa3b, v23
	v_exp_f32_e32 v23, v17
	v_lshlrev_b32_e32 v17, 16, v181
	v_lshlrev_b32_e32 v28, 16, v177
	v_and_b32_e32 v29, 0xffff0000, v177
	v_pk_add_f32 v[22:23], v[22:23], 1.0 op_sel_hi:[1,0]
	v_mul_f32_e32 v24, 0xbfb8aa3b, v17
	v_rcp_f32_e32 v33, v23
	v_exp_f32_e32 v24, v24
	v_mov_b32_e32 v23, v33
	v_rcp_f32_e32 v33, v22
	s_nop 0
	v_mov_b32_e32 v22, v33
	v_mul_f32_e32 v25, 0xbfb8aa3b, v32
	v_exp_f32_e32 v25, v25
	v_pk_mul_f32 v[22:23], v[22:23], v[28:29]
	v_pk_add_f32 v[24:25], v[24:25], 1.0 op_sel_hi:[1,0]
	s_nop 0
	v_rcp_f32_e32 v29, v25
	s_nop 0
	v_mul_f32_e32 v25, v32, v29
	v_rcp_f32_e32 v29, v24
	s_nop 0
	v_mul_f32_e32 v24, v17, v29
	v_pk_mul_f32 v[22:23], v[24:25], v[22:23]
	v_lshlrev_b32_e32 v24, 16, v178
	v_cvt_pk_bf16_f32 v17, v22, v23
	v_and_b32_e32 v25, 0xffff0000, v178
	v_rcp_f32_e32 v26, v19
	v_lshlrev_b32_e32 v28, 16, v182
	v_and_b32_e32 v29, 0xffff0000, v182
	v_mul_f32_e32 v22, 0xbfb8aa3b, v28
	v_mov_b32_e32 v19, v26
	v_rcp_f32_e32 v26, v18
	v_exp_f32_e32 v22, v22
	v_mov_b32_e32 v18, v26
	v_mul_f32_e32 v23, 0xbfb8aa3b, v29
	v_exp_f32_e32 v23, v23
	v_pk_mul_f32 v[18:19], v[18:19], v[24:25]
	v_pk_add_f32 v[22:23], v[22:23], 1.0 op_sel_hi:[1,0]
	s_nop 0
	v_rcp_f32_e32 v25, v23
	s_nop 0
	v_mul_f32_e32 v23, v29, v25
	v_rcp_f32_e32 v25, v22
	s_nop 0
	v_mul_f32_e32 v22, v28, v25
	v_pk_mul_f32 v[18:19], v[22:23], v[18:19]
	v_lshlrev_b32_e32 v24, 16, v179
	v_cvt_pk_bf16_f32 v18, v18, v19
	v_mul_f32_e32 v19, 0xbfb8aa3b, v20
	v_exp_f32_e32 v20, v19
	v_mul_f32_e32 v19, 0xbfb8aa3b, v21
	v_exp_f32_e32 v21, v19
	v_and_b32_e32 v25, 0xffff0000, v179
	v_lshlrev_b32_e32 v19, 16, v183
	v_and_b32_e32 v26, 0xffff0000, v183
	v_pk_add_f32 v[20:21], v[20:21], 1.0 op_sel_hi:[1,0]
	v_mul_f32_e32 v22, 0xbfb8aa3b, v19
	v_rcp_f32_e32 v27, v21
	v_exp_f32_e32 v22, v22
	v_mov_b32_e32 v21, v27
	v_rcp_f32_e32 v27, v20
	s_nop 0
	v_mov_b32_e32 v20, v27
	v_mul_f32_e32 v23, 0xbfb8aa3b, v26
	v_exp_f32_e32 v23, v23
	v_pk_mul_f32 v[20:21], v[20:21], v[24:25]
	v_pk_add_f32 v[22:23], v[22:23], 1.0 op_sel_hi:[1,0]
	s_nop 0
	v_rcp_f32_e32 v25, v23
	s_nop 0
	v_mul_f32_e32 v23, v26, v25
	v_rcp_f32_e32 v25, v22
	s_nop 0
	v_mul_f32_e32 v24, v19, v25
	v_mov_b32_e32 v22, v24
	v_pk_mul_f32 v[20:21], v[22:23], v[20:21]
	s_nop 0
	v_cvt_pk_bf16_f32 v19, v20, v21
	global_store_dwordx4 v[214:215], v[16:19], off offset:256
	global_load_dwordx4 v[176:179], v[174:175], off offset:256
	global_load_dwordx4 v[180:183], v[250:251], off offset:256
	global_load_dwordx4 v[184:187], v[142:143], off offset:528
	global_load_dwordx4 v[208:211], v[142:143], off offset:512
	s_waitcnt vmcnt(5)
	v_pk_add_f32 v[30:31], v[10:11], v[238:239]
	v_pk_add_f32 v[12:13], v[12:13], v[240:241]
	v_pk_add_f32 v[10:11], v[8:9], v[236:237]
	v_mul_f32_e32 v8, 0xbfb8aa3b, v12
	v_mul_f32_e32 v9, 0xbfb8aa3b, v13
	v_exp_f32_e32 v8, v8
	v_exp_f32_e32 v9, v9
	v_lshlrev_b32_e32 v28, 16, v228
	v_and_b32_e32 v29, 0xffff0000, v228
	v_pk_add_f32 v[14:15], v[14:15], v[242:243]
	v_pk_add_f32 v[8:9], v[8:9], 1.0 op_sel_hi:[1,0]
	v_lshlrev_b32_e32 v32, 16, v232
	v_rcp_f32_e32 v16, v9
	v_and_b32_e32 v20, 0xffff0000, v232
	v_mul_f32_e32 v12, 0xbfb8aa3b, v32
	v_exp_f32_e32 v12, v12
	v_mov_b32_e32 v9, v16
	v_rcp_f32_e32 v16, v8
	v_mul_f32_e32 v10, 0xbfb8aa3b, v10
	v_mul_f32_e32 v11, 0xbfb8aa3b, v11
	v_exp_f32_e32 v10, v10
	v_mov_b32_e32 v8, v16
	v_mul_f32_e32 v13, 0xbfb8aa3b, v20
	v_exp_f32_e32 v13, v13
	v_pk_mul_f32 v[8:9], v[8:9], v[28:29]
	v_exp_f32_e32 v11, v11
	v_pk_add_f32 v[12:13], v[12:13], 1.0 op_sel_hi:[1,0]
	s_nop 0
	v_rcp_f32_e32 v28, v13
	v_pk_add_f32 v[10:11], v[10:11], 1.0 op_sel_hi:[1,0]
	v_mul_f32_e32 v13, v20, v28
	v_rcp_f32_e32 v20, v12
	s_nop 0
	v_mul_f32_e32 v12, v32, v20
	v_pk_mul_f32 v[8:9], v[12:13], v[8:9]
	v_and_b32_e32 v20, 0xffff0000, v233
	v_cvt_pk_bf16_f32 v8, v8, v9
	v_mul_f32_e32 v9, 0xbfb8aa3b, v14
	v_exp_f32_e32 v12, v9
	v_mul_f32_e32 v9, 0xbfb8aa3b, v15
	v_exp_f32_e32 v13, v9
	v_lshlrev_b32_e32 v9, 16, v233
	v_mul_f32_e32 v14, 0xbfb8aa3b, v9
	v_exp_f32_e32 v14, v14
	v_pk_add_f32 v[12:13], v[12:13], 1.0 op_sel_hi:[1,0]
	v_lshlrev_b32_e32 v16, 16, v229
	v_rcp_f32_e32 v21, v13
	v_and_b32_e32 v17, 0xffff0000, v229
	v_mov_b32_e32 v13, v21
	v_rcp_f32_e32 v21, v12
	s_nop 0
	v_mov_b32_e32 v12, v21
	v_mul_f32_e32 v15, 0xbfb8aa3b, v20
	v_exp_f32_e32 v15, v15
	v_pk_mul_f32 v[12:13], v[12:13], v[16:17]
	v_pk_add_f32 v[14:15], v[14:15], 1.0 op_sel_hi:[1,0]
	s_nop 0
	v_rcp_f32_e32 v17, v15
	s_nop 0
	v_mul_f32_e32 v15, v20, v17
	v_rcp_f32_e32 v17, v14
	s_nop 0
	v_mul_f32_e32 v14, v9, v17
	v_pk_mul_f32 v[12:13], v[14:15], v[12:13]
	v_lshlrev_b32_e32 v14, 16, v230
	v_cvt_pk_bf16_f32 v9, v12, v13
	v_and_b32_e32 v15, 0xffff0000, v230
	v_rcp_f32_e32 v18, v11
	v_lshlrev_b32_e32 v16, 16, v234
	v_and_b32_e32 v17, 0xffff0000, v234
	v_mul_f32_e32 v12, 0xbfb8aa3b, v16
	v_mov_b32_e32 v11, v18
	v_rcp_f32_e32 v18, v10
	v_exp_f32_e32 v12, v12
	v_mov_b32_e32 v10, v18
	v_mul_f32_e32 v13, 0xbfb8aa3b, v17
	v_exp_f32_e32 v13, v13
	v_pk_mul_f32 v[10:11], v[10:11], v[14:15]
	v_pk_add_f32 v[12:13], v[12:13], 1.0 op_sel_hi:[1,0]
	s_nop 0
	v_rcp_f32_e32 v15, v13
	s_nop 0
	v_mul_f32_e32 v13, v17, v15
	v_rcp_f32_e32 v15, v12
	s_nop 0
	v_mul_f32_e32 v12, v16, v15
	v_pk_mul_f32 v[10:11], v[12:13], v[10:11]
	v_lshlrev_b32_e32 v16, 16, v231
	v_cvt_pk_bf16_f32 v10, v10, v11
	v_mul_f32_e32 v11, 0xbfb8aa3b, v30
	v_exp_f32_e32 v12, v11
	v_mul_f32_e32 v11, 0xbfb8aa3b, v31
	v_exp_f32_e32 v13, v11
	v_and_b32_e32 v17, 0xffff0000, v231
	v_lshlrev_b32_e32 v11, 16, v235
	v_and_b32_e32 v18, 0xffff0000, v235
	v_pk_add_f32 v[12:13], v[12:13], 1.0 op_sel_hi:[1,0]
	v_mul_f32_e32 v14, 0xbfb8aa3b, v11
	v_rcp_f32_e32 v19, v13
	v_exp_f32_e32 v14, v14
	v_mov_b32_e32 v13, v19
	v_rcp_f32_e32 v19, v12
	s_nop 0
	v_mov_b32_e32 v12, v19
	v_mul_f32_e32 v15, 0xbfb8aa3b, v18
	v_exp_f32_e32 v15, v15
	v_pk_mul_f32 v[12:13], v[12:13], v[16:17]
	v_pk_add_f32 v[14:15], v[14:15], 1.0 op_sel_hi:[1,0]
	s_nop 0
	v_rcp_f32_e32 v17, v15
	s_nop 0
	v_mul_f32_e32 v15, v18, v17
	v_rcp_f32_e32 v17, v14
	s_nop 0
	v_mul_f32_e32 v14, v11, v17
	v_pk_mul_f32 v[12:13], v[14:15], v[12:13]
	s_nop 0
	v_cvt_pk_bf16_f32 v11, v12, v13
	global_store_dwordx4 v[250:251], v[8:11], off
	s_waitcnt vmcnt(1)
	v_pk_add_f32 v[20:21], v[4:5], v[208:209]
	v_pk_add_f32 v[4:5], v[2:3], v[186:187]
	v_pk_add_f32 v[2:3], v[0:1], v[184:185]
	v_mul_f32_e32 v0, 0xbfb8aa3b, v20
	v_mul_f32_e32 v1, 0xbfb8aa3b, v21
	v_exp_f32_e32 v0, v0
	v_exp_f32_e32 v1, v1
	v_lshlrev_b32_e32 v18, 16, v176
	v_and_b32_e32 v19, 0xffff0000, v176
	v_pk_add_f32 v[6:7], v[6:7], v[210:211]
	v_pk_add_f32 v[0:1], v[0:1], 1.0 op_sel_hi:[1,0]
	v_lshlrev_b32_e32 v20, 16, v180
	v_rcp_f32_e32 v17, v1
	v_and_b32_e32 v12, 0xffff0000, v180
	v_mul_f32_e32 v16, 0xbfb8aa3b, v20
	v_exp_f32_e32 v16, v16
	v_mov_b32_e32 v1, v17
	v_rcp_f32_e32 v17, v0
	v_mul_f32_e32 v2, 0xbfb8aa3b, v2
	v_mul_f32_e32 v3, 0xbfb8aa3b, v3
	v_exp_f32_e32 v2, v2
	v_mov_b32_e32 v0, v17
	v_mul_f32_e32 v8, 0xbfb8aa3b, v12
	v_exp_f32_e32 v17, v8
	v_pk_mul_f32 v[0:1], v[0:1], v[18:19]
	v_exp_f32_e32 v3, v3
	v_pk_add_f32 v[16:17], v[16:17], 1.0 op_sel_hi:[1,0]
	s_nop 0
	v_rcp_f32_e32 v18, v17
	v_pk_add_f32 v[2:3], v[2:3], 1.0 op_sel_hi:[1,0]
	v_mul_f32_e32 v17, v12, v18
	v_rcp_f32_e32 v12, v16
	s_nop 0
	v_mul_f32_e32 v16, v20, v12
	v_pk_mul_f32 v[0:1], v[16:17], v[0:1]
	v_and_b32_e32 v16, 0xffff0000, v181
	v_cvt_pk_bf16_f32 v0, v0, v1
	v_mul_f32_e32 v1, 0xbfb8aa3b, v6
	v_exp_f32_e32 v6, v1
	v_mul_f32_e32 v1, 0xbfb8aa3b, v7
	v_exp_f32_e32 v7, v1
	v_lshlrev_b32_e32 v1, 16, v181
	v_lshlrev_b32_e32 v12, 16, v177
	v_and_b32_e32 v13, 0xffff0000, v177
	v_pk_add_f32 v[6:7], v[6:7], 1.0 op_sel_hi:[1,0]
	v_mul_f32_e32 v8, 0xbfb8aa3b, v1
	v_rcp_f32_e32 v17, v7
	v_exp_f32_e32 v8, v8
	v_mov_b32_e32 v7, v17
	v_rcp_f32_e32 v17, v6
	s_nop 0
	v_mov_b32_e32 v6, v17
	v_mul_f32_e32 v9, 0xbfb8aa3b, v16
	v_exp_f32_e32 v9, v9
	v_pk_mul_f32 v[6:7], v[6:7], v[12:13]
	v_pk_add_f32 v[8:9], v[8:9], 1.0 op_sel_hi:[1,0]
	s_nop 0
	v_rcp_f32_e32 v13, v9
	s_nop 0
	v_mul_f32_e32 v9, v16, v13
	v_rcp_f32_e32 v13, v8
	s_nop 0
	v_mul_f32_e32 v8, v1, v13
	v_pk_mul_f32 v[6:7], v[8:9], v[6:7]
	v_lshlrev_b32_e32 v8, 16, v178
	v_cvt_pk_bf16_f32 v1, v6, v7
	v_and_b32_e32 v9, 0xffff0000, v178
	v_rcp_f32_e32 v10, v3
	v_lshlrev_b32_e32 v12, 16, v182
	v_and_b32_e32 v13, 0xffff0000, v182
	v_mul_f32_e32 v6, 0xbfb8aa3b, v12
	v_mov_b32_e32 v3, v10
	v_rcp_f32_e32 v10, v2
	v_exp_f32_e32 v6, v6
	v_mov_b32_e32 v2, v10
	v_mul_f32_e32 v7, 0xbfb8aa3b, v13
	v_exp_f32_e32 v7, v7
	v_pk_mul_f32 v[2:3], v[2:3], v[8:9]
	v_pk_add_f32 v[6:7], v[6:7], 1.0 op_sel_hi:[1,0]
	s_nop 0
	v_rcp_f32_e32 v9, v7
	s_nop 0
	v_mul_f32_e32 v7, v13, v9
	v_rcp_f32_e32 v9, v6
	s_nop 0
	v_mul_f32_e32 v6, v12, v9
	v_pk_mul_f32 v[2:3], v[6:7], v[2:3]
	v_lshlrev_b32_e32 v8, 16, v179
	v_cvt_pk_bf16_f32 v2, v2, v3
	v_mul_f32_e32 v3, 0xbfb8aa3b, v4
	v_exp_f32_e32 v4, v3
	v_mul_f32_e32 v3, 0xbfb8aa3b, v5
	v_exp_f32_e32 v5, v3
	v_and_b32_e32 v9, 0xffff0000, v179
	v_lshlrev_b32_e32 v3, 16, v183
	v_and_b32_e32 v10, 0xffff0000, v183
	v_pk_add_f32 v[4:5], v[4:5], 1.0 op_sel_hi:[1,0]
	v_mul_f32_e32 v6, 0xbfb8aa3b, v3
	v_rcp_f32_e32 v11, v5
	v_exp_f32_e32 v6, v6
	v_mov_b32_e32 v5, v11
	v_rcp_f32_e32 v11, v4
	s_nop 0
	v_mov_b32_e32 v4, v11
	v_mul_f32_e32 v7, 0xbfb8aa3b, v10
	v_exp_f32_e32 v7, v7
	v_pk_mul_f32 v[4:5], v[4:5], v[8:9]
	v_pk_add_f32 v[6:7], v[6:7], 1.0 op_sel_hi:[1,0]
	s_nop 0
	v_rcp_f32_e32 v9, v7
	s_nop 0
	v_mul_f32_e32 v7, v10, v9
	v_rcp_f32_e32 v9, v6
	s_mov_b64 s[0:1], -1
	v_mul_f32_e32 v8, v3, v9
	v_mov_b32_e32 v6, v8
	v_pk_mul_f32 v[4:5], v[6:7], v[4:5]
	s_and_b64 vcc, exec, s[38:39]
	v_cvt_pk_bf16_f32 v3, v4, v5
	global_store_dwordx4 v[250:251], v[0:3], off offset:256
	s_cbranch_vccnz .LBB0_903
	s_andn2_b64 vcc, exec, s[84:85]
	s_cbranch_vccnz .LBB0_902
	s_barrier
	s_branch .LBB0_902
